# GEMM MFMA Gray walk, first-operand-major (consecutive accumulator pairs share the first operand fragment)
# baseline (speedup 1.0000x reference)
; #define PG8_STAGE(bufoff, gbase, voff) do { if constexpr (!pg8_noload<Epi>::value) { _Pragma("unroll") for (int _i = 0; _i < 2; ++_i) \
;         __builtin_amdgcn_global_load_lds((const unsigned*)((const char*)(gbase) + (size_t)_i * pstep + (voff)[0]), (PG8_LAS unsigned*)(lds + (bufoff) + ldsw + _i * 8192), 16, 0, 0); } } while (0)
; #define PG8_LDA(dst, b, h) do { _Pragma("unroll") for (int m = 0; m < 4; ++m) _Pragma("unroll") for (int k = 0; k < 2; ++k) dst[m][k] = *(const PG8_LAS bf16x8*)(lds + PG8_SA(b, h) + aoff + m * 2048 + k * 1024); } while (0)
; #define PG8_LDB(dst, b, h) do { _Pragma("unroll") for (int n = 0; n < 2; ++n) _Pragma("unroll") for (int k = 0; k < 2; ++k) dst[n][k] = *(const PG8_LAS bf16x8*)(lds + PG8_SB(b, h) + boff + n * 2048 + k * 1024); } while (0)
; #define PG8_MMA(ai, bj, At, Bt) do { __builtin_amdgcn_s_setprio(1); _Pragma("unroll") for (int m = 0; m < 4; ++m) _Pragma("unroll") for (int n = 0; n < 2; ++n) _Pragma("unroll") for (int k = 0; k < 2; ++k) \
;         acc[ai][bj][m][n] = __builtin_amdgcn_mfma_f32_16x16x32_bf16(Bt[n][k], At[m][k], acc[ai][bj][m][n], 0, 0, 0); __builtin_amdgcn_s_setprio(0); } while (0)
; #define PG8_WAIT_V(n) asm volatile("s_waitcnt vmcnt(" #n ")" ::: "memory")
; #define PG8_WAIT_L(n) asm volatile("s_waitcnt lgkmcnt(" #n ")" ::: "memory")
; #define PG8_BAR __builtin_amdgcn_s_barrier()
; template <class Epi, class Sched, bool ALIGN_EPI = false, bool SP2 = false, bool ABLK = false>
; __device__ __forceinline__ void gemm_phase(PG8_LAS unsigned char* lds, const Gemm g, const Sched& S, const Epi& E) {
;     ...
;             const bool last = (t == nt - 2);
;             const char* a1 = cA + (size_t)(t + 1) * kstep;
;             const char* a2 = last ? nA : cA + (size_t)(t + 2) * kstep; const char* b2 = last ? nB : cB + (size_t)(t + 2) * kstepB;
;             const char* a3 = a2 + kstep; const char* b3 = b2 + kstepB;
;             if (last && has_next) S.a_ready(nxt);
;             if constexpr (SP2) {
;             PG8_LDB(B0, 0, 0); PG8_LDB(B1, 0, 1); PG8_SCHED; PG8_LDA(At, 0, 0); PG8_STAGE(PG8_SA(1, 1), a1 + hstep, voffA);
;             PG8_WAIT_V(8); PG8_WAIT_L(0); PG8_BAR; PG8_MMA(0, 0, At, B0); PG8_MMA(0, 1, At, B1); PG8_BAR; PG8_SCHED;
;             PG8_LDA(At, 0, 1); PG8_STAGE(PG8_SB(0, 0), b2, voffB); PG8_STAGE(PG8_SB(0, 1), b2 + hstep, voffB); PG8_STAGE(PG8_SA(0, 0), a2, voffA);
.LBB0_114:
	ds_read_b128 v[144:147], v168
	ds_read_b128 v[184:187], v168 offset:1024
	ds_read_b128 v[188:191], v168 offset:2048
	ds_read_b128 v[192:195], v168 offset:3072
	ds_read_b128 v[196:199], v169
	ds_read_b128 v[200:203], v169 offset:1024
	ds_read_b128 v[204:207], v169 offset:2048
	ds_read_b128 v[208:211], v169 offset:3072
	s_add_u32 s71, vcc_lo, 0xfff80800
	s_addc_u32 s73, vcc_hi, -1
	s_cmp_eq_u32 s70, 28
	s_cselect_b32 s75, s3, s73
	s_cselect_b32 s74, s7, s71
	s_cselect_b32 s77, s21, s17
	s_cselect_b32 s76, s72, s16
	v_lshl_add_u64 v[244:245], vcc, 0, v[136:137]
	s_add_i32 m0, s53, 0xc000
	ds_read_b128 v[212:215], v170
	ds_read_b128 v[216:219], v170 offset:1024
	ds_read_b128 v[220:223], v170 offset:2048
	ds_read_b128 v[224:227], v170 offset:3072
	ds_read_b128 v[228:231], v170 offset:4096
	ds_read_b128 v[232:235], v170 offset:5120
	ds_read_b128 v[236:239], v170 offset:6144
	ds_read_b128 v[240:243], v170 offset:7168
	global_load_lds_dwordx4 v[244:245], off
	v_lshl_add_u64 v[244:245], v[244:245], 0, s[0:1]
	s_add_i32 m0, s53, 0xe000
	s_nop 0
	global_load_lds_dwordx4 v[244:245], off
	s_waitcnt vmcnt(8)
	s_waitcnt lgkmcnt(0)
	s_barrier
	s_setprio 1
	s_waitcnt lgkmcnt(0)
	v_mfma_f32_16x16x32_bf16 v[126:129], v[144:147], v[212:215], v[126:129]
	v_mfma_f32_16x16x32_bf16 v[126:129], v[184:187], v[216:219], v[126:129]
	v_mfma_f32_16x16x32_bf16 v[110:113], v[184:187], v[224:227], v[110:113]
	v_mfma_f32_16x16x32_bf16 v[110:113], v[144:147], v[220:223], v[110:113]
	v_mfma_f32_16x16x32_bf16 v[94:97], v[144:147], v[228:231], v[94:97]
	v_mfma_f32_16x16x32_bf16 v[94:97], v[184:187], v[232:235], v[94:97]
	v_mfma_f32_16x16x32_bf16 v[78:81], v[184:187], v[240:243], v[78:81]
	v_mfma_f32_16x16x32_bf16 v[78:81], v[144:147], v[236:239], v[78:81]
	v_mfma_f32_16x16x32_bf16 v[74:77], v[188:191], v[236:239], v[74:77]
	v_mfma_f32_16x16x32_bf16 v[74:77], v[192:195], v[240:243], v[74:77]
	v_mfma_f32_16x16x32_bf16 v[90:93], v[192:195], v[232:235], v[90:93]
	v_mfma_f32_16x16x32_bf16 v[90:93], v[188:191], v[228:231], v[90:93]
	v_mfma_f32_16x16x32_bf16 v[106:109], v[188:191], v[220:223], v[106:109]
	v_mfma_f32_16x16x32_bf16 v[106:109], v[192:195], v[224:227], v[106:109]
	v_mfma_f32_16x16x32_bf16 v[122:125], v[192:195], v[216:219], v[122:125]
	v_mfma_f32_16x16x32_bf16 v[122:125], v[188:191], v[212:215], v[122:125]
	v_mfma_f32_16x16x32_bf16 v[118:121], v[196:199], v[212:215], v[118:121]
	v_mfma_f32_16x16x32_bf16 v[118:121], v[200:203], v[216:219], v[118:121]
	v_mfma_f32_16x16x32_bf16 v[102:105], v[200:203], v[224:227], v[102:105]
	v_mfma_f32_16x16x32_bf16 v[102:105], v[196:199], v[220:223], v[102:105]
	v_mfma_f32_16x16x32_bf16 v[86:89], v[196:199], v[228:231], v[86:89]
	v_mfma_f32_16x16x32_bf16 v[86:89], v[200:203], v[232:235], v[86:89]
	v_mfma_f32_16x16x32_bf16 v[70:73], v[200:203], v[240:243], v[70:73]
	v_mfma_f32_16x16x32_bf16 v[70:73], v[196:199], v[236:239], v[70:73]
	v_mfma_f32_16x16x32_bf16 v[66:69], v[204:207], v[236:239], v[66:69]
	v_mfma_f32_16x16x32_bf16 v[66:69], v[208:211], v[240:243], v[66:69]
	v_mfma_f32_16x16x32_bf16 v[82:85], v[208:211], v[232:235], v[82:85]
	v_mfma_f32_16x16x32_bf16 v[82:85], v[204:207], v[228:231], v[82:85]
	s_barrier
	s_setprio 2
	v_mfma_f32_16x16x32_bf16 v[98:101], v[204:207], v[220:223], v[98:101]
	v_mfma_f32_16x16x32_bf16 v[98:101], v[208:211], v[224:227], v[98:101]
	v_mfma_f32_16x16x32_bf16 v[114:117], v[208:211], v[216:219], v[114:117]
	v_mfma_f32_16x16x32_bf16 v[114:117], v[204:207], v[212:215], v[114:117]
	s_setprio 0
	s_add_i32 s71, s64, s52
	v_lshl_add_u64 v[244:245], s[76:77], 0, v[130:131]
	s_mov_b32 m0, s71
	ds_read_b128 v[212:215], v170 offset:16384
	ds_read_b128 v[216:219], v170 offset:17408
	ds_read_b128 v[220:223], v170 offset:18432
	ds_read_b128 v[224:227], v170 offset:19456
	ds_read_b128 v[228:231], v170 offset:20480
	ds_read_b128 v[232:235], v170 offset:21504
	ds_read_b128 v[236:239], v170 offset:22528
	ds_read_b128 v[240:243], v170 offset:23552
	global_load_lds_dwordx4 v[244:245], off
	v_lshl_add_u64 v[246:247], v[244:245], 0, s[0:1]
	s_add_i32 m0, s71, 0x2000
	s_add_i32 s71, s65, s52
	global_load_lds_dwordx4 v[246:247], off
	v_lshl_add_u64 v[246:247], v[244:245], 0, s[14:15]
	s_mov_b32 m0, s71
	s_nop 0
	global_load_lds_dwordx4 v[246:247], off
	v_lshl_add_u64 v[246:247], v[244:245], 0, s[18:19]
	s_add_i32 m0, s71, 0x2000
	s_nop 0
	global_load_lds_dwordx4 v[246:247], off
	v_lshl_add_u64 v[246:247], s[74:75], 0, v[130:131]
	s_mov_b32 m0, s53
	v_lshl_add_u64 v[248:249], v[246:247], 0, s[0:1]
	global_load_lds_dwordx4 v[246:247], off
	s_mov_b32 m0, s54
	s_nop 0
	global_load_lds_dwordx4 v[248:249], off
	s_waitcnt vmcnt(8)
	s_waitcnt lgkmcnt(0)
	s_barrier
; #define PG8_STAGE(bufoff, gbase, voff) do { if constexpr (!pg8_noload<Epi>::value) { _Pragma("unroll") for (int _i = 0; _i < 2; ++_i) \
;         __builtin_amdgcn_global_load_lds((const unsigned*)((const char*)(gbase) + (size_t)_i * pstep + (voff)[0]), (PG8_LAS unsigned*)(lds + (bufoff) + ldsw + _i * 8192), 16, 0, 0); } } while (0)
; #define PG8_LDA(dst, b, h) do { _Pragma("unroll") for (int m = 0; m < 4; ++m) _Pragma("unroll") for (int k = 0; k < 2; ++k) dst[m][k] = *(const PG8_LAS bf16x8*)(lds + PG8_SA(b, h) + aoff + m * 2048 + k * 1024); } while (0)
; #define PG8_LDB(dst, b, h) do { _Pragma("unroll") for (int n = 0; n < 2; ++n) _Pragma("unroll") for (int k = 0; k < 2; ++k) dst[n][k] = *(const PG8_LAS bf16x8*)(lds + PG8_SB(b, h) + boff + n * 2048 + k * 1024); } while (0)
; #define PG8_MMA(ai, bj, At, Bt) do { __builtin_amdgcn_s_setprio(1); _Pragma("unroll") for (int m = 0; m < 4; ++m) _Pragma("unroll") for (int n = 0; n < 2; ++n) _Pragma("unroll") for (int k = 0; k < 2; ++k) \
;         acc[ai][bj][m][n] = __builtin_amdgcn_mfma_f32_16x16x32_bf16(Bt[n][k], At[m][k], acc[ai][bj][m][n], 0, 0, 0); __builtin_amdgcn_s_setprio(0); } while (0)
; #define PG8_WAIT_V(n) asm volatile("s_waitcnt vmcnt(" #n ")" ::: "memory")
; #define PG8_WAIT_L(n) asm volatile("s_waitcnt lgkmcnt(" #n ")" ::: "memory")
; #define PG8_BAR __builtin_amdgcn_s_barrier()
; #define PG8_SCHED __builtin_amdgcn_sched_barrier(0)
; template <class Epi, class Sched, bool ALIGN_EPI = false, bool SP2 = false, bool ABLK = false>
; __device__ __forceinline__ void gemm_phase(PG8_LAS unsigned char* lds, const Gemm g, const Sched& S, const Epi& E) {
;     ...
;             PG8_WAIT_V(8); PG8_WAIT_L(0); PG8_BAR; PG8_MMA(1, 0, At, B0); PG8_MMA(1, 1, At, B1); PG8_BAR; PG8_SCHED;
;             PG8_LDB(B0, 1, 0); PG8_LDB(B1, 1, 1); PG8_SCHED; PG8_LDA(At, 1, 0); PG8_STAGE(PG8_SA(0, 1), a2 + hstep, voffA);
;             PG8_WAIT_V(8); PG8_WAIT_L(0); PG8_BAR; PG8_MMA(0, 0, At, B0); PG8_MMA(0, 1, At, B1); PG8_BAR; PG8_SCHED;
	s_setprio 1
	s_waitcnt lgkmcnt(0)
	v_mfma_f32_16x16x32_bf16 v[62:65], v[144:147], v[212:215], v[62:65]
	v_mfma_f32_16x16x32_bf16 v[62:65], v[184:187], v[216:219], v[62:65]
	v_mfma_f32_16x16x32_bf16 v[46:49], v[184:187], v[224:227], v[46:49]
	v_mfma_f32_16x16x32_bf16 v[46:49], v[144:147], v[220:223], v[46:49]
	v_mfma_f32_16x16x32_bf16 v[30:33], v[144:147], v[228:231], v[30:33]
	v_mfma_f32_16x16x32_bf16 v[30:33], v[184:187], v[232:235], v[30:33]
	v_mfma_f32_16x16x32_bf16 v[14:17], v[184:187], v[240:243], v[14:17]
	v_mfma_f32_16x16x32_bf16 v[14:17], v[144:147], v[236:239], v[14:17]
	v_mfma_f32_16x16x32_bf16 v[10:13], v[188:191], v[236:239], v[10:13]
	v_mfma_f32_16x16x32_bf16 v[10:13], v[192:195], v[240:243], v[10:13]
	v_mfma_f32_16x16x32_bf16 v[26:29], v[192:195], v[232:235], v[26:29]
	v_mfma_f32_16x16x32_bf16 v[26:29], v[188:191], v[228:231], v[26:29]
	v_mfma_f32_16x16x32_bf16 v[42:45], v[188:191], v[220:223], v[42:45]
	v_mfma_f32_16x16x32_bf16 v[42:45], v[192:195], v[224:227], v[42:45]
	v_mfma_f32_16x16x32_bf16 v[58:61], v[192:195], v[216:219], v[58:61]
	v_mfma_f32_16x16x32_bf16 v[58:61], v[188:191], v[212:215], v[58:61]
	v_mfma_f32_16x16x32_bf16 v[54:57], v[196:199], v[212:215], v[54:57]
	v_mfma_f32_16x16x32_bf16 v[54:57], v[200:203], v[216:219], v[54:57]
	v_mfma_f32_16x16x32_bf16 v[38:41], v[200:203], v[224:227], v[38:41]
	v_mfma_f32_16x16x32_bf16 v[38:41], v[196:199], v[220:223], v[38:41]
	v_mfma_f32_16x16x32_bf16 v[22:25], v[196:199], v[228:231], v[22:25]
	v_mfma_f32_16x16x32_bf16 v[22:25], v[200:203], v[232:235], v[22:25]
	v_mfma_f32_16x16x32_bf16 v[6:9], v[200:203], v[240:243], v[6:9]
	v_mfma_f32_16x16x32_bf16 v[6:9], v[196:199], v[236:239], v[6:9]
	v_mfma_f32_16x16x32_bf16 v[2:5], v[204:207], v[236:239], v[2:5]
	v_mfma_f32_16x16x32_bf16 v[2:5], v[208:211], v[240:243], v[2:5]
	v_mfma_f32_16x16x32_bf16 v[18:21], v[208:211], v[232:235], v[18:21]
	v_mfma_f32_16x16x32_bf16 v[18:21], v[204:207], v[228:231], v[18:21]
	s_barrier
	s_setprio 2
	v_mfma_f32_16x16x32_bf16 v[34:37], v[204:207], v[220:223], v[34:37]
	v_mfma_f32_16x16x32_bf16 v[34:37], v[208:211], v[224:227], v[34:37]
	v_mfma_f32_16x16x32_bf16 v[50:53], v[208:211], v[216:219], v[50:53]
	v_mfma_f32_16x16x32_bf16 v[50:53], v[204:207], v[212:215], v[50:53]
	s_setprio 0
	s_add_i32 s71, 0, 0x18000
	v_add_u32_e32 v133, s71, v149
	s_add_i32 s73, 0, 0x1c000
	ds_read_b128 v[144:147], v133
	ds_read_b128 v[184:187], v133 offset:1024
	ds_read_b128 v[188:191], v133 offset:2048
	ds_read_b128 v[192:195], v133 offset:3072
	v_add_u32_e32 v133, s73, v149
	ds_read_b128 v[196:199], v133
	ds_read_b128 v[200:203], v133 offset:1024
	ds_read_b128 v[204:207], v133 offset:2048
	ds_read_b128 v[208:211], v133 offset:3072
	s_mov_b32 m0, s55
	v_lshl_add_u64 v[248:249], v[246:247], 0, s[14:15]
	ds_read_b128 v[212:215], v170 offset:32768
	ds_read_b128 v[216:219], v170 offset:33792
	ds_read_b128 v[220:223], v170 offset:34816
	ds_read_b128 v[224:227], v170 offset:35840
	ds_read_b128 v[228:231], v170 offset:36864
	ds_read_b128 v[232:235], v170 offset:37888
	ds_read_b128 v[236:239], v170 offset:38912
	ds_read_b128 v[240:243], v170 offset:39936
	global_load_lds_dwordx4 v[248:249], off
	v_lshl_add_u64 v[248:249], v[246:247], 0, s[18:19]
	s_mov_b32 m0, s56
	s_nop 0
	global_load_lds_dwordx4 v[248:249], off
	s_waitcnt vmcnt(8)
	s_waitcnt lgkmcnt(0)
	s_barrier
	s_setprio 1
	s_waitcnt lgkmcnt(0)
	v_mfma_f32_16x16x32_bf16 v[126:129], v[144:147], v[212:215], v[126:129]
	v_mfma_f32_16x16x32_bf16 v[126:129], v[184:187], v[216:219], v[126:129]
	v_mfma_f32_16x16x32_bf16 v[110:113], v[184:187], v[224:227], v[110:113]
	v_mfma_f32_16x16x32_bf16 v[110:113], v[144:147], v[220:223], v[110:113]
	v_mfma_f32_16x16x32_bf16 v[94:97], v[144:147], v[228:231], v[94:97]
	v_mfma_f32_16x16x32_bf16 v[94:97], v[184:187], v[232:235], v[94:97]
	v_mfma_f32_16x16x32_bf16 v[78:81], v[184:187], v[240:243], v[78:81]
	v_mfma_f32_16x16x32_bf16 v[78:81], v[144:147], v[236:239], v[78:81]
	v_mfma_f32_16x16x32_bf16 v[74:77], v[188:191], v[236:239], v[74:77]
	v_mfma_f32_16x16x32_bf16 v[74:77], v[192:195], v[240:243], v[74:77]
	v_mfma_f32_16x16x32_bf16 v[90:93], v[192:195], v[232:235], v[90:93]
	v_mfma_f32_16x16x32_bf16 v[90:93], v[188:191], v[228:231], v[90:93]
	v_mfma_f32_16x16x32_bf16 v[106:109], v[188:191], v[220:223], v[106:109]
	v_mfma_f32_16x16x32_bf16 v[106:109], v[192:195], v[224:227], v[106:109]
	v_mfma_f32_16x16x32_bf16 v[122:125], v[192:195], v[216:219], v[122:125]
	v_mfma_f32_16x16x32_bf16 v[122:125], v[188:191], v[212:215], v[122:125]
	v_mfma_f32_16x16x32_bf16 v[118:121], v[196:199], v[212:215], v[118:121]
	v_mfma_f32_16x16x32_bf16 v[118:121], v[200:203], v[216:219], v[118:121]
	v_mfma_f32_16x16x32_bf16 v[102:105], v[200:203], v[224:227], v[102:105]
	v_mfma_f32_16x16x32_bf16 v[102:105], v[196:199], v[220:223], v[102:105]
	v_mfma_f32_16x16x32_bf16 v[86:89], v[196:199], v[228:231], v[86:89]
	v_mfma_f32_16x16x32_bf16 v[86:89], v[200:203], v[232:235], v[86:89]
	v_mfma_f32_16x16x32_bf16 v[70:73], v[200:203], v[240:243], v[70:73]
	v_mfma_f32_16x16x32_bf16 v[70:73], v[196:199], v[236:239], v[70:73]
	v_mfma_f32_16x16x32_bf16 v[66:69], v[204:207], v[236:239], v[66:69]
	v_mfma_f32_16x16x32_bf16 v[66:69], v[208:211], v[240:243], v[66:69]
	v_mfma_f32_16x16x32_bf16 v[82:85], v[208:211], v[232:235], v[82:85]
	v_mfma_f32_16x16x32_bf16 v[82:85], v[204:207], v[228:231], v[82:85]
	s_barrier
; #define PG8_STAGE(bufoff, gbase, voff) do { if constexpr (!pg8_noload<Epi>::value) { _Pragma("unroll") for (int _i = 0; _i < 2; ++_i) \
;         __builtin_amdgcn_global_load_lds((const unsigned*)((const char*)(gbase) + (size_t)_i * pstep + (voff)[0]), (PG8_LAS unsigned*)(lds + (bufoff) + ldsw + _i * 8192), 16, 0, 0); } } while (0)
; #define PG8_LDA(dst, b, h) do { _Pragma("unroll") for (int m = 0; m < 4; ++m) _Pragma("unroll") for (int k = 0; k < 2; ++k) dst[m][k] = *(const PG8_LAS bf16x8*)(lds + PG8_SA(b, h) + aoff + m * 2048 + k * 1024); } while (0)
; #define PG8_MMA(ai, bj, At, Bt) do { __builtin_amdgcn_s_setprio(1); _Pragma("unroll") for (int m = 0; m < 4; ++m) _Pragma("unroll") for (int n = 0; n < 2; ++n) _Pragma("unroll") for (int k = 0; k < 2; ++k) \
;         acc[ai][bj][m][n] = __builtin_amdgcn_mfma_f32_16x16x32_bf16(Bt[n][k], At[m][k], acc[ai][bj][m][n], 0, 0, 0); __builtin_amdgcn_s_setprio(0); } while (0)
; #define PG8_WAIT_V(n) asm volatile("s_waitcnt vmcnt(" #n ")" ::: "memory")
; #define PG8_WAIT_L(n) asm volatile("s_waitcnt lgkmcnt(" #n ")" ::: "memory")
; #define PG8_BAR __builtin_amdgcn_s_barrier()
; #define PG8_SCHED __builtin_amdgcn_sched_barrier(0)
; template <class Epi, class Sched, bool ALIGN_EPI = false, bool SP2 = false, bool ABLK = false>
; __device__ __forceinline__ void gemm_phase(PG8_LAS unsigned char* lds, const Gemm g, const Sched& S, const Epi& E) {
;     ...
;             PG8_WAIT_V(8); PG8_WAIT_L(0); PG8_BAR; PG8_MMA(0, 0, At, B0); PG8_MMA(0, 1, At, B1); PG8_BAR; PG8_SCHED;
;             PG8_LDA(At, 1, 1); PG8_STAGE(PG8_SB(1, 0), b3, voffB); PG8_STAGE(PG8_SB(1, 1), b3 + hstep, voffB); PG8_STAGE(PG8_SA(1, 0), a3, voffA);
;             PG8_WAIT_V(8); PG8_WAIT_L(0); PG8_BAR; PG8_MMA(1, 0, At, B0); PG8_MMA(1, 1, At, B1); PG8_BAR; PG8_SCHED;
;     ...
;         if constexpr (ALIGN_EPI) { if (wr == 0) PG8_BAR; }
	s_setprio 2
	v_mfma_f32_16x16x32_bf16 v[98:101], v[204:207], v[220:223], v[98:101]
	v_mfma_f32_16x16x32_bf16 v[98:101], v[208:211], v[224:227], v[98:101]
	v_mfma_f32_16x16x32_bf16 v[114:117], v[208:211], v[216:219], v[114:117]
	v_mfma_f32_16x16x32_bf16 v[114:117], v[204:207], v[212:215], v[114:117]
	s_setprio 0
	s_add_i32 s71, s71, s52
	v_lshl_add_u64 v[248:249], v[244:245], 0, s[28:29]
	s_mov_b32 m0, s71
	ds_read_b128 v[212:215], v170 offset:49152
	ds_read_b128 v[216:219], v170 offset:50176
	ds_read_b128 v[220:223], v170 offset:51200
	ds_read_b128 v[224:227], v170 offset:52224
	ds_read_b128 v[228:231], v170 offset:53248
	ds_read_b128 v[232:235], v170 offset:54272
	ds_read_b128 v[236:239], v170 offset:55296
	ds_read_b128 v[240:243], v170 offset:56320
	global_load_lds_dwordx4 v[248:249], off
	v_lshl_add_u64 v[248:249], v[244:245], 0, s[30:31]
	s_add_i32 m0, s71, 0x2000
	s_add_i32 s71, s73, s52
	global_load_lds_dwordx4 v[248:249], off
	v_lshl_add_u64 v[248:249], v[244:245], 0, s[34:35]
	s_mov_b32 m0, s71
	v_lshl_add_u64 v[244:245], v[244:245], 0, s[36:37]
	global_load_lds_dwordx4 v[248:249], off
	s_add_i32 m0, s71, 0x2000
	s_nop 0
	global_load_lds_dwordx4 v[244:245], off
	v_lshl_add_u64 v[244:245], v[246:247], 0, s[28:29]
	s_mov_b32 m0, s59
	s_nop 0
	global_load_lds_dwordx4 v[244:245], off
	v_lshl_add_u64 v[244:245], v[246:247], 0, s[30:31]
	s_mov_b32 m0, s60
	s_nop 0
	global_load_lds_dwordx4 v[244:245], off
	s_waitcnt vmcnt(8)
	s_waitcnt lgkmcnt(0)
	s_barrier
	s_setprio 1
	s_waitcnt lgkmcnt(0)
	v_mfma_f32_16x16x32_bf16 v[62:65], v[144:147], v[212:215], v[62:65]
	v_mfma_f32_16x16x32_bf16 v[62:65], v[184:187], v[216:219], v[62:65]
	v_mfma_f32_16x16x32_bf16 v[46:49], v[184:187], v[224:227], v[46:49]
	v_mfma_f32_16x16x32_bf16 v[46:49], v[144:147], v[220:223], v[46:49]
	v_mfma_f32_16x16x32_bf16 v[30:33], v[144:147], v[228:231], v[30:33]
	v_mfma_f32_16x16x32_bf16 v[30:33], v[184:187], v[232:235], v[30:33]
	v_mfma_f32_16x16x32_bf16 v[14:17], v[184:187], v[240:243], v[14:17]
	v_mfma_f32_16x16x32_bf16 v[14:17], v[144:147], v[236:239], v[14:17]
	v_mfma_f32_16x16x32_bf16 v[10:13], v[188:191], v[236:239], v[10:13]
	v_mfma_f32_16x16x32_bf16 v[10:13], v[192:195], v[240:243], v[10:13]
	v_mfma_f32_16x16x32_bf16 v[26:29], v[192:195], v[232:235], v[26:29]
	v_mfma_f32_16x16x32_bf16 v[26:29], v[188:191], v[228:231], v[26:29]
	v_mfma_f32_16x16x32_bf16 v[42:45], v[188:191], v[220:223], v[42:45]
	v_mfma_f32_16x16x32_bf16 v[42:45], v[192:195], v[224:227], v[42:45]
	v_mfma_f32_16x16x32_bf16 v[58:61], v[192:195], v[216:219], v[58:61]
	v_mfma_f32_16x16x32_bf16 v[58:61], v[188:191], v[212:215], v[58:61]
	v_mfma_f32_16x16x32_bf16 v[54:57], v[196:199], v[212:215], v[54:57]
	v_mfma_f32_16x16x32_bf16 v[54:57], v[200:203], v[216:219], v[54:57]
	v_mfma_f32_16x16x32_bf16 v[38:41], v[200:203], v[224:227], v[38:41]
	v_mfma_f32_16x16x32_bf16 v[38:41], v[196:199], v[220:223], v[38:41]
	v_mfma_f32_16x16x32_bf16 v[22:25], v[196:199], v[228:231], v[22:25]
	v_mfma_f32_16x16x32_bf16 v[22:25], v[200:203], v[232:235], v[22:25]
	v_mfma_f32_16x16x32_bf16 v[6:9], v[200:203], v[240:243], v[6:9]
	v_mfma_f32_16x16x32_bf16 v[6:9], v[196:199], v[236:239], v[6:9]
	v_mfma_f32_16x16x32_bf16 v[2:5], v[204:207], v[236:239], v[2:5]
	v_mfma_f32_16x16x32_bf16 v[2:5], v[208:211], v[240:243], v[2:5]
	v_mfma_f32_16x16x32_bf16 v[18:21], v[208:211], v[232:235], v[18:21]
	v_mfma_f32_16x16x32_bf16 v[18:21], v[204:207], v[228:231], v[18:21]
	s_barrier
	s_setprio 2
	v_mfma_f32_16x16x32_bf16 v[34:37], v[204:207], v[220:223], v[34:37]
	v_mfma_f32_16x16x32_bf16 v[34:37], v[208:211], v[224:227], v[34:37]
	v_mfma_f32_16x16x32_bf16 v[50:53], v[208:211], v[216:219], v[50:53]
	v_mfma_f32_16x16x32_bf16 v[50:53], v[204:207], v[212:215], v[50:53]
	s_setprio 0
	s_add_i32 s70, s70, 2
	s_add_u32 vcc_lo, vcc_lo, 0x1000
	s_addc_u32 vcc_hi, vcc_hi, 0
	s_add_u32 s16, s16, 0x1000
	s_addc_u32 s17, s17, 0
	s_cmp_gt_u32 s70, 29
	s_cbranch_scc0 .LBB0_114
	s_and_b64 vcc, exec, s[38:39]
	s_cbranch_vccz .LBB0_117
	s_barrier

; #define PG8_STAGE(bufoff, gbase, voff) do { if constexpr (!pg8_noload<Epi>::value) { _Pragma("unroll") for (int _i = 0; _i < 2; ++_i) \
;         __builtin_amdgcn_global_load_lds((const unsigned*)((const char*)(gbase) + (size_t)_i * pstep + (voff)[0]), (PG8_LAS unsigned*)(lds + (bufoff) + ldsw + _i * 8192), 16, 0, 0); } } while (0)
; #define PG8_LDA(dst, b, h) do { _Pragma("unroll") for (int m = 0; m < 4; ++m) _Pragma("unroll") for (int k = 0; k < 2; ++k) dst[m][k] = *(const PG8_LAS bf16x8*)(lds + PG8_SA(b, h) + aoff + m * 2048 + k * 1024); } while (0)
; #define PG8_LDB(dst, b, h) do { _Pragma("unroll") for (int n = 0; n < 2; ++n) _Pragma("unroll") for (int k = 0; k < 2; ++k) dst[n][k] = *(const PG8_LAS bf16x8*)(lds + PG8_SB(b, h) + boff + n * 2048 + k * 1024); } while (0)
; #define PG8_MMA(ai, bj, At, Bt) do { __builtin_amdgcn_s_setprio(1); _Pragma("unroll") for (int m = 0; m < 4; ++m) _Pragma("unroll") for (int n = 0; n < 2; ++n) _Pragma("unroll") for (int k = 0; k < 2; ++k) \
;         acc[ai][bj][m][n] = __builtin_amdgcn_mfma_f32_16x16x32_bf16(Bt[n][k], At[m][k], acc[ai][bj][m][n], 0, 0, 0); __builtin_amdgcn_s_setprio(0); } while (0)
; #define PG8_WAIT_V(n) asm volatile("s_waitcnt vmcnt(" #n ")" ::: "memory")
; #define PG8_WAIT_L(n) asm volatile("s_waitcnt lgkmcnt(" #n ")" ::: "memory")
; #define PG8_BAR __builtin_amdgcn_s_barrier()
; template <class Epi, class Sched, bool ALIGN_EPI = false, bool SP2 = false, bool ABLK = false>
; __device__ __forceinline__ void gemm_phase(PG8_LAS unsigned char* lds, const Gemm g, const Sched& S, const Epi& E) {
;     ...
;             const bool last = (t == nt - 2);
;             const char* a1 = cA + (size_t)(t + 1) * kstep;
;             const char* a2 = last ? nA : cA + (size_t)(t + 2) * kstep; const char* b2 = last ? nB : cB + (size_t)(t + 2) * kstepB;
;             const char* a3 = a2 + kstep; const char* b3 = b2 + kstepB;
;             if (last && has_next) S.a_ready(nxt);
;             if constexpr (SP2) {
;             PG8_LDB(B0, 0, 0); PG8_LDB(B1, 0, 1); PG8_SCHED; PG8_LDA(At, 0, 0); PG8_STAGE(PG8_SA(1, 1), a1 + hstep, voffA);
;             PG8_WAIT_V(8); PG8_WAIT_L(0); PG8_BAR; PG8_MMA(0, 0, At, B0); PG8_MMA(0, 1, At, B1); PG8_BAR; PG8_SCHED;
;             PG8_LDA(At, 0, 1); PG8_STAGE(PG8_SB(0, 0), b2, voffB); PG8_STAGE(PG8_SB(0, 1), b2 + hstep, voffB); PG8_STAGE(PG8_SA(0, 0), a2, voffA);
.LBB0_487:
	ds_read_b128 v[114:117], v167
	ds_read_b128 v[126:129], v167 offset:1024
	ds_read_b128 v[130:133], v167 offset:2048
	ds_read_b128 v[142:145], v167 offset:3072
	ds_read_b128 v[146:149], v168
	ds_read_b128 v[150:153], v168 offset:1024
	ds_read_b128 v[174:177], v168 offset:2048
	ds_read_b128 v[178:181], v168 offset:3072
	s_add_i32 s65, s39, 2
	s_add_u32 s68, s92, 0xfff00800
	s_addc_u32 s69, s93, -1
	s_cmp_eq_u32 s3, s39
	s_cselect_b32 s69, s79, s69
	s_cselect_b32 s68, s78, s68
	s_cselect_b32 s71, s89, s37
	s_cselect_b32 s70, s88, s11
	v_lshl_add_u64 v[162:163], s[92:93], 0, v[158:159]
	s_add_i32 m0, s56, 0xc000
	ds_read_b128 v[184:187], v169
	ds_read_b128 v[188:191], v169 offset:1024
	ds_read_b128 v[192:195], v169 offset:2048
	ds_read_b128 v[196:199], v169 offset:3072
	ds_read_b128 v[200:203], v169 offset:4096
	ds_read_b128 v[204:207], v169 offset:5120
	ds_read_b128 v[208:211], v169 offset:6144
	ds_read_b128 v[212:215], v169 offset:7168
	global_load_lds_dwordx4 v[162:163], off
	v_lshl_add_u64 v[162:163], v[162:163], 0, s[12:13]
	s_add_i32 m0, s56, 0xe000
	s_nop 0
	global_load_lds_dwordx4 v[162:163], off
	s_waitcnt vmcnt(8)
	s_waitcnt lgkmcnt(0)
	s_barrier
	s_setprio 1
	s_waitcnt lgkmcnt(0)
	v_mfma_f32_16x16x32_bf16 v[138:141], v[114:117], v[184:187], v[138:141]
	v_mfma_f32_16x16x32_bf16 v[138:141], v[126:129], v[188:191], v[138:141]
	v_mfma_f32_16x16x32_bf16 v[110:113], v[126:129], v[196:199], v[110:113]
	v_mfma_f32_16x16x32_bf16 v[110:113], v[114:117], v[192:195], v[110:113]
	v_mfma_f32_16x16x32_bf16 v[94:97], v[114:117], v[200:203], v[94:97]
	v_mfma_f32_16x16x32_bf16 v[94:97], v[126:129], v[204:207], v[94:97]
	v_mfma_f32_16x16x32_bf16 v[78:81], v[126:129], v[212:215], v[78:81]
	v_mfma_f32_16x16x32_bf16 v[78:81], v[114:117], v[208:211], v[78:81]
	v_mfma_f32_16x16x32_bf16 v[74:77], v[130:133], v[208:211], v[74:77]
	v_mfma_f32_16x16x32_bf16 v[74:77], v[142:145], v[212:215], v[74:77]
	v_mfma_f32_16x16x32_bf16 v[90:93], v[142:145], v[204:207], v[90:93]
	v_mfma_f32_16x16x32_bf16 v[90:93], v[130:133], v[200:203], v[90:93]
	v_mfma_f32_16x16x32_bf16 v[106:109], v[130:133], v[192:195], v[106:109]
	v_mfma_f32_16x16x32_bf16 v[106:109], v[142:145], v[196:199], v[106:109]
	v_mfma_f32_16x16x32_bf16 v[134:137], v[142:145], v[188:191], v[134:137]
	v_mfma_f32_16x16x32_bf16 v[134:137], v[130:133], v[184:187], v[134:137]
	v_mfma_f32_16x16x32_bf16 v[122:125], v[146:149], v[184:187], v[122:125]
	v_mfma_f32_16x16x32_bf16 v[122:125], v[150:153], v[188:191], v[122:125]
	v_mfma_f32_16x16x32_bf16 v[102:105], v[150:153], v[196:199], v[102:105]
	v_mfma_f32_16x16x32_bf16 v[102:105], v[146:149], v[192:195], v[102:105]
	v_mfma_f32_16x16x32_bf16 v[86:89], v[146:149], v[200:203], v[86:89]
	v_mfma_f32_16x16x32_bf16 v[86:89], v[150:153], v[204:207], v[86:89]
	v_mfma_f32_16x16x32_bf16 v[70:73], v[150:153], v[212:215], v[70:73]
	v_mfma_f32_16x16x32_bf16 v[70:73], v[146:149], v[208:211], v[70:73]
	v_mfma_f32_16x16x32_bf16 v[66:69], v[174:177], v[208:211], v[66:69]
	v_mfma_f32_16x16x32_bf16 v[66:69], v[178:181], v[212:215], v[66:69]
	v_mfma_f32_16x16x32_bf16 v[82:85], v[178:181], v[204:207], v[82:85]
	v_mfma_f32_16x16x32_bf16 v[82:85], v[174:177], v[200:203], v[82:85]
	s_barrier
	s_setprio 2
	v_mfma_f32_16x16x32_bf16 v[98:101], v[174:177], v[192:195], v[98:101]
	v_mfma_f32_16x16x32_bf16 v[98:101], v[178:181], v[196:199], v[98:101]
	v_mfma_f32_16x16x32_bf16 v[118:121], v[178:181], v[188:191], v[118:121]
	v_mfma_f32_16x16x32_bf16 v[118:121], v[174:177], v[184:187], v[118:121]
	s_setprio 0
	s_add_i32 s39, s73, s55
	v_lshl_add_u64 v[162:163], s[70:71], 0, v[154:155]
	s_mov_b32 m0, s39
	ds_read_b128 v[184:187], v169 offset:16384
	ds_read_b128 v[188:191], v169 offset:17408
	ds_read_b128 v[192:195], v169 offset:18432
	ds_read_b128 v[196:199], v169 offset:19456
	ds_read_b128 v[200:203], v169 offset:20480
	ds_read_b128 v[204:207], v169 offset:21504
	ds_read_b128 v[208:211], v169 offset:22528
	ds_read_b128 v[212:215], v169 offset:23552
	global_load_lds_dwordx4 v[162:163], off
	v_lshl_add_u64 v[216:217], v[162:163], 0, s[12:13]
	s_add_i32 m0, s39, 0x2000
	s_add_i32 s39, s74, s55
	global_load_lds_dwordx4 v[216:217], off
	v_lshl_add_u64 v[216:217], v[162:163], 0, s[14:15]
	s_mov_b32 m0, s39
	s_nop 0
	global_load_lds_dwordx4 v[216:217], off
	v_lshl_add_u64 v[216:217], v[162:163], 0, s[16:17]
	s_add_i32 m0, s39, 0x2000
	s_nop 0
	global_load_lds_dwordx4 v[216:217], off
	v_lshl_add_u64 v[216:217], s[68:69], 0, v[154:155]
	s_mov_b32 m0, s56
	v_lshl_add_u64 v[218:219], v[216:217], 0, s[12:13]
	global_load_lds_dwordx4 v[216:217], off
	s_mov_b32 m0, s57
	s_nop 0
	global_load_lds_dwordx4 v[218:219], off
	s_waitcnt vmcnt(8)
	s_waitcnt lgkmcnt(0)
	s_barrier
; #define PG8_STAGE(bufoff, gbase, voff) do { if constexpr (!pg8_noload<Epi>::value) { _Pragma("unroll") for (int _i = 0; _i < 2; ++_i) \
;         __builtin_amdgcn_global_load_lds((const unsigned*)((const char*)(gbase) + (size_t)_i * pstep + (voff)[0]), (PG8_LAS unsigned*)(lds + (bufoff) + ldsw + _i * 8192), 16, 0, 0); } } while (0)
; #define PG8_LDA(dst, b, h) do { _Pragma("unroll") for (int m = 0; m < 4; ++m) _Pragma("unroll") for (int k = 0; k < 2; ++k) dst[m][k] = *(const PG8_LAS bf16x8*)(lds + PG8_SA(b, h) + aoff + m * 2048 + k * 1024); } while (0)
; #define PG8_LDB(dst, b, h) do { _Pragma("unroll") for (int n = 0; n < 2; ++n) _Pragma("unroll") for (int k = 0; k < 2; ++k) dst[n][k] = *(const PG8_LAS bf16x8*)(lds + PG8_SB(b, h) + boff + n * 2048 + k * 1024); } while (0)
; #define PG8_MMA(ai, bj, At, Bt) do { __builtin_amdgcn_s_setprio(1); _Pragma("unroll") for (int m = 0; m < 4; ++m) _Pragma("unroll") for (int n = 0; n < 2; ++n) _Pragma("unroll") for (int k = 0; k < 2; ++k) \
;         acc[ai][bj][m][n] = __builtin_amdgcn_mfma_f32_16x16x32_bf16(Bt[n][k], At[m][k], acc[ai][bj][m][n], 0, 0, 0); __builtin_amdgcn_s_setprio(0); } while (0)
; #define PG8_WAIT_V(n) asm volatile("s_waitcnt vmcnt(" #n ")" ::: "memory")
; #define PG8_WAIT_L(n) asm volatile("s_waitcnt lgkmcnt(" #n ")" ::: "memory")
; #define PG8_BAR __builtin_amdgcn_s_barrier()
; #define PG8_SCHED __builtin_amdgcn_sched_barrier(0)
; template <class Epi, class Sched, bool ALIGN_EPI = false, bool SP2 = false, bool ABLK = false>
; __device__ __forceinline__ void gemm_phase(PG8_LAS unsigned char* lds, const Gemm g, const Sched& S, const Epi& E) {
;     ...
;             PG8_WAIT_V(8); PG8_WAIT_L(0); PG8_BAR; PG8_MMA(1, 0, At, B0); PG8_MMA(1, 1, At, B1); PG8_BAR; PG8_SCHED;
;             PG8_LDB(B0, 1, 0); PG8_LDB(B1, 1, 1); PG8_SCHED; PG8_LDA(At, 1, 0); PG8_STAGE(PG8_SA(0, 1), a2 + hstep, voffA);
;             PG8_WAIT_V(8); PG8_WAIT_L(0); PG8_BAR; PG8_MMA(0, 0, At, B0); PG8_MMA(0, 1, At, B1); PG8_BAR; PG8_SCHED;
	s_setprio 1
	s_waitcnt lgkmcnt(0)
	v_mfma_f32_16x16x32_bf16 v[62:65], v[114:117], v[184:187], v[62:65]
	v_mfma_f32_16x16x32_bf16 v[62:65], v[126:129], v[188:191], v[62:65]
	v_mfma_f32_16x16x32_bf16 v[46:49], v[126:129], v[196:199], v[46:49]
	v_mfma_f32_16x16x32_bf16 v[46:49], v[114:117], v[192:195], v[46:49]
	v_mfma_f32_16x16x32_bf16 v[30:33], v[114:117], v[200:203], v[30:33]
	v_mfma_f32_16x16x32_bf16 v[30:33], v[126:129], v[204:207], v[30:33]
	v_mfma_f32_16x16x32_bf16 v[14:17], v[126:129], v[212:215], v[14:17]
	v_mfma_f32_16x16x32_bf16 v[14:17], v[114:117], v[208:211], v[14:17]
	v_mfma_f32_16x16x32_bf16 v[10:13], v[130:133], v[208:211], v[10:13]
	v_mfma_f32_16x16x32_bf16 v[10:13], v[142:145], v[212:215], v[10:13]
	v_mfma_f32_16x16x32_bf16 v[26:29], v[142:145], v[204:207], v[26:29]
	v_mfma_f32_16x16x32_bf16 v[26:29], v[130:133], v[200:203], v[26:29]
	v_mfma_f32_16x16x32_bf16 v[42:45], v[130:133], v[192:195], v[42:45]
	v_mfma_f32_16x16x32_bf16 v[42:45], v[142:145], v[196:199], v[42:45]
	v_mfma_f32_16x16x32_bf16 v[58:61], v[142:145], v[188:191], v[58:61]
	v_mfma_f32_16x16x32_bf16 v[58:61], v[130:133], v[184:187], v[58:61]
	v_mfma_f32_16x16x32_bf16 v[54:57], v[146:149], v[184:187], v[54:57]
	v_mfma_f32_16x16x32_bf16 v[54:57], v[150:153], v[188:191], v[54:57]
	v_mfma_f32_16x16x32_bf16 v[38:41], v[150:153], v[196:199], v[38:41]
	v_mfma_f32_16x16x32_bf16 v[38:41], v[146:149], v[192:195], v[38:41]
	v_mfma_f32_16x16x32_bf16 v[22:25], v[146:149], v[200:203], v[22:25]
	v_mfma_f32_16x16x32_bf16 v[22:25], v[150:153], v[204:207], v[22:25]
	v_mfma_f32_16x16x32_bf16 v[6:9], v[150:153], v[212:215], v[6:9]
	v_mfma_f32_16x16x32_bf16 v[6:9], v[146:149], v[208:211], v[6:9]
	v_mfma_f32_16x16x32_bf16 v[2:5], v[174:177], v[208:211], v[2:5]
	v_mfma_f32_16x16x32_bf16 v[2:5], v[178:181], v[212:215], v[2:5]
	v_mfma_f32_16x16x32_bf16 v[18:21], v[178:181], v[204:207], v[18:21]
	v_mfma_f32_16x16x32_bf16 v[18:21], v[174:177], v[200:203], v[18:21]
	s_barrier
	s_setprio 2
	v_mfma_f32_16x16x32_bf16 v[34:37], v[174:177], v[192:195], v[34:37]
	v_mfma_f32_16x16x32_bf16 v[34:37], v[178:181], v[196:199], v[34:37]
	v_mfma_f32_16x16x32_bf16 v[50:53], v[178:181], v[188:191], v[50:53]
	v_mfma_f32_16x16x32_bf16 v[50:53], v[174:177], v[184:187], v[50:53]
	s_setprio 0
	s_add_i32 s39, 0, 0x18000
	s_add_i32 s68, 0, 0x1c000
	v_add_u32_e32 v142, s39, v1
	v_add_u32_e32 v173, s68, v1
	ds_read_b128 v[114:117], v142
	ds_read_b128 v[126:129], v142 offset:1024
	ds_read_b128 v[130:133], v142 offset:2048
	ds_read_b128 v[142:145], v142 offset:3072
	ds_read_b128 v[146:149], v173
	ds_read_b128 v[150:153], v173 offset:1024
	ds_read_b128 v[174:177], v173 offset:2048
	ds_read_b128 v[178:181], v173 offset:3072
	s_mov_b32 m0, s58
	v_lshl_add_u64 v[218:219], v[216:217], 0, s[14:15]
	ds_read_b128 v[184:187], v169 offset:32768
	ds_read_b128 v[188:191], v169 offset:33792
	ds_read_b128 v[192:195], v169 offset:34816
	ds_read_b128 v[196:199], v169 offset:35840
	ds_read_b128 v[200:203], v169 offset:36864
	ds_read_b128 v[204:207], v169 offset:37888
	ds_read_b128 v[208:211], v169 offset:38912
	ds_read_b128 v[212:215], v169 offset:39936
	global_load_lds_dwordx4 v[218:219], off
	v_lshl_add_u64 v[218:219], v[216:217], 0, s[16:17]
	s_mov_b32 m0, s59
	s_nop 0
	global_load_lds_dwordx4 v[218:219], off
	s_waitcnt vmcnt(8)
	s_waitcnt lgkmcnt(0)
	s_barrier
	s_setprio 1
	s_waitcnt lgkmcnt(0)
	v_mfma_f32_16x16x32_bf16 v[138:141], v[114:117], v[184:187], v[138:141]
	v_mfma_f32_16x16x32_bf16 v[138:141], v[126:129], v[188:191], v[138:141]
	v_mfma_f32_16x16x32_bf16 v[110:113], v[126:129], v[196:199], v[110:113]
	v_mfma_f32_16x16x32_bf16 v[110:113], v[114:117], v[192:195], v[110:113]
	v_mfma_f32_16x16x32_bf16 v[94:97], v[114:117], v[200:203], v[94:97]
	v_mfma_f32_16x16x32_bf16 v[94:97], v[126:129], v[204:207], v[94:97]
	v_mfma_f32_16x16x32_bf16 v[78:81], v[126:129], v[212:215], v[78:81]
	v_mfma_f32_16x16x32_bf16 v[78:81], v[114:117], v[208:211], v[78:81]
	v_mfma_f32_16x16x32_bf16 v[74:77], v[130:133], v[208:211], v[74:77]
	v_mfma_f32_16x16x32_bf16 v[74:77], v[142:145], v[212:215], v[74:77]
	v_mfma_f32_16x16x32_bf16 v[90:93], v[142:145], v[204:207], v[90:93]
	v_mfma_f32_16x16x32_bf16 v[90:93], v[130:133], v[200:203], v[90:93]
	v_mfma_f32_16x16x32_bf16 v[106:109], v[130:133], v[192:195], v[106:109]
	v_mfma_f32_16x16x32_bf16 v[106:109], v[142:145], v[196:199], v[106:109]
	v_mfma_f32_16x16x32_bf16 v[134:137], v[142:145], v[188:191], v[134:137]
	v_mfma_f32_16x16x32_bf16 v[134:137], v[130:133], v[184:187], v[134:137]
	v_mfma_f32_16x16x32_bf16 v[122:125], v[146:149], v[184:187], v[122:125]
	v_mfma_f32_16x16x32_bf16 v[122:125], v[150:153], v[188:191], v[122:125]
	v_mfma_f32_16x16x32_bf16 v[102:105], v[150:153], v[196:199], v[102:105]
	v_mfma_f32_16x16x32_bf16 v[102:105], v[146:149], v[192:195], v[102:105]
	v_mfma_f32_16x16x32_bf16 v[86:89], v[146:149], v[200:203], v[86:89]
	v_mfma_f32_16x16x32_bf16 v[86:89], v[150:153], v[204:207], v[86:89]
	v_mfma_f32_16x16x32_bf16 v[70:73], v[150:153], v[212:215], v[70:73]
	v_mfma_f32_16x16x32_bf16 v[70:73], v[146:149], v[208:211], v[70:73]
	v_mfma_f32_16x16x32_bf16 v[66:69], v[174:177], v[208:211], v[66:69]
	v_mfma_f32_16x16x32_bf16 v[66:69], v[178:181], v[212:215], v[66:69]
	v_mfma_f32_16x16x32_bf16 v[82:85], v[178:181], v[204:207], v[82:85]
	v_mfma_f32_16x16x32_bf16 v[82:85], v[174:177], v[200:203], v[82:85]
	s_barrier
; #define PG8_STAGE(bufoff, gbase, voff) do { if constexpr (!pg8_noload<Epi>::value) { _Pragma("unroll") for (int _i = 0; _i < 2; ++_i) \
;         __builtin_amdgcn_global_load_lds((const unsigned*)((const char*)(gbase) + (size_t)_i * pstep + (voff)[0]), (PG8_LAS unsigned*)(lds + (bufoff) + ldsw + _i * 8192), 16, 0, 0); } } while (0)
; #define PG8_LDA(dst, b, h) do { _Pragma("unroll") for (int m = 0; m < 4; ++m) _Pragma("unroll") for (int k = 0; k < 2; ++k) dst[m][k] = *(const PG8_LAS bf16x8*)(lds + PG8_SA(b, h) + aoff + m * 2048 + k * 1024); } while (0)
; #define PG8_MMA(ai, bj, At, Bt) do { __builtin_amdgcn_s_setprio(1); _Pragma("unroll") for (int m = 0; m < 4; ++m) _Pragma("unroll") for (int n = 0; n < 2; ++n) _Pragma("unroll") for (int k = 0; k < 2; ++k) \
;         acc[ai][bj][m][n] = __builtin_amdgcn_mfma_f32_16x16x32_bf16(Bt[n][k], At[m][k], acc[ai][bj][m][n], 0, 0, 0); __builtin_amdgcn_s_setprio(0); } while (0)
; #define PG8_WAIT_V(n) asm volatile("s_waitcnt vmcnt(" #n ")" ::: "memory")
; #define PG8_WAIT_L(n) asm volatile("s_waitcnt lgkmcnt(" #n ")" ::: "memory")
; #define PG8_BAR __builtin_amdgcn_s_barrier()
; #define PG8_SCHED __builtin_amdgcn_sched_barrier(0)
; template <class Epi, class Sched, bool ALIGN_EPI = false, bool SP2 = false, bool ABLK = false>
; __device__ __forceinline__ void gemm_phase(PG8_LAS unsigned char* lds, const Gemm g, const Sched& S, const Epi& E) {
;     ...
;             PG8_WAIT_V(8); PG8_WAIT_L(0); PG8_BAR; PG8_MMA(0, 0, At, B0); PG8_MMA(0, 1, At, B1); PG8_BAR; PG8_SCHED;
;             PG8_LDA(At, 1, 1); PG8_STAGE(PG8_SB(1, 0), b3, voffB); PG8_STAGE(PG8_SB(1, 1), b3 + hstep, voffB); PG8_STAGE(PG8_SA(1, 0), a3, voffA);
;             PG8_WAIT_V(8); PG8_WAIT_L(0); PG8_BAR; PG8_MMA(1, 0, At, B0); PG8_MMA(1, 1, At, B1); PG8_BAR; PG8_SCHED;
	s_setprio 2
	v_mfma_f32_16x16x32_bf16 v[98:101], v[174:177], v[192:195], v[98:101]
	v_mfma_f32_16x16x32_bf16 v[98:101], v[178:181], v[196:199], v[98:101]
	v_mfma_f32_16x16x32_bf16 v[118:121], v[178:181], v[188:191], v[118:121]
	v_mfma_f32_16x16x32_bf16 v[118:121], v[174:177], v[184:187], v[118:121]
	s_setprio 0
	s_add_i32 s39, s39, s55
	v_lshl_add_u64 v[218:219], v[162:163], 0, s[24:25]
	s_mov_b32 m0, s39
	ds_read_b128 v[184:187], v169 offset:49152
	ds_read_b128 v[188:191], v169 offset:50176
	ds_read_b128 v[192:195], v169 offset:51200
	ds_read_b128 v[196:199], v169 offset:52224
	ds_read_b128 v[200:203], v169 offset:53248
	ds_read_b128 v[204:207], v169 offset:54272
	ds_read_b128 v[208:211], v169 offset:55296
	ds_read_b128 v[212:215], v169 offset:56320
	global_load_lds_dwordx4 v[218:219], off
	v_lshl_add_u64 v[218:219], v[162:163], 0, s[26:27]
	s_add_i32 m0, s39, 0x2000
	s_add_i32 s39, s68, s55
	global_load_lds_dwordx4 v[218:219], off
	v_lshl_add_u64 v[218:219], v[162:163], 0, s[28:29]
	s_mov_b32 m0, s39
	v_lshl_add_u64 v[162:163], v[162:163], 0, s[30:31]
	global_load_lds_dwordx4 v[218:219], off
	s_add_i32 m0, s39, 0x2000
	s_nop 0
	global_load_lds_dwordx4 v[162:163], off
	v_lshl_add_u64 v[162:163], v[216:217], 0, s[24:25]
	s_mov_b32 m0, s62
	s_nop 0
	global_load_lds_dwordx4 v[162:163], off
	v_lshl_add_u64 v[162:163], v[216:217], 0, s[26:27]
	s_mov_b32 m0, s63
	s_nop 0
	global_load_lds_dwordx4 v[162:163], off
	s_waitcnt vmcnt(8)
	s_waitcnt lgkmcnt(0)
	s_barrier
	s_setprio 1
	s_waitcnt lgkmcnt(0)
	v_mfma_f32_16x16x32_bf16 v[62:65], v[114:117], v[184:187], v[62:65]
	v_mfma_f32_16x16x32_bf16 v[62:65], v[126:129], v[188:191], v[62:65]
	v_mfma_f32_16x16x32_bf16 v[46:49], v[126:129], v[196:199], v[46:49]
	v_mfma_f32_16x16x32_bf16 v[46:49], v[114:117], v[192:195], v[46:49]
	v_mfma_f32_16x16x32_bf16 v[30:33], v[114:117], v[200:203], v[30:33]
	v_mfma_f32_16x16x32_bf16 v[30:33], v[126:129], v[204:207], v[30:33]
	v_mfma_f32_16x16x32_bf16 v[14:17], v[126:129], v[212:215], v[14:17]
	v_mfma_f32_16x16x32_bf16 v[14:17], v[114:117], v[208:211], v[14:17]
	v_mfma_f32_16x16x32_bf16 v[10:13], v[130:133], v[208:211], v[10:13]
	v_mfma_f32_16x16x32_bf16 v[10:13], v[142:145], v[212:215], v[10:13]
	v_mfma_f32_16x16x32_bf16 v[26:29], v[142:145], v[204:207], v[26:29]
	v_mfma_f32_16x16x32_bf16 v[26:29], v[130:133], v[200:203], v[26:29]
	v_mfma_f32_16x16x32_bf16 v[42:45], v[130:133], v[192:195], v[42:45]
	v_mfma_f32_16x16x32_bf16 v[42:45], v[142:145], v[196:199], v[42:45]
	v_mfma_f32_16x16x32_bf16 v[58:61], v[142:145], v[188:191], v[58:61]
	v_mfma_f32_16x16x32_bf16 v[58:61], v[130:133], v[184:187], v[58:61]
	v_mfma_f32_16x16x32_bf16 v[54:57], v[146:149], v[184:187], v[54:57]
	v_mfma_f32_16x16x32_bf16 v[54:57], v[150:153], v[188:191], v[54:57]
	v_mfma_f32_16x16x32_bf16 v[38:41], v[150:153], v[196:199], v[38:41]
	v_mfma_f32_16x16x32_bf16 v[38:41], v[146:149], v[192:195], v[38:41]
	v_mfma_f32_16x16x32_bf16 v[22:25], v[146:149], v[200:203], v[22:25]
	v_mfma_f32_16x16x32_bf16 v[22:25], v[150:153], v[204:207], v[22:25]
	v_mfma_f32_16x16x32_bf16 v[6:9], v[150:153], v[212:215], v[6:9]
	v_mfma_f32_16x16x32_bf16 v[6:9], v[146:149], v[208:211], v[6:9]
	v_mfma_f32_16x16x32_bf16 v[2:5], v[174:177], v[208:211], v[2:5]
	v_mfma_f32_16x16x32_bf16 v[2:5], v[178:181], v[212:215], v[2:5]
	v_mfma_f32_16x16x32_bf16 v[18:21], v[178:181], v[204:207], v[18:21]
	v_mfma_f32_16x16x32_bf16 v[18:21], v[174:177], v[200:203], v[18:21]
	s_barrier
	s_setprio 2
	v_mfma_f32_16x16x32_bf16 v[34:37], v[174:177], v[192:195], v[34:37]
	v_mfma_f32_16x16x32_bf16 v[34:37], v[178:181], v[196:199], v[34:37]
	v_mfma_f32_16x16x32_bf16 v[50:53], v[178:181], v[188:191], v[50:53]
	v_mfma_f32_16x16x32_bf16 v[50:53], v[174:177], v[184:187], v[50:53]
	s_setprio 0
	s_add_u32 s92, s92, 0x1000
	s_addc_u32 s93, s93, 0
	s_add_u32 s11, s11, 0x1000
	s_addc_u32 s37, s37, 0
	s_cmp_ge_i32 s65, s80
	s_mov_b32 s39, s65
	s_cbranch_scc0 .LBB0_487
	s_and_b64 vcc, exec, s[34:35]
	s_cbranch_vccnz .LBB0_492
	s_lshl_b32 s11, s2, 8
	s_cmp_gt_i32 s2, 63
	s_mov_b64 s[68:69], -1
	s_cbranch_scc1 .LBB0_493

; #define PG8_STAGE(bufoff, gbase, voff) do { if constexpr (!pg8_noload<Epi>::value) { _Pragma("unroll") for (int _i = 0; _i < 2; ++_i) \
;         __builtin_amdgcn_global_load_lds((const unsigned*)((const char*)(gbase) + (size_t)_i * pstep + (voff)[0]), (PG8_LAS unsigned*)(lds + (bufoff) + ldsw + _i * 8192), 16, 0, 0); } } while (0)
; #define PG8_LDA(dst, b, h) do { _Pragma("unroll") for (int m = 0; m < 4; ++m) _Pragma("unroll") for (int k = 0; k < 2; ++k) dst[m][k] = *(const PG8_LAS bf16x8*)(lds + PG8_SA(b, h) + aoff + m * 2048 + k * 1024); } while (0)
; #define PG8_LDB(dst, b, h) do { _Pragma("unroll") for (int n = 0; n < 2; ++n) _Pragma("unroll") for (int k = 0; k < 2; ++k) dst[n][k] = *(const PG8_LAS bf16x8*)(lds + PG8_SB(b, h) + boff + n * 2048 + k * 1024); } while (0)
; #define PG8_MMA(ai, bj, At, Bt) do { __builtin_amdgcn_s_setprio(1); _Pragma("unroll") for (int m = 0; m < 4; ++m) _Pragma("unroll") for (int n = 0; n < 2; ++n) _Pragma("unroll") for (int k = 0; k < 2; ++k) \
;         acc[ai][bj][m][n] = __builtin_amdgcn_mfma_f32_16x16x32_bf16(Bt[n][k], At[m][k], acc[ai][bj][m][n], 0, 0, 0); __builtin_amdgcn_s_setprio(0); } while (0)
; #define PG8_WAIT_V(n) asm volatile("s_waitcnt vmcnt(" #n ")" ::: "memory")
; #define PG8_WAIT_L(n) asm volatile("s_waitcnt lgkmcnt(" #n ")" ::: "memory")
; #define PG8_BAR __builtin_amdgcn_s_barrier()
; template <class Epi, class Sched, bool ALIGN_EPI = false, bool SP2 = false, bool ABLK = false>
; __device__ __forceinline__ void gemm_phase(PG8_LAS unsigned char* lds, const Gemm g, const Sched& S, const Epi& E) {
;     ...
;             const bool last = (t == nt - 2);
;             const char* a1 = cA + (size_t)(t + 1) * kstep;
;             const char* a2 = last ? nA : cA + (size_t)(t + 2) * kstep; const char* b2 = last ? nB : cB + (size_t)(t + 2) * kstepB;
;             const char* a3 = a2 + kstep; const char* b3 = b2 + kstepB;
;             if (last && has_next) S.a_ready(nxt);
;             if constexpr (SP2) {
;             PG8_LDB(B0, 0, 0); PG8_LDB(B1, 0, 1); PG8_SCHED; PG8_LDA(At, 0, 0); PG8_STAGE(PG8_SA(1, 1), a1 + hstep, voffA);
;             PG8_WAIT_V(8); PG8_WAIT_L(0); PG8_BAR; PG8_MMA(0, 0, At, B0); PG8_MMA(0, 1, At, B1); PG8_BAR; PG8_SCHED;
;             PG8_LDA(At, 0, 1); PG8_STAGE(PG8_SB(0, 0), b2, voffB); PG8_STAGE(PG8_SB(0, 1), b2 + hstep, voffB); PG8_STAGE(PG8_SA(0, 0), a2, voffA);
.LBB0_619:
	s_or_b32 s28, s57, 1
	s_lshl_b64 s[58:59], s[28:29], 11
	s_add_u32 s58, s2, s58
	s_addc_u32 s59, s3, s59
	s_add_i32 s28, s57, 2
	v_add_u32_e32 v160, s78, v168
	v_add_u32_e32 v180, s79, v168
	s_lshl_b64 s[60:61], s[28:29], 11
	ds_read_b128 v[130:133], v160
	ds_read_b128 v[134:137], v160 offset:1024
	ds_read_b128 v[156:159], v160 offset:2048
	ds_read_b128 v[160:163], v160 offset:3072
	ds_read_b128 v[164:167], v180
	ds_read_b128 v[176:179], v180 offset:1024
	ds_read_b128 v[184:187], v180 offset:2048
	ds_read_b128 v[188:191], v180 offset:3072
	s_add_u32 s66, s2, s60
	s_addc_u32 s67, s3, s61
	s_and_b64 s[62:63], s[68:69], exec
	s_cselect_b32 s73, s67, s7
	s_cselect_b32 s72, s66, s15
	s_add_u32 s62, s16, s60
	s_addc_u32 s63, s17, s61
	s_and_b64 s[60:61], s[68:69], exec
	s_cselect_b32 s61, s63, s9
	s_cselect_b32 s60, s62, s56
	v_lshl_add_u64 v[180:181], s[58:59], 0, v[138:139]
	v_lshl_add_u64 v[224:225], v[180:181], 0, s[24:25]
	s_add_i32 m0, s70, 0xc000
	ds_read_b128 v[192:195], v173
	ds_read_b128 v[196:199], v173 offset:1024
	ds_read_b128 v[200:203], v173 offset:2048
	ds_read_b128 v[204:207], v173 offset:3072
	ds_read_b128 v[208:211], v173 offset:4096
	ds_read_b128 v[212:215], v173 offset:5120
	ds_read_b128 v[216:219], v173 offset:6144
	ds_read_b128 v[220:223], v173 offset:7168
	global_load_lds_dwordx4 v[224:225], off
	v_lshl_add_u64 v[180:181], v[180:181], 0, s[26:27]
	s_add_i32 m0, s70, 0xe000
	s_nop 0
	global_load_lds_dwordx4 v[180:181], off
	s_waitcnt vmcnt(8)
	s_waitcnt lgkmcnt(0)
	s_barrier
	s_setprio 1
	s_waitcnt lgkmcnt(0)
	v_mfma_f32_16x16x32_bf16 v[126:129], v[130:133], v[192:195], v[126:129]
	v_mfma_f32_16x16x32_bf16 v[126:129], v[134:137], v[196:199], v[126:129]
	v_mfma_f32_16x16x32_bf16 v[110:113], v[134:137], v[204:207], v[110:113]
	v_mfma_f32_16x16x32_bf16 v[110:113], v[130:133], v[200:203], v[110:113]
	v_mfma_f32_16x16x32_bf16 v[94:97], v[130:133], v[208:211], v[94:97]
	v_mfma_f32_16x16x32_bf16 v[94:97], v[134:137], v[212:215], v[94:97]
	v_mfma_f32_16x16x32_bf16 v[78:81], v[134:137], v[220:223], v[78:81]
	v_mfma_f32_16x16x32_bf16 v[78:81], v[130:133], v[216:219], v[78:81]
	v_mfma_f32_16x16x32_bf16 v[74:77], v[156:159], v[216:219], v[74:77]
	v_mfma_f32_16x16x32_bf16 v[74:77], v[160:163], v[220:223], v[74:77]
	v_mfma_f32_16x16x32_bf16 v[90:93], v[160:163], v[212:215], v[90:93]
	v_mfma_f32_16x16x32_bf16 v[90:93], v[156:159], v[208:211], v[90:93]
	v_mfma_f32_16x16x32_bf16 v[106:109], v[156:159], v[200:203], v[106:109]
	v_mfma_f32_16x16x32_bf16 v[106:109], v[160:163], v[204:207], v[106:109]
	v_mfma_f32_16x16x32_bf16 v[122:125], v[160:163], v[196:199], v[122:125]
	v_mfma_f32_16x16x32_bf16 v[122:125], v[156:159], v[192:195], v[122:125]
	v_mfma_f32_16x16x32_bf16 v[118:121], v[164:167], v[192:195], v[118:121]
	v_mfma_f32_16x16x32_bf16 v[118:121], v[176:179], v[196:199], v[118:121]
	v_mfma_f32_16x16x32_bf16 v[102:105], v[176:179], v[204:207], v[102:105]
	v_mfma_f32_16x16x32_bf16 v[102:105], v[164:167], v[200:203], v[102:105]
	v_mfma_f32_16x16x32_bf16 v[86:89], v[164:167], v[208:211], v[86:89]
	v_mfma_f32_16x16x32_bf16 v[86:89], v[176:179], v[212:215], v[86:89]
	v_mfma_f32_16x16x32_bf16 v[70:73], v[176:179], v[220:223], v[70:73]
	v_mfma_f32_16x16x32_bf16 v[70:73], v[164:167], v[216:219], v[70:73]
	v_mfma_f32_16x16x32_bf16 v[66:69], v[184:187], v[216:219], v[66:69]
	v_mfma_f32_16x16x32_bf16 v[66:69], v[188:191], v[220:223], v[66:69]
	v_mfma_f32_16x16x32_bf16 v[82:85], v[188:191], v[212:215], v[82:85]
	v_mfma_f32_16x16x32_bf16 v[82:85], v[184:187], v[208:211], v[82:85]
	s_barrier
	s_setprio 2
	v_mfma_f32_16x16x32_bf16 v[98:101], v[184:187], v[200:203], v[98:101]
	v_mfma_f32_16x16x32_bf16 v[98:101], v[188:191], v[204:207], v[98:101]
	v_mfma_f32_16x16x32_bf16 v[114:117], v[188:191], v[196:199], v[114:117]
	v_mfma_f32_16x16x32_bf16 v[114:117], v[184:187], v[192:195], v[114:117]
	s_setprio 0
	s_add_i32 s58, s78, s91
	v_lshl_add_u64 v[180:181], s[60:61], 0, v[138:139]
	s_mov_b32 m0, s58
	ds_read_b128 v[192:195], v173 offset:16384
	ds_read_b128 v[196:199], v173 offset:17408
	ds_read_b128 v[200:203], v173 offset:18432
	ds_read_b128 v[204:207], v173 offset:19456
	ds_read_b128 v[208:211], v173 offset:20480
	ds_read_b128 v[212:215], v173 offset:21504
	ds_read_b128 v[216:219], v173 offset:22528
	ds_read_b128 v[220:223], v173 offset:23552
	global_load_lds_dwordx4 v[180:181], off
	v_lshl_add_u64 v[224:225], v[180:181], 0, s[22:23]
	s_add_i32 m0, s58, 0x2000
	s_add_i32 s58, s79, s91
	global_load_lds_dwordx4 v[224:225], off
	v_lshl_add_u64 v[224:225], v[180:181], 0, s[24:25]
	s_mov_b32 m0, s58
	s_nop 0
	global_load_lds_dwordx4 v[224:225], off
	v_lshl_add_u64 v[224:225], v[180:181], 0, s[26:27]
	s_add_i32 m0, s58, 0x2000
	s_nop 0
	global_load_lds_dwordx4 v[224:225], off
	v_lshl_add_u64 v[224:225], s[72:73], 0, v[138:139]
	s_mov_b32 m0, s70
	v_lshl_add_u64 v[226:227], v[224:225], 0, s[22:23]
	global_load_lds_dwordx4 v[224:225], off
	s_mov_b32 m0, s71
	s_nop 0
	global_load_lds_dwordx4 v[226:227], off
	s_waitcnt vmcnt(8)
	s_waitcnt lgkmcnt(0)
	s_barrier
; #define PG8_STAGE(bufoff, gbase, voff) do { if constexpr (!pg8_noload<Epi>::value) { _Pragma("unroll") for (int _i = 0; _i < 2; ++_i) \
;         __builtin_amdgcn_global_load_lds((const unsigned*)((const char*)(gbase) + (size_t)_i * pstep + (voff)[0]), (PG8_LAS unsigned*)(lds + (bufoff) + ldsw + _i * 8192), 16, 0, 0); } } while (0)
; #define PG8_LDA(dst, b, h) do { _Pragma("unroll") for (int m = 0; m < 4; ++m) _Pragma("unroll") for (int k = 0; k < 2; ++k) dst[m][k] = *(const PG8_LAS bf16x8*)(lds + PG8_SA(b, h) + aoff + m * 2048 + k * 1024); } while (0)
; #define PG8_LDB(dst, b, h) do { _Pragma("unroll") for (int n = 0; n < 2; ++n) _Pragma("unroll") for (int k = 0; k < 2; ++k) dst[n][k] = *(const PG8_LAS bf16x8*)(lds + PG8_SB(b, h) + boff + n * 2048 + k * 1024); } while (0)
; #define PG8_MMA(ai, bj, At, Bt) do { __builtin_amdgcn_s_setprio(1); _Pragma("unroll") for (int m = 0; m < 4; ++m) _Pragma("unroll") for (int n = 0; n < 2; ++n) _Pragma("unroll") for (int k = 0; k < 2; ++k) \
;         acc[ai][bj][m][n] = __builtin_amdgcn_mfma_f32_16x16x32_bf16(Bt[n][k], At[m][k], acc[ai][bj][m][n], 0, 0, 0); __builtin_amdgcn_s_setprio(0); } while (0)
; #define PG8_WAIT_V(n) asm volatile("s_waitcnt vmcnt(" #n ")" ::: "memory")
; #define PG8_WAIT_L(n) asm volatile("s_waitcnt lgkmcnt(" #n ")" ::: "memory")
; #define PG8_BAR __builtin_amdgcn_s_barrier()
; #define PG8_SCHED __builtin_amdgcn_sched_barrier(0)
; template <class Epi, class Sched, bool ALIGN_EPI = false, bool SP2 = false, bool ABLK = false>
; __device__ __forceinline__ void gemm_phase(PG8_LAS unsigned char* lds, const Gemm g, const Sched& S, const Epi& E) {
;     ...
;             PG8_WAIT_V(8); PG8_WAIT_L(0); PG8_BAR; PG8_MMA(1, 0, At, B0); PG8_MMA(1, 1, At, B1); PG8_BAR; PG8_SCHED;
;             PG8_LDB(B0, 1, 0); PG8_LDB(B1, 1, 1); PG8_SCHED; PG8_LDA(At, 1, 0); PG8_STAGE(PG8_SA(0, 1), a2 + hstep, voffA);
;             PG8_WAIT_V(8); PG8_WAIT_L(0); PG8_BAR; PG8_MMA(0, 0, At, B0); PG8_MMA(0, 1, At, B1); PG8_BAR; PG8_SCHED;
	s_setprio 1
	s_waitcnt lgkmcnt(0)
	v_mfma_f32_16x16x32_bf16 v[62:65], v[130:133], v[192:195], v[62:65]
	v_mfma_f32_16x16x32_bf16 v[62:65], v[134:137], v[196:199], v[62:65]
	v_mfma_f32_16x16x32_bf16 v[46:49], v[134:137], v[204:207], v[46:49]
	v_mfma_f32_16x16x32_bf16 v[46:49], v[130:133], v[200:203], v[46:49]
	v_mfma_f32_16x16x32_bf16 v[30:33], v[130:133], v[208:211], v[30:33]
	v_mfma_f32_16x16x32_bf16 v[30:33], v[134:137], v[212:215], v[30:33]
	v_mfma_f32_16x16x32_bf16 v[14:17], v[134:137], v[220:223], v[14:17]
	v_mfma_f32_16x16x32_bf16 v[14:17], v[130:133], v[216:219], v[14:17]
	v_mfma_f32_16x16x32_bf16 v[10:13], v[156:159], v[216:219], v[10:13]
	v_mfma_f32_16x16x32_bf16 v[10:13], v[160:163], v[220:223], v[10:13]
	v_mfma_f32_16x16x32_bf16 v[26:29], v[160:163], v[212:215], v[26:29]
	v_mfma_f32_16x16x32_bf16 v[26:29], v[156:159], v[208:211], v[26:29]
	v_mfma_f32_16x16x32_bf16 v[42:45], v[156:159], v[200:203], v[42:45]
	v_mfma_f32_16x16x32_bf16 v[42:45], v[160:163], v[204:207], v[42:45]
	v_mfma_f32_16x16x32_bf16 v[58:61], v[160:163], v[196:199], v[58:61]
	v_mfma_f32_16x16x32_bf16 v[58:61], v[156:159], v[192:195], v[58:61]
	v_mfma_f32_16x16x32_bf16 v[54:57], v[164:167], v[192:195], v[54:57]
	v_mfma_f32_16x16x32_bf16 v[54:57], v[176:179], v[196:199], v[54:57]
	v_mfma_f32_16x16x32_bf16 v[38:41], v[176:179], v[204:207], v[38:41]
	v_mfma_f32_16x16x32_bf16 v[38:41], v[164:167], v[200:203], v[38:41]
	v_mfma_f32_16x16x32_bf16 v[22:25], v[164:167], v[208:211], v[22:25]
	v_mfma_f32_16x16x32_bf16 v[22:25], v[176:179], v[212:215], v[22:25]
	v_mfma_f32_16x16x32_bf16 v[6:9], v[176:179], v[220:223], v[6:9]
	v_mfma_f32_16x16x32_bf16 v[6:9], v[164:167], v[216:219], v[6:9]
	v_mfma_f32_16x16x32_bf16 v[2:5], v[184:187], v[216:219], v[2:5]
	v_mfma_f32_16x16x32_bf16 v[2:5], v[188:191], v[220:223], v[2:5]
	v_mfma_f32_16x16x32_bf16 v[18:21], v[188:191], v[212:215], v[18:21]
	v_mfma_f32_16x16x32_bf16 v[18:21], v[184:187], v[208:211], v[18:21]
	s_barrier
	s_setprio 2
	v_mfma_f32_16x16x32_bf16 v[34:37], v[184:187], v[200:203], v[34:37]
	v_mfma_f32_16x16x32_bf16 v[34:37], v[188:191], v[204:207], v[34:37]
	v_mfma_f32_16x16x32_bf16 v[50:53], v[188:191], v[196:199], v[50:53]
	v_mfma_f32_16x16x32_bf16 v[50:53], v[184:187], v[192:195], v[50:53]
	s_setprio 0
	s_add_i32 s58, 0, 0x18000
	s_add_i32 s59, 0, 0x1c000
	v_add_u32_e32 v160, s58, v168
	v_add_u32_e32 v188, s59, v168
	ds_read_b128 v[130:133], v160
	ds_read_b128 v[134:137], v160 offset:1024
	ds_read_b128 v[156:159], v160 offset:2048
	ds_read_b128 v[160:163], v160 offset:3072
	ds_read_b128 v[164:167], v188
	ds_read_b128 v[176:179], v188 offset:1024
	ds_read_b128 v[184:187], v188 offset:2048
	ds_read_b128 v[188:191], v188 offset:3072
	s_mov_b32 m0, s34
	v_lshl_add_u64 v[226:227], v[224:225], 0, s[24:25]
	ds_read_b128 v[192:195], v173 offset:32768
	ds_read_b128 v[196:199], v173 offset:33792
	ds_read_b128 v[200:203], v173 offset:34816
	ds_read_b128 v[204:207], v173 offset:35840
	ds_read_b128 v[208:211], v173 offset:36864
	ds_read_b128 v[212:215], v173 offset:37888
	ds_read_b128 v[216:219], v173 offset:38912
	ds_read_b128 v[220:223], v173 offset:39936
	global_load_lds_dwordx4 v[226:227], off
	v_lshl_add_u64 v[226:227], v[224:225], 0, s[26:27]
	s_mov_b32 m0, s35
	s_nop 0
	global_load_lds_dwordx4 v[226:227], off
	s_waitcnt vmcnt(8)
	s_waitcnt lgkmcnt(0)
	s_barrier
	s_setprio 1
	s_waitcnt lgkmcnt(0)
	v_mfma_f32_16x16x32_bf16 v[126:129], v[130:133], v[192:195], v[126:129]
	v_mfma_f32_16x16x32_bf16 v[126:129], v[134:137], v[196:199], v[126:129]
	v_mfma_f32_16x16x32_bf16 v[110:113], v[134:137], v[204:207], v[110:113]
	v_mfma_f32_16x16x32_bf16 v[110:113], v[130:133], v[200:203], v[110:113]
	v_mfma_f32_16x16x32_bf16 v[94:97], v[130:133], v[208:211], v[94:97]
	v_mfma_f32_16x16x32_bf16 v[94:97], v[134:137], v[212:215], v[94:97]
	v_mfma_f32_16x16x32_bf16 v[78:81], v[134:137], v[220:223], v[78:81]
	v_mfma_f32_16x16x32_bf16 v[78:81], v[130:133], v[216:219], v[78:81]
	v_mfma_f32_16x16x32_bf16 v[74:77], v[156:159], v[216:219], v[74:77]
	v_mfma_f32_16x16x32_bf16 v[74:77], v[160:163], v[220:223], v[74:77]
	v_mfma_f32_16x16x32_bf16 v[90:93], v[160:163], v[212:215], v[90:93]
	v_mfma_f32_16x16x32_bf16 v[90:93], v[156:159], v[208:211], v[90:93]
	v_mfma_f32_16x16x32_bf16 v[106:109], v[156:159], v[200:203], v[106:109]
	v_mfma_f32_16x16x32_bf16 v[106:109], v[160:163], v[204:207], v[106:109]
	v_mfma_f32_16x16x32_bf16 v[122:125], v[160:163], v[196:199], v[122:125]
	v_mfma_f32_16x16x32_bf16 v[122:125], v[156:159], v[192:195], v[122:125]
	v_mfma_f32_16x16x32_bf16 v[118:121], v[164:167], v[192:195], v[118:121]
	v_mfma_f32_16x16x32_bf16 v[118:121], v[176:179], v[196:199], v[118:121]
	v_mfma_f32_16x16x32_bf16 v[102:105], v[176:179], v[204:207], v[102:105]
	v_mfma_f32_16x16x32_bf16 v[102:105], v[164:167], v[200:203], v[102:105]
	v_mfma_f32_16x16x32_bf16 v[86:89], v[164:167], v[208:211], v[86:89]
	v_mfma_f32_16x16x32_bf16 v[86:89], v[176:179], v[212:215], v[86:89]
	v_mfma_f32_16x16x32_bf16 v[70:73], v[176:179], v[220:223], v[70:73]
	v_mfma_f32_16x16x32_bf16 v[70:73], v[164:167], v[216:219], v[70:73]
	v_mfma_f32_16x16x32_bf16 v[66:69], v[184:187], v[216:219], v[66:69]
	v_mfma_f32_16x16x32_bf16 v[66:69], v[188:191], v[220:223], v[66:69]
	v_mfma_f32_16x16x32_bf16 v[82:85], v[188:191], v[212:215], v[82:85]
	v_mfma_f32_16x16x32_bf16 v[82:85], v[184:187], v[208:211], v[82:85]
	s_barrier
; #define PG8_STAGE(bufoff, gbase, voff) do { if constexpr (!pg8_noload<Epi>::value) { _Pragma("unroll") for (int _i = 0; _i < 2; ++_i) \
;         __builtin_amdgcn_global_load_lds((const unsigned*)((const char*)(gbase) + (size_t)_i * pstep + (voff)[0]), (PG8_LAS unsigned*)(lds + (bufoff) + ldsw + _i * 8192), 16, 0, 0); } } while (0)
; #define PG8_LDA(dst, b, h) do { _Pragma("unroll") for (int m = 0; m < 4; ++m) _Pragma("unroll") for (int k = 0; k < 2; ++k) dst[m][k] = *(const PG8_LAS bf16x8*)(lds + PG8_SA(b, h) + aoff + m * 2048 + k * 1024); } while (0)
; #define PG8_MMA(ai, bj, At, Bt) do { __builtin_amdgcn_s_setprio(1); _Pragma("unroll") for (int m = 0; m < 4; ++m) _Pragma("unroll") for (int n = 0; n < 2; ++n) _Pragma("unroll") for (int k = 0; k < 2; ++k) \
;         acc[ai][bj][m][n] = __builtin_amdgcn_mfma_f32_16x16x32_bf16(Bt[n][k], At[m][k], acc[ai][bj][m][n], 0, 0, 0); __builtin_amdgcn_s_setprio(0); } while (0)
; #define PG8_WAIT_V(n) asm volatile("s_waitcnt vmcnt(" #n ")" ::: "memory")
; #define PG8_WAIT_L(n) asm volatile("s_waitcnt lgkmcnt(" #n ")" ::: "memory")
; #define PG8_BAR __builtin_amdgcn_s_barrier()
; #define PG8_SCHED __builtin_amdgcn_sched_barrier(0)
; template <class Epi, class Sched, bool ALIGN_EPI = false, bool SP2 = false, bool ABLK = false>
; __device__ __forceinline__ void gemm_phase(PG8_LAS unsigned char* lds, const Gemm g, const Sched& S, const Epi& E) {
;     ...
;             PG8_WAIT_V(8); PG8_WAIT_L(0); PG8_BAR; PG8_MMA(0, 0, At, B0); PG8_MMA(0, 1, At, B1); PG8_BAR; PG8_SCHED;
;             PG8_LDA(At, 1, 1); PG8_STAGE(PG8_SB(1, 0), b3, voffB); PG8_STAGE(PG8_SB(1, 1), b3 + hstep, voffB); PG8_STAGE(PG8_SA(1, 0), a3, voffA);
;             PG8_WAIT_V(8); PG8_WAIT_L(0); PG8_BAR; PG8_MMA(1, 0, At, B0); PG8_MMA(1, 1, At, B1); PG8_BAR; PG8_SCHED;
	s_setprio 2
	v_mfma_f32_16x16x32_bf16 v[98:101], v[184:187], v[200:203], v[98:101]
	v_mfma_f32_16x16x32_bf16 v[98:101], v[188:191], v[204:207], v[98:101]
	v_mfma_f32_16x16x32_bf16 v[114:117], v[188:191], v[196:199], v[114:117]
	v_mfma_f32_16x16x32_bf16 v[114:117], v[184:187], v[192:195], v[114:117]
	s_setprio 0
	s_add_i32 s58, s58, s91
	v_lshl_add_u64 v[226:227], v[180:181], 0, s[92:93]
	s_mov_b32 m0, s58
	ds_read_b128 v[192:195], v173 offset:49152
	ds_read_b128 v[196:199], v173 offset:50176
	ds_read_b128 v[200:203], v173 offset:51200
	ds_read_b128 v[204:207], v173 offset:52224
	ds_read_b128 v[208:211], v173 offset:53248
	ds_read_b128 v[212:215], v173 offset:54272
	ds_read_b128 v[216:219], v173 offset:55296
	ds_read_b128 v[220:223], v173 offset:56320
	global_load_lds_dwordx4 v[226:227], off
	v_lshl_add_u64 v[226:227], v[180:181], 0, s[94:95]
	s_add_i32 m0, s58, 0x2000
	s_add_i32 s58, s59, s91
	global_load_lds_dwordx4 v[226:227], off
	v_lshl_add_u64 v[226:227], v[180:181], 0, s[96:97]
	s_mov_b32 m0, s58
	v_lshl_add_u64 v[180:181], v[180:181], 0, s[88:89]
	global_load_lds_dwordx4 v[226:227], off
	s_add_i32 m0, s58, 0x2000
	s_nop 0
	global_load_lds_dwordx4 v[180:181], off
	v_lshl_add_u64 v[180:181], v[224:225], 0, s[92:93]
	s_mov_b32 m0, s10
	s_nop 0
	global_load_lds_dwordx4 v[180:181], off
	v_lshl_add_u64 v[180:181], v[224:225], 0, s[94:95]
	s_mov_b32 m0, s11
	s_nop 0
	global_load_lds_dwordx4 v[180:181], off
	s_waitcnt vmcnt(8)
	s_waitcnt lgkmcnt(0)
	s_barrier
	s_setprio 1
	s_waitcnt lgkmcnt(0)
	v_mfma_f32_16x16x32_bf16 v[62:65], v[130:133], v[192:195], v[62:65]
	v_mfma_f32_16x16x32_bf16 v[62:65], v[134:137], v[196:199], v[62:65]
	v_mfma_f32_16x16x32_bf16 v[46:49], v[134:137], v[204:207], v[46:49]
	v_mfma_f32_16x16x32_bf16 v[46:49], v[130:133], v[200:203], v[46:49]
	v_mfma_f32_16x16x32_bf16 v[30:33], v[130:133], v[208:211], v[30:33]
	v_mfma_f32_16x16x32_bf16 v[30:33], v[134:137], v[212:215], v[30:33]
	v_mfma_f32_16x16x32_bf16 v[14:17], v[134:137], v[220:223], v[14:17]
	v_mfma_f32_16x16x32_bf16 v[14:17], v[130:133], v[216:219], v[14:17]
	v_mfma_f32_16x16x32_bf16 v[10:13], v[156:159], v[216:219], v[10:13]
	v_mfma_f32_16x16x32_bf16 v[10:13], v[160:163], v[220:223], v[10:13]
	v_mfma_f32_16x16x32_bf16 v[26:29], v[160:163], v[212:215], v[26:29]
	v_mfma_f32_16x16x32_bf16 v[26:29], v[156:159], v[208:211], v[26:29]
	v_mfma_f32_16x16x32_bf16 v[42:45], v[156:159], v[200:203], v[42:45]
	v_mfma_f32_16x16x32_bf16 v[42:45], v[160:163], v[204:207], v[42:45]
	v_mfma_f32_16x16x32_bf16 v[58:61], v[160:163], v[196:199], v[58:61]
	v_mfma_f32_16x16x32_bf16 v[58:61], v[156:159], v[192:195], v[58:61]
	v_mfma_f32_16x16x32_bf16 v[54:57], v[164:167], v[192:195], v[54:57]
	v_mfma_f32_16x16x32_bf16 v[54:57], v[176:179], v[196:199], v[54:57]
	v_mfma_f32_16x16x32_bf16 v[38:41], v[176:179], v[204:207], v[38:41]
	v_mfma_f32_16x16x32_bf16 v[38:41], v[164:167], v[200:203], v[38:41]
	v_mfma_f32_16x16x32_bf16 v[22:25], v[164:167], v[208:211], v[22:25]
	v_mfma_f32_16x16x32_bf16 v[22:25], v[176:179], v[212:215], v[22:25]
	v_mfma_f32_16x16x32_bf16 v[6:9], v[176:179], v[220:223], v[6:9]
	v_mfma_f32_16x16x32_bf16 v[6:9], v[164:167], v[216:219], v[6:9]
	v_mfma_f32_16x16x32_bf16 v[2:5], v[184:187], v[216:219], v[2:5]
	v_mfma_f32_16x16x32_bf16 v[2:5], v[188:191], v[220:223], v[2:5]
	v_mfma_f32_16x16x32_bf16 v[18:21], v[188:191], v[212:215], v[18:21]
	v_mfma_f32_16x16x32_bf16 v[18:21], v[184:187], v[208:211], v[18:21]
	s_barrier
	s_setprio 2
	v_mfma_f32_16x16x32_bf16 v[34:37], v[184:187], v[200:203], v[34:37]
	v_mfma_f32_16x16x32_bf16 v[34:37], v[188:191], v[204:207], v[34:37]
	v_mfma_f32_16x16x32_bf16 v[50:53], v[188:191], v[196:199], v[50:53]
	v_mfma_f32_16x16x32_bf16 v[50:53], v[184:187], v[192:195], v[50:53]
	s_setprio 0
	s_cmp_gt_u32 s57, 29
	s_mov_b32 s57, s28
	s_cbranch_scc1 .LBB0_631

; #define PG8_STAGE(bufoff, gbase, voff) do { if constexpr (!pg8_noload<Epi>::value) { _Pragma("unroll") for (int _i = 0; _i < 2; ++_i) \
;         __builtin_amdgcn_global_load_lds((const unsigned*)((const char*)(gbase) + (size_t)_i * pstep + (voff)[0]), (PG8_LAS unsigned*)(lds + (bufoff) + ldsw + _i * 8192), 16, 0, 0); } } while (0)
; #define PG8_LDA(dst, b, h) do { _Pragma("unroll") for (int m = 0; m < 4; ++m) _Pragma("unroll") for (int k = 0; k < 2; ++k) dst[m][k] = *(const PG8_LAS bf16x8*)(lds + PG8_SA(b, h) + aoff + m * 2048 + k * 1024); } while (0)
; #define PG8_LDB(dst, b, h) do { _Pragma("unroll") for (int n = 0; n < 2; ++n) _Pragma("unroll") for (int k = 0; k < 2; ++k) dst[n][k] = *(const PG8_LAS bf16x8*)(lds + PG8_SB(b, h) + boff + n * 2048 + k * 1024); } while (0)
; #define PG8_MMA(ai, bj, At, Bt) do { __builtin_amdgcn_s_setprio(1); _Pragma("unroll") for (int m = 0; m < 4; ++m) _Pragma("unroll") for (int n = 0; n < 2; ++n) _Pragma("unroll") for (int k = 0; k < 2; ++k) \
;         acc[ai][bj][m][n] = __builtin_amdgcn_mfma_f32_16x16x32_bf16(Bt[n][k], At[m][k], acc[ai][bj][m][n], 0, 0, 0); __builtin_amdgcn_s_setprio(0); } while (0)
; #define PG8_WAIT_V(n) asm volatile("s_waitcnt vmcnt(" #n ")" ::: "memory")
; #define PG8_WAIT_L(n) asm volatile("s_waitcnt lgkmcnt(" #n ")" ::: "memory")
; #define PG8_BAR __builtin_amdgcn_s_barrier()
; template <class Epi, class Sched, bool ALIGN_EPI = false, bool SP2 = false, bool ABLK = false>
; __device__ __forceinline__ void gemm_phase(PG8_LAS unsigned char* lds, const Gemm g, const Sched& S, const Epi& E) {
;     ...
;             const bool last = (t == nt - 2);
;             const char* a1 = cA + (size_t)(t + 1) * kstep;
;             const char* a2 = last ? nA : cA + (size_t)(t + 2) * kstep; const char* b2 = last ? nB : cB + (size_t)(t + 2) * kstepB;
;             const char* a3 = a2 + kstep; const char* b3 = b2 + kstepB;
;             if (last && has_next) S.a_ready(nxt);
;             if constexpr (SP2) {
;             PG8_LDB(B0, 0, 0); PG8_LDB(B1, 0, 1); PG8_SCHED; PG8_LDA(At, 0, 0); PG8_STAGE(PG8_SA(1, 1), a1 + hstep, voffA);
;             PG8_WAIT_V(8); PG8_WAIT_L(0); PG8_BAR; PG8_MMA(0, 0, At, B0); PG8_MMA(0, 1, At, B1); PG8_BAR; PG8_SCHED;
;             PG8_LDA(At, 0, 1); PG8_STAGE(PG8_SB(0, 0), b2, voffB); PG8_STAGE(PG8_SB(0, 1), b2 + hstep, voffB); PG8_STAGE(PG8_SA(0, 0), a2, voffA);
.LBB0_1533:
	ds_read_b128 v[114:117], v167
	ds_read_b128 v[126:129], v167 offset:1024
	ds_read_b128 v[130:133], v167 offset:2048
	ds_read_b128 v[142:145], v167 offset:3072
	ds_read_b128 v[146:149], v168
	ds_read_b128 v[150:153], v168 offset:1024
	ds_read_b128 v[174:177], v168 offset:2048
	ds_read_b128 v[178:181], v168 offset:3072
	s_add_i32 s41, s39, 2
	s_add_u32 s70, s68, 0xfff00800
	s_addc_u32 s71, s69, -1
	s_cmp_eq_u32 s3, s39
	s_cselect_b32 s71, s43, s71
	s_cselect_b32 s70, s42, s70
	s_cselect_b32 s81, s65, s37
	s_cselect_b32 s80, s64, s11
	v_lshl_add_u64 v[162:163], s[68:69], 0, v[158:159]
	s_add_i32 m0, s56, 0xc000
	ds_read_b128 v[184:187], v169
	ds_read_b128 v[188:191], v169 offset:1024
	ds_read_b128 v[192:195], v169 offset:2048
	ds_read_b128 v[196:199], v169 offset:3072
	ds_read_b128 v[200:203], v169 offset:4096
	ds_read_b128 v[204:207], v169 offset:5120
	ds_read_b128 v[208:211], v169 offset:6144
	ds_read_b128 v[212:215], v169 offset:7168
	global_load_lds_dwordx4 v[162:163], off
	v_lshl_add_u64 v[162:163], v[162:163], 0, s[12:13]
	s_add_i32 m0, s56, 0xe000
	s_nop 0
	global_load_lds_dwordx4 v[162:163], off
	s_waitcnt vmcnt(8)
	s_waitcnt lgkmcnt(0)
	s_barrier
	s_setprio 1
	s_waitcnt lgkmcnt(0)
	v_mfma_f32_16x16x32_bf16 v[138:141], v[114:117], v[184:187], v[138:141]
	v_mfma_f32_16x16x32_bf16 v[138:141], v[126:129], v[188:191], v[138:141]
	v_mfma_f32_16x16x32_bf16 v[110:113], v[126:129], v[196:199], v[110:113]
	v_mfma_f32_16x16x32_bf16 v[110:113], v[114:117], v[192:195], v[110:113]
	v_mfma_f32_16x16x32_bf16 v[94:97], v[114:117], v[200:203], v[94:97]
	v_mfma_f32_16x16x32_bf16 v[94:97], v[126:129], v[204:207], v[94:97]
	v_mfma_f32_16x16x32_bf16 v[78:81], v[126:129], v[212:215], v[78:81]
	v_mfma_f32_16x16x32_bf16 v[78:81], v[114:117], v[208:211], v[78:81]
	v_mfma_f32_16x16x32_bf16 v[74:77], v[130:133], v[208:211], v[74:77]
	v_mfma_f32_16x16x32_bf16 v[74:77], v[142:145], v[212:215], v[74:77]
	v_mfma_f32_16x16x32_bf16 v[90:93], v[142:145], v[204:207], v[90:93]
	v_mfma_f32_16x16x32_bf16 v[90:93], v[130:133], v[200:203], v[90:93]
	v_mfma_f32_16x16x32_bf16 v[106:109], v[130:133], v[192:195], v[106:109]
	v_mfma_f32_16x16x32_bf16 v[106:109], v[142:145], v[196:199], v[106:109]
	v_mfma_f32_16x16x32_bf16 v[134:137], v[142:145], v[188:191], v[134:137]
	v_mfma_f32_16x16x32_bf16 v[134:137], v[130:133], v[184:187], v[134:137]
	v_mfma_f32_16x16x32_bf16 v[122:125], v[146:149], v[184:187], v[122:125]
	v_mfma_f32_16x16x32_bf16 v[122:125], v[150:153], v[188:191], v[122:125]
	v_mfma_f32_16x16x32_bf16 v[102:105], v[150:153], v[196:199], v[102:105]
	v_mfma_f32_16x16x32_bf16 v[102:105], v[146:149], v[192:195], v[102:105]
	v_mfma_f32_16x16x32_bf16 v[86:89], v[146:149], v[200:203], v[86:89]
	v_mfma_f32_16x16x32_bf16 v[86:89], v[150:153], v[204:207], v[86:89]
	v_mfma_f32_16x16x32_bf16 v[70:73], v[150:153], v[212:215], v[70:73]
	v_mfma_f32_16x16x32_bf16 v[70:73], v[146:149], v[208:211], v[70:73]
	v_mfma_f32_16x16x32_bf16 v[66:69], v[174:177], v[208:211], v[66:69]
	v_mfma_f32_16x16x32_bf16 v[66:69], v[178:181], v[212:215], v[66:69]
	v_mfma_f32_16x16x32_bf16 v[82:85], v[178:181], v[204:207], v[82:85]
	v_mfma_f32_16x16x32_bf16 v[82:85], v[174:177], v[200:203], v[82:85]
	s_barrier
	s_setprio 2
	v_mfma_f32_16x16x32_bf16 v[98:101], v[174:177], v[192:195], v[98:101]
	v_mfma_f32_16x16x32_bf16 v[98:101], v[178:181], v[196:199], v[98:101]
	v_mfma_f32_16x16x32_bf16 v[118:121], v[178:181], v[188:191], v[118:121]
	v_mfma_f32_16x16x32_bf16 v[118:121], v[174:177], v[184:187], v[118:121]
	s_setprio 0
	s_add_i32 s39, s74, s55
	v_lshl_add_u64 v[162:163], s[80:81], 0, v[154:155]
	s_mov_b32 m0, s39
	ds_read_b128 v[184:187], v169 offset:16384
	ds_read_b128 v[188:191], v169 offset:17408
	ds_read_b128 v[192:195], v169 offset:18432
	ds_read_b128 v[196:199], v169 offset:19456
	ds_read_b128 v[200:203], v169 offset:20480
	ds_read_b128 v[204:207], v169 offset:21504
	ds_read_b128 v[208:211], v169 offset:22528
	ds_read_b128 v[212:215], v169 offset:23552
	global_load_lds_dwordx4 v[162:163], off
	v_lshl_add_u64 v[216:217], v[162:163], 0, s[12:13]
	s_add_i32 m0, s39, 0x2000
	s_add_i32 s39, s75, s55
	global_load_lds_dwordx4 v[216:217], off
	v_lshl_add_u64 v[216:217], v[162:163], 0, s[14:15]
	s_mov_b32 m0, s39
	s_nop 0
	global_load_lds_dwordx4 v[216:217], off
	v_lshl_add_u64 v[216:217], v[162:163], 0, s[16:17]
	s_add_i32 m0, s39, 0x2000
	s_nop 0
	global_load_lds_dwordx4 v[216:217], off
	v_lshl_add_u64 v[216:217], s[70:71], 0, v[154:155]
	s_mov_b32 m0, s56
	v_lshl_add_u64 v[218:219], v[216:217], 0, s[12:13]
	global_load_lds_dwordx4 v[216:217], off
	s_mov_b32 m0, s57
	s_nop 0
	global_load_lds_dwordx4 v[218:219], off
	s_waitcnt vmcnt(8)
	s_waitcnt lgkmcnt(0)
	s_barrier
; #define PG8_STAGE(bufoff, gbase, voff) do { if constexpr (!pg8_noload<Epi>::value) { _Pragma("unroll") for (int _i = 0; _i < 2; ++_i) \
;         __builtin_amdgcn_global_load_lds((const unsigned*)((const char*)(gbase) + (size_t)_i * pstep + (voff)[0]), (PG8_LAS unsigned*)(lds + (bufoff) + ldsw + _i * 8192), 16, 0, 0); } } while (0)
; #define PG8_LDA(dst, b, h) do { _Pragma("unroll") for (int m = 0; m < 4; ++m) _Pragma("unroll") for (int k = 0; k < 2; ++k) dst[m][k] = *(const PG8_LAS bf16x8*)(lds + PG8_SA(b, h) + aoff + m * 2048 + k * 1024); } while (0)
; #define PG8_LDB(dst, b, h) do { _Pragma("unroll") for (int n = 0; n < 2; ++n) _Pragma("unroll") for (int k = 0; k < 2; ++k) dst[n][k] = *(const PG8_LAS bf16x8*)(lds + PG8_SB(b, h) + boff + n * 2048 + k * 1024); } while (0)
; #define PG8_MMA(ai, bj, At, Bt) do { __builtin_amdgcn_s_setprio(1); _Pragma("unroll") for (int m = 0; m < 4; ++m) _Pragma("unroll") for (int n = 0; n < 2; ++n) _Pragma("unroll") for (int k = 0; k < 2; ++k) \
;         acc[ai][bj][m][n] = __builtin_amdgcn_mfma_f32_16x16x32_bf16(Bt[n][k], At[m][k], acc[ai][bj][m][n], 0, 0, 0); __builtin_amdgcn_s_setprio(0); } while (0)
; #define PG8_WAIT_V(n) asm volatile("s_waitcnt vmcnt(" #n ")" ::: "memory")
; #define PG8_WAIT_L(n) asm volatile("s_waitcnt lgkmcnt(" #n ")" ::: "memory")
; #define PG8_BAR __builtin_amdgcn_s_barrier()
; #define PG8_SCHED __builtin_amdgcn_sched_barrier(0)
; template <class Epi, class Sched, bool ALIGN_EPI = false, bool SP2 = false, bool ABLK = false>
; __device__ __forceinline__ void gemm_phase(PG8_LAS unsigned char* lds, const Gemm g, const Sched& S, const Epi& E) {
;     ...
;             PG8_WAIT_V(8); PG8_WAIT_L(0); PG8_BAR; PG8_MMA(1, 0, At, B0); PG8_MMA(1, 1, At, B1); PG8_BAR; PG8_SCHED;
;             PG8_LDB(B0, 1, 0); PG8_LDB(B1, 1, 1); PG8_SCHED; PG8_LDA(At, 1, 0); PG8_STAGE(PG8_SA(0, 1), a2 + hstep, voffA);
;             PG8_WAIT_V(8); PG8_WAIT_L(0); PG8_BAR; PG8_MMA(0, 0, At, B0); PG8_MMA(0, 1, At, B1); PG8_BAR; PG8_SCHED;
	s_setprio 1
	s_waitcnt lgkmcnt(0)
	v_mfma_f32_16x16x32_bf16 v[62:65], v[114:117], v[184:187], v[62:65]
	v_mfma_f32_16x16x32_bf16 v[62:65], v[126:129], v[188:191], v[62:65]
	v_mfma_f32_16x16x32_bf16 v[46:49], v[126:129], v[196:199], v[46:49]
	v_mfma_f32_16x16x32_bf16 v[46:49], v[114:117], v[192:195], v[46:49]
	v_mfma_f32_16x16x32_bf16 v[30:33], v[114:117], v[200:203], v[30:33]
	v_mfma_f32_16x16x32_bf16 v[30:33], v[126:129], v[204:207], v[30:33]
	v_mfma_f32_16x16x32_bf16 v[14:17], v[126:129], v[212:215], v[14:17]
	v_mfma_f32_16x16x32_bf16 v[14:17], v[114:117], v[208:211], v[14:17]
	v_mfma_f32_16x16x32_bf16 v[10:13], v[130:133], v[208:211], v[10:13]
	v_mfma_f32_16x16x32_bf16 v[10:13], v[142:145], v[212:215], v[10:13]
	v_mfma_f32_16x16x32_bf16 v[26:29], v[142:145], v[204:207], v[26:29]
	v_mfma_f32_16x16x32_bf16 v[26:29], v[130:133], v[200:203], v[26:29]
	v_mfma_f32_16x16x32_bf16 v[42:45], v[130:133], v[192:195], v[42:45]
	v_mfma_f32_16x16x32_bf16 v[42:45], v[142:145], v[196:199], v[42:45]
	v_mfma_f32_16x16x32_bf16 v[58:61], v[142:145], v[188:191], v[58:61]
	v_mfma_f32_16x16x32_bf16 v[58:61], v[130:133], v[184:187], v[58:61]
	v_mfma_f32_16x16x32_bf16 v[54:57], v[146:149], v[184:187], v[54:57]
	v_mfma_f32_16x16x32_bf16 v[54:57], v[150:153], v[188:191], v[54:57]
	v_mfma_f32_16x16x32_bf16 v[38:41], v[150:153], v[196:199], v[38:41]
	v_mfma_f32_16x16x32_bf16 v[38:41], v[146:149], v[192:195], v[38:41]
	v_mfma_f32_16x16x32_bf16 v[22:25], v[146:149], v[200:203], v[22:25]
	v_mfma_f32_16x16x32_bf16 v[22:25], v[150:153], v[204:207], v[22:25]
	v_mfma_f32_16x16x32_bf16 v[6:9], v[150:153], v[212:215], v[6:9]
	v_mfma_f32_16x16x32_bf16 v[6:9], v[146:149], v[208:211], v[6:9]
	v_mfma_f32_16x16x32_bf16 v[2:5], v[174:177], v[208:211], v[2:5]
	v_mfma_f32_16x16x32_bf16 v[2:5], v[178:181], v[212:215], v[2:5]
	v_mfma_f32_16x16x32_bf16 v[18:21], v[178:181], v[204:207], v[18:21]
	v_mfma_f32_16x16x32_bf16 v[18:21], v[174:177], v[200:203], v[18:21]
	s_barrier
	s_setprio 2
	v_mfma_f32_16x16x32_bf16 v[34:37], v[174:177], v[192:195], v[34:37]
	v_mfma_f32_16x16x32_bf16 v[34:37], v[178:181], v[196:199], v[34:37]
	v_mfma_f32_16x16x32_bf16 v[50:53], v[178:181], v[188:191], v[50:53]
	v_mfma_f32_16x16x32_bf16 v[50:53], v[174:177], v[184:187], v[50:53]
	s_setprio 0
	s_add_i32 s39, 0, 0x18000
	s_add_i32 s70, 0, 0x1c000
	v_add_u32_e32 v142, s39, v1
	v_add_u32_e32 v173, s70, v1
	ds_read_b128 v[114:117], v142
	ds_read_b128 v[126:129], v142 offset:1024
	ds_read_b128 v[130:133], v142 offset:2048
	ds_read_b128 v[142:145], v142 offset:3072
	ds_read_b128 v[146:149], v173
	ds_read_b128 v[150:153], v173 offset:1024
	ds_read_b128 v[174:177], v173 offset:2048
	ds_read_b128 v[178:181], v173 offset:3072
	s_mov_b32 m0, s58
	v_lshl_add_u64 v[218:219], v[216:217], 0, s[14:15]
	ds_read_b128 v[184:187], v169 offset:32768
	ds_read_b128 v[188:191], v169 offset:33792
	ds_read_b128 v[192:195], v169 offset:34816
	ds_read_b128 v[196:199], v169 offset:35840
	ds_read_b128 v[200:203], v169 offset:36864
	ds_read_b128 v[204:207], v169 offset:37888
	ds_read_b128 v[208:211], v169 offset:38912
	ds_read_b128 v[212:215], v169 offset:39936
	global_load_lds_dwordx4 v[218:219], off
	v_lshl_add_u64 v[218:219], v[216:217], 0, s[16:17]
	s_mov_b32 m0, s59
	s_nop 0
	global_load_lds_dwordx4 v[218:219], off
	s_waitcnt vmcnt(8)
	s_waitcnt lgkmcnt(0)
	s_barrier
	s_setprio 1
	s_waitcnt lgkmcnt(0)
	v_mfma_f32_16x16x32_bf16 v[138:141], v[114:117], v[184:187], v[138:141]
	v_mfma_f32_16x16x32_bf16 v[138:141], v[126:129], v[188:191], v[138:141]
	v_mfma_f32_16x16x32_bf16 v[110:113], v[126:129], v[196:199], v[110:113]
	v_mfma_f32_16x16x32_bf16 v[110:113], v[114:117], v[192:195], v[110:113]
	v_mfma_f32_16x16x32_bf16 v[94:97], v[114:117], v[200:203], v[94:97]
	v_mfma_f32_16x16x32_bf16 v[94:97], v[126:129], v[204:207], v[94:97]
	v_mfma_f32_16x16x32_bf16 v[78:81], v[126:129], v[212:215], v[78:81]
	v_mfma_f32_16x16x32_bf16 v[78:81], v[114:117], v[208:211], v[78:81]
	v_mfma_f32_16x16x32_bf16 v[74:77], v[130:133], v[208:211], v[74:77]
	v_mfma_f32_16x16x32_bf16 v[74:77], v[142:145], v[212:215], v[74:77]
	v_mfma_f32_16x16x32_bf16 v[90:93], v[142:145], v[204:207], v[90:93]
	v_mfma_f32_16x16x32_bf16 v[90:93], v[130:133], v[200:203], v[90:93]
	v_mfma_f32_16x16x32_bf16 v[106:109], v[130:133], v[192:195], v[106:109]
	v_mfma_f32_16x16x32_bf16 v[106:109], v[142:145], v[196:199], v[106:109]
	v_mfma_f32_16x16x32_bf16 v[134:137], v[142:145], v[188:191], v[134:137]
	v_mfma_f32_16x16x32_bf16 v[134:137], v[130:133], v[184:187], v[134:137]
	v_mfma_f32_16x16x32_bf16 v[122:125], v[146:149], v[184:187], v[122:125]
	v_mfma_f32_16x16x32_bf16 v[122:125], v[150:153], v[188:191], v[122:125]
	v_mfma_f32_16x16x32_bf16 v[102:105], v[150:153], v[196:199], v[102:105]
	v_mfma_f32_16x16x32_bf16 v[102:105], v[146:149], v[192:195], v[102:105]
	v_mfma_f32_16x16x32_bf16 v[86:89], v[146:149], v[200:203], v[86:89]
	v_mfma_f32_16x16x32_bf16 v[86:89], v[150:153], v[204:207], v[86:89]
	v_mfma_f32_16x16x32_bf16 v[70:73], v[150:153], v[212:215], v[70:73]
	v_mfma_f32_16x16x32_bf16 v[70:73], v[146:149], v[208:211], v[70:73]
	v_mfma_f32_16x16x32_bf16 v[66:69], v[174:177], v[208:211], v[66:69]
	v_mfma_f32_16x16x32_bf16 v[66:69], v[178:181], v[212:215], v[66:69]
	v_mfma_f32_16x16x32_bf16 v[82:85], v[178:181], v[204:207], v[82:85]
	v_mfma_f32_16x16x32_bf16 v[82:85], v[174:177], v[200:203], v[82:85]
	s_barrier
; #define PG8_STAGE(bufoff, gbase, voff) do { if constexpr (!pg8_noload<Epi>::value) { _Pragma("unroll") for (int _i = 0; _i < 2; ++_i) \
;         __builtin_amdgcn_global_load_lds((const unsigned*)((const char*)(gbase) + (size_t)_i * pstep + (voff)[0]), (PG8_LAS unsigned*)(lds + (bufoff) + ldsw + _i * 8192), 16, 0, 0); } } while (0)
; #define PG8_LDA(dst, b, h) do { _Pragma("unroll") for (int m = 0; m < 4; ++m) _Pragma("unroll") for (int k = 0; k < 2; ++k) dst[m][k] = *(const PG8_LAS bf16x8*)(lds + PG8_SA(b, h) + aoff + m * 2048 + k * 1024); } while (0)
; #define PG8_MMA(ai, bj, At, Bt) do { __builtin_amdgcn_s_setprio(1); _Pragma("unroll") for (int m = 0; m < 4; ++m) _Pragma("unroll") for (int n = 0; n < 2; ++n) _Pragma("unroll") for (int k = 0; k < 2; ++k) \
;         acc[ai][bj][m][n] = __builtin_amdgcn_mfma_f32_16x16x32_bf16(Bt[n][k], At[m][k], acc[ai][bj][m][n], 0, 0, 0); __builtin_amdgcn_s_setprio(0); } while (0)
; #define PG8_WAIT_V(n) asm volatile("s_waitcnt vmcnt(" #n ")" ::: "memory")
; #define PG8_WAIT_L(n) asm volatile("s_waitcnt lgkmcnt(" #n ")" ::: "memory")
; #define PG8_BAR __builtin_amdgcn_s_barrier()
; #define PG8_SCHED __builtin_amdgcn_sched_barrier(0)
; template <class Epi, class Sched, bool ALIGN_EPI = false, bool SP2 = false, bool ABLK = false>
; __device__ __forceinline__ void gemm_phase(PG8_LAS unsigned char* lds, const Gemm g, const Sched& S, const Epi& E) {
;     ...
;             PG8_WAIT_V(8); PG8_WAIT_L(0); PG8_BAR; PG8_MMA(0, 0, At, B0); PG8_MMA(0, 1, At, B1); PG8_BAR; PG8_SCHED;
;             PG8_LDA(At, 1, 1); PG8_STAGE(PG8_SB(1, 0), b3, voffB); PG8_STAGE(PG8_SB(1, 1), b3 + hstep, voffB); PG8_STAGE(PG8_SA(1, 0), a3, voffA);
;             PG8_WAIT_V(8); PG8_WAIT_L(0); PG8_BAR; PG8_MMA(1, 0, At, B0); PG8_MMA(1, 1, At, B1); PG8_BAR; PG8_SCHED;
	s_setprio 2
	v_mfma_f32_16x16x32_bf16 v[98:101], v[174:177], v[192:195], v[98:101]
	v_mfma_f32_16x16x32_bf16 v[98:101], v[178:181], v[196:199], v[98:101]
	v_mfma_f32_16x16x32_bf16 v[118:121], v[178:181], v[188:191], v[118:121]
	v_mfma_f32_16x16x32_bf16 v[118:121], v[174:177], v[184:187], v[118:121]
	s_setprio 0
	s_add_i32 s39, s39, s55
	v_lshl_add_u64 v[218:219], v[162:163], 0, s[24:25]
	s_mov_b32 m0, s39
	ds_read_b128 v[184:187], v169 offset:49152
	ds_read_b128 v[188:191], v169 offset:50176
	ds_read_b128 v[192:195], v169 offset:51200
	ds_read_b128 v[196:199], v169 offset:52224
	ds_read_b128 v[200:203], v169 offset:53248
	ds_read_b128 v[204:207], v169 offset:54272
	ds_read_b128 v[208:211], v169 offset:55296
	ds_read_b128 v[212:215], v169 offset:56320
	global_load_lds_dwordx4 v[218:219], off
	v_lshl_add_u64 v[218:219], v[162:163], 0, s[26:27]
	s_add_i32 m0, s39, 0x2000
	s_add_i32 s39, s70, s55
	global_load_lds_dwordx4 v[218:219], off
	v_lshl_add_u64 v[218:219], v[162:163], 0, s[28:29]
	s_mov_b32 m0, s39
	v_lshl_add_u64 v[162:163], v[162:163], 0, s[30:31]
	global_load_lds_dwordx4 v[218:219], off
	s_add_i32 m0, s39, 0x2000
	s_nop 0
	global_load_lds_dwordx4 v[162:163], off
	v_lshl_add_u64 v[162:163], v[216:217], 0, s[24:25]
	s_mov_b32 m0, s62
	s_nop 0
	global_load_lds_dwordx4 v[162:163], off
	v_lshl_add_u64 v[162:163], v[216:217], 0, s[26:27]
	s_mov_b32 m0, s63
	s_nop 0
	global_load_lds_dwordx4 v[162:163], off
	s_waitcnt vmcnt(8)
	s_waitcnt lgkmcnt(0)
	s_barrier
	s_setprio 1
	s_waitcnt lgkmcnt(0)
	v_mfma_f32_16x16x32_bf16 v[62:65], v[114:117], v[184:187], v[62:65]
	v_mfma_f32_16x16x32_bf16 v[62:65], v[126:129], v[188:191], v[62:65]
	v_mfma_f32_16x16x32_bf16 v[46:49], v[126:129], v[196:199], v[46:49]
	v_mfma_f32_16x16x32_bf16 v[46:49], v[114:117], v[192:195], v[46:49]
	v_mfma_f32_16x16x32_bf16 v[30:33], v[114:117], v[200:203], v[30:33]
	v_mfma_f32_16x16x32_bf16 v[30:33], v[126:129], v[204:207], v[30:33]
	v_mfma_f32_16x16x32_bf16 v[14:17], v[126:129], v[212:215], v[14:17]
	v_mfma_f32_16x16x32_bf16 v[14:17], v[114:117], v[208:211], v[14:17]
	v_mfma_f32_16x16x32_bf16 v[10:13], v[130:133], v[208:211], v[10:13]
	v_mfma_f32_16x16x32_bf16 v[10:13], v[142:145], v[212:215], v[10:13]
	v_mfma_f32_16x16x32_bf16 v[26:29], v[142:145], v[204:207], v[26:29]
	v_mfma_f32_16x16x32_bf16 v[26:29], v[130:133], v[200:203], v[26:29]
	v_mfma_f32_16x16x32_bf16 v[42:45], v[130:133], v[192:195], v[42:45]
	v_mfma_f32_16x16x32_bf16 v[42:45], v[142:145], v[196:199], v[42:45]
	v_mfma_f32_16x16x32_bf16 v[58:61], v[142:145], v[188:191], v[58:61]
	v_mfma_f32_16x16x32_bf16 v[58:61], v[130:133], v[184:187], v[58:61]
	v_mfma_f32_16x16x32_bf16 v[54:57], v[146:149], v[184:187], v[54:57]
	v_mfma_f32_16x16x32_bf16 v[54:57], v[150:153], v[188:191], v[54:57]
	v_mfma_f32_16x16x32_bf16 v[38:41], v[150:153], v[196:199], v[38:41]
	v_mfma_f32_16x16x32_bf16 v[38:41], v[146:149], v[192:195], v[38:41]
	v_mfma_f32_16x16x32_bf16 v[22:25], v[146:149], v[200:203], v[22:25]
	v_mfma_f32_16x16x32_bf16 v[22:25], v[150:153], v[204:207], v[22:25]
	v_mfma_f32_16x16x32_bf16 v[6:9], v[150:153], v[212:215], v[6:9]
	v_mfma_f32_16x16x32_bf16 v[6:9], v[146:149], v[208:211], v[6:9]
	v_mfma_f32_16x16x32_bf16 v[2:5], v[174:177], v[208:211], v[2:5]
	v_mfma_f32_16x16x32_bf16 v[2:5], v[178:181], v[212:215], v[2:5]
	v_mfma_f32_16x16x32_bf16 v[18:21], v[178:181], v[204:207], v[18:21]
	v_mfma_f32_16x16x32_bf16 v[18:21], v[174:177], v[200:203], v[18:21]
	s_barrier
	s_setprio 2
	v_mfma_f32_16x16x32_bf16 v[34:37], v[174:177], v[192:195], v[34:37]
	v_mfma_f32_16x16x32_bf16 v[34:37], v[178:181], v[196:199], v[34:37]
	v_mfma_f32_16x16x32_bf16 v[50:53], v[178:181], v[188:191], v[50:53]
	v_mfma_f32_16x16x32_bf16 v[50:53], v[174:177], v[184:187], v[50:53]
	s_setprio 0
	s_add_u32 s68, s68, 0x1000
	s_addc_u32 s69, s69, 0
	s_add_u32 s11, s11, 0x1000
	s_addc_u32 s37, s37, 0
	s_cmp_ge_i32 s41, s79
	s_mov_b32 s39, s41
	s_cbranch_scc0 .LBB0_1533
	s_and_b64 vcc, exec, s[34:35]
	s_cbranch_vccnz .LBB0_1538
	s_lshl_b32 s11, s2, 8
	s_cmp_gt_i32 s2, 63
	s_mov_b64 s[68:69], -1
	s_cbranch_scc1 .LBB0_1539

; #define PG8_STAGE(bufoff, gbase, voff) do { if constexpr (!pg8_noload<Epi>::value) { _Pragma("unroll") for (int _i = 0; _i < 2; ++_i) \
;         __builtin_amdgcn_global_load_lds((const unsigned*)((const char*)(gbase) + (size_t)_i * pstep + (voff)[0]), (PG8_LAS unsigned*)(lds + (bufoff) + ldsw + _i * 8192), 16, 0, 0); } } while (0)
; #define PG8_LDA(dst, b, h) do { _Pragma("unroll") for (int m = 0; m < 4; ++m) _Pragma("unroll") for (int k = 0; k < 2; ++k) dst[m][k] = *(const PG8_LAS bf16x8*)(lds + PG8_SA(b, h) + aoff + m * 2048 + k * 1024); } while (0)
; #define PG8_LDB(dst, b, h) do { _Pragma("unroll") for (int n = 0; n < 2; ++n) _Pragma("unroll") for (int k = 0; k < 2; ++k) dst[n][k] = *(const PG8_LAS bf16x8*)(lds + PG8_SB(b, h) + boff + n * 2048 + k * 1024); } while (0)
; #define PG8_MMA(ai, bj, At, Bt) do { __builtin_amdgcn_s_setprio(1); _Pragma("unroll") for (int m = 0; m < 4; ++m) _Pragma("unroll") for (int n = 0; n < 2; ++n) _Pragma("unroll") for (int k = 0; k < 2; ++k) \
;         acc[ai][bj][m][n] = __builtin_amdgcn_mfma_f32_16x16x32_bf16(Bt[n][k], At[m][k], acc[ai][bj][m][n], 0, 0, 0); __builtin_amdgcn_s_setprio(0); } while (0)
; #define PG8_WAIT_V(n) asm volatile("s_waitcnt vmcnt(" #n ")" ::: "memory")
; #define PG8_WAIT_L(n) asm volatile("s_waitcnt lgkmcnt(" #n ")" ::: "memory")
; #define PG8_BAR __builtin_amdgcn_s_barrier()
; template <class Epi, class Sched, bool ALIGN_EPI = false, bool SP2 = false, bool ABLK = false>
; __device__ __forceinline__ void gemm_phase(PG8_LAS unsigned char* lds, const Gemm g, const Sched& S, const Epi& E) {
;     ...
;             const bool last = (t == nt - 2);
;             const char* a1 = cA + (size_t)(t + 1) * kstep;
;             const char* a2 = last ? nA : cA + (size_t)(t + 2) * kstep; const char* b2 = last ? nB : cB + (size_t)(t + 2) * kstepB;
;             const char* a3 = a2 + kstep; const char* b3 = b2 + kstepB;
;             if (last && has_next) S.a_ready(nxt);
;             if constexpr (SP2) {
;             PG8_LDB(B0, 0, 0); PG8_LDB(B1, 0, 1); PG8_SCHED; PG8_LDA(At, 0, 0); PG8_STAGE(PG8_SA(1, 1), a1 + hstep, voffA);
;             PG8_WAIT_V(8); PG8_WAIT_L(0); PG8_BAR; PG8_MMA(0, 0, At, B0); PG8_MMA(0, 1, At, B1); PG8_BAR; PG8_SCHED;
;             PG8_LDA(At, 0, 1); PG8_STAGE(PG8_SB(0, 0), b2, voffB); PG8_STAGE(PG8_SB(0, 1), b2 + hstep, voffB); PG8_STAGE(PG8_SA(0, 0), a2, voffA);
.LBB0_1657:
	s_or_b32 s26, s94, 1
	s_lshl_b64 s[82:83], s[26:27], 11
	s_add_u32 s88, s74, s82
	v_add_u32_e32 v140, s12, v173
	s_addc_u32 s89, s75, s83
	s_add_i32 s26, s94, 2
	ds_read_b128 v[130:133], v140
	ds_read_b128 v[134:137], v140 offset:1024
	ds_read_b128 v[154:157], v140 offset:2048
	ds_read_b128 v[158:161], v140 offset:3072
	v_add_u32_e32 v140, s13, v173
	s_lshl_b64 s[90:91], s[26:27], 11
	ds_read_b128 v[162:165], v140
	ds_read_b128 v[166:169], v140 offset:1024
	ds_read_b128 v[184:187], v140 offset:2048
	ds_read_b128 v[188:191], v140 offset:3072
	s_add_u32 s92, s74, s90
	s_addc_u32 s93, s75, s91
	s_and_b64 s[82:83], s[80:81], exec
	s_cselect_b32 s83, s93, s3
	s_cselect_b32 s82, s92, s25
	s_add_u32 s90, s76, s90
	s_addc_u32 s91, s77, s91
	s_and_b64 s[80:81], s[80:81], exec
	s_cselect_b32 s81, s91, s65
	s_cselect_b32 s80, s90, s67
	v_lshl_add_u64 v[170:171], s[88:89], 0, v[138:139]
	v_lshl_add_u64 v[224:225], v[170:171], 0, s[20:21]
	s_add_i32 m0, s56, 0xc000
	ds_read_b128 v[192:195], v178
	ds_read_b128 v[196:199], v178 offset:1024
	ds_read_b128 v[200:203], v178 offset:2048
	ds_read_b128 v[204:207], v178 offset:3072
	ds_read_b128 v[208:211], v178 offset:4096
	ds_read_b128 v[212:215], v178 offset:5120
	ds_read_b128 v[216:219], v178 offset:6144
	ds_read_b128 v[220:223], v178 offset:7168
	global_load_lds_dwordx4 v[224:225], off
	v_lshl_add_u64 v[170:171], v[170:171], 0, s[22:23]
	s_add_i32 m0, s56, 0xe000
	s_nop 0
	global_load_lds_dwordx4 v[170:171], off
	s_waitcnt vmcnt(8)
	s_waitcnt lgkmcnt(0)
	s_barrier
	s_setprio 1
	s_waitcnt lgkmcnt(0)
	v_mfma_f32_16x16x32_bf16 v[126:129], v[130:133], v[192:195], v[126:129]
	v_mfma_f32_16x16x32_bf16 v[126:129], v[134:137], v[196:199], v[126:129]
	v_mfma_f32_16x16x32_bf16 v[110:113], v[134:137], v[204:207], v[110:113]
	v_mfma_f32_16x16x32_bf16 v[110:113], v[130:133], v[200:203], v[110:113]
	v_mfma_f32_16x16x32_bf16 v[94:97], v[130:133], v[208:211], v[94:97]
	v_mfma_f32_16x16x32_bf16 v[94:97], v[134:137], v[212:215], v[94:97]
	v_mfma_f32_16x16x32_bf16 v[78:81], v[134:137], v[220:223], v[78:81]
	v_mfma_f32_16x16x32_bf16 v[78:81], v[130:133], v[216:219], v[78:81]
	v_mfma_f32_16x16x32_bf16 v[74:77], v[154:157], v[216:219], v[74:77]
	v_mfma_f32_16x16x32_bf16 v[74:77], v[158:161], v[220:223], v[74:77]
	v_mfma_f32_16x16x32_bf16 v[90:93], v[158:161], v[212:215], v[90:93]
	v_mfma_f32_16x16x32_bf16 v[90:93], v[154:157], v[208:211], v[90:93]
	v_mfma_f32_16x16x32_bf16 v[106:109], v[154:157], v[200:203], v[106:109]
	v_mfma_f32_16x16x32_bf16 v[106:109], v[158:161], v[204:207], v[106:109]
	v_mfma_f32_16x16x32_bf16 v[122:125], v[158:161], v[196:199], v[122:125]
	v_mfma_f32_16x16x32_bf16 v[122:125], v[154:157], v[192:195], v[122:125]
	v_mfma_f32_16x16x32_bf16 v[118:121], v[162:165], v[192:195], v[118:121]
	v_mfma_f32_16x16x32_bf16 v[118:121], v[166:169], v[196:199], v[118:121]
	v_mfma_f32_16x16x32_bf16 v[102:105], v[166:169], v[204:207], v[102:105]
	v_mfma_f32_16x16x32_bf16 v[102:105], v[162:165], v[200:203], v[102:105]
	v_mfma_f32_16x16x32_bf16 v[86:89], v[162:165], v[208:211], v[86:89]
	v_mfma_f32_16x16x32_bf16 v[86:89], v[166:169], v[212:215], v[86:89]
	v_mfma_f32_16x16x32_bf16 v[70:73], v[166:169], v[220:223], v[70:73]
	v_mfma_f32_16x16x32_bf16 v[70:73], v[162:165], v[216:219], v[70:73]
	v_mfma_f32_16x16x32_bf16 v[66:69], v[184:187], v[216:219], v[66:69]
	v_mfma_f32_16x16x32_bf16 v[66:69], v[188:191], v[220:223], v[66:69]
	v_mfma_f32_16x16x32_bf16 v[82:85], v[188:191], v[212:215], v[82:85]
	v_mfma_f32_16x16x32_bf16 v[82:85], v[184:187], v[208:211], v[82:85]
	s_barrier
	s_setprio 2
	v_mfma_f32_16x16x32_bf16 v[98:101], v[184:187], v[200:203], v[98:101]
	v_mfma_f32_16x16x32_bf16 v[98:101], v[188:191], v[204:207], v[98:101]
	v_mfma_f32_16x16x32_bf16 v[114:117], v[188:191], v[196:199], v[114:117]
	v_mfma_f32_16x16x32_bf16 v[114:117], v[184:187], v[192:195], v[114:117]
	s_setprio 0
	v_lshl_add_u64 v[170:171], s[80:81], 0, v[138:139]
	s_add_i32 s80, s12, s55
	s_mov_b32 m0, s80
	ds_read_b128 v[192:195], v178 offset:16384
	ds_read_b128 v[196:199], v178 offset:17408
	ds_read_b128 v[200:203], v178 offset:18432
	ds_read_b128 v[204:207], v178 offset:19456
	ds_read_b128 v[208:211], v178 offset:20480
	ds_read_b128 v[212:215], v178 offset:21504
	ds_read_b128 v[216:219], v178 offset:22528
	ds_read_b128 v[220:223], v178 offset:23552
	global_load_lds_dwordx4 v[170:171], off
	v_lshl_add_u64 v[224:225], v[170:171], 0, s[18:19]
	s_add_i32 m0, s80, 0x2000
	s_add_i32 s80, s13, s55
	global_load_lds_dwordx4 v[224:225], off
	v_lshl_add_u64 v[224:225], v[170:171], 0, s[20:21]
	s_mov_b32 m0, s80
	s_nop 0
	global_load_lds_dwordx4 v[224:225], off
	v_lshl_add_u64 v[224:225], v[170:171], 0, s[22:23]
	s_add_i32 m0, s80, 0x2000
	s_nop 0
	global_load_lds_dwordx4 v[224:225], off
	v_lshl_add_u64 v[224:225], s[82:83], 0, v[138:139]
	s_mov_b32 m0, s56
	v_lshl_add_u64 v[226:227], v[224:225], 0, s[18:19]
	global_load_lds_dwordx4 v[224:225], off
	s_mov_b32 m0, s57
	s_nop 0
	global_load_lds_dwordx4 v[226:227], off
	s_waitcnt vmcnt(8)
	s_waitcnt lgkmcnt(0)
	s_barrier
; #define PG8_STAGE(bufoff, gbase, voff) do { if constexpr (!pg8_noload<Epi>::value) { _Pragma("unroll") for (int _i = 0; _i < 2; ++_i) \
;         __builtin_amdgcn_global_load_lds((const unsigned*)((const char*)(gbase) + (size_t)_i * pstep + (voff)[0]), (PG8_LAS unsigned*)(lds + (bufoff) + ldsw + _i * 8192), 16, 0, 0); } } while (0)
; #define PG8_LDA(dst, b, h) do { _Pragma("unroll") for (int m = 0; m < 4; ++m) _Pragma("unroll") for (int k = 0; k < 2; ++k) dst[m][k] = *(const PG8_LAS bf16x8*)(lds + PG8_SA(b, h) + aoff + m * 2048 + k * 1024); } while (0)
; #define PG8_LDB(dst, b, h) do { _Pragma("unroll") for (int n = 0; n < 2; ++n) _Pragma("unroll") for (int k = 0; k < 2; ++k) dst[n][k] = *(const PG8_LAS bf16x8*)(lds + PG8_SB(b, h) + boff + n * 2048 + k * 1024); } while (0)
; #define PG8_MMA(ai, bj, At, Bt) do { __builtin_amdgcn_s_setprio(1); _Pragma("unroll") for (int m = 0; m < 4; ++m) _Pragma("unroll") for (int n = 0; n < 2; ++n) _Pragma("unroll") for (int k = 0; k < 2; ++k) \
;         acc[ai][bj][m][n] = __builtin_amdgcn_mfma_f32_16x16x32_bf16(Bt[n][k], At[m][k], acc[ai][bj][m][n], 0, 0, 0); __builtin_amdgcn_s_setprio(0); } while (0)
; #define PG8_WAIT_V(n) asm volatile("s_waitcnt vmcnt(" #n ")" ::: "memory")
; #define PG8_WAIT_L(n) asm volatile("s_waitcnt lgkmcnt(" #n ")" ::: "memory")
; #define PG8_BAR __builtin_amdgcn_s_barrier()
; #define PG8_SCHED __builtin_amdgcn_sched_barrier(0)
; template <class Epi, class Sched, bool ALIGN_EPI = false, bool SP2 = false, bool ABLK = false>
; __device__ __forceinline__ void gemm_phase(PG8_LAS unsigned char* lds, const Gemm g, const Sched& S, const Epi& E) {
;     ...
;             PG8_LDA(At, 0, 1); PG8_STAGE(PG8_SB(0, 0), b2, voffB); PG8_STAGE(PG8_SB(0, 1), b2 + hstep, voffB); PG8_STAGE(PG8_SA(0, 0), a2, voffA);
;             PG8_WAIT_V(8); PG8_WAIT_L(0); PG8_BAR; PG8_MMA(1, 0, At, B0); PG8_MMA(1, 1, At, B1); PG8_BAR; PG8_SCHED;
;             PG8_LDB(B0, 1, 0); PG8_LDB(B1, 1, 1); PG8_SCHED; PG8_LDA(At, 1, 0); PG8_STAGE(PG8_SA(0, 1), a2 + hstep, voffA);
;             PG8_WAIT_V(8); PG8_WAIT_L(0); PG8_BAR; PG8_MMA(0, 0, At, B0); PG8_MMA(0, 1, At, B1); PG8_BAR; PG8_SCHED;
	s_setprio 1
	s_waitcnt lgkmcnt(0)
	v_mfma_f32_16x16x32_bf16 v[62:65], v[130:133], v[192:195], v[62:65]
	v_mfma_f32_16x16x32_bf16 v[62:65], v[134:137], v[196:199], v[62:65]
	v_mfma_f32_16x16x32_bf16 v[46:49], v[134:137], v[204:207], v[46:49]
	v_mfma_f32_16x16x32_bf16 v[46:49], v[130:133], v[200:203], v[46:49]
	v_mfma_f32_16x16x32_bf16 v[30:33], v[130:133], v[208:211], v[30:33]
	v_mfma_f32_16x16x32_bf16 v[30:33], v[134:137], v[212:215], v[30:33]
	v_mfma_f32_16x16x32_bf16 v[14:17], v[134:137], v[220:223], v[14:17]
	v_mfma_f32_16x16x32_bf16 v[14:17], v[130:133], v[216:219], v[14:17]
	v_mfma_f32_16x16x32_bf16 v[10:13], v[154:157], v[216:219], v[10:13]
	v_mfma_f32_16x16x32_bf16 v[10:13], v[158:161], v[220:223], v[10:13]
	v_mfma_f32_16x16x32_bf16 v[26:29], v[158:161], v[212:215], v[26:29]
	v_mfma_f32_16x16x32_bf16 v[26:29], v[154:157], v[208:211], v[26:29]
	v_mfma_f32_16x16x32_bf16 v[42:45], v[154:157], v[200:203], v[42:45]
	v_mfma_f32_16x16x32_bf16 v[42:45], v[158:161], v[204:207], v[42:45]
	v_mfma_f32_16x16x32_bf16 v[58:61], v[158:161], v[196:199], v[58:61]
	v_mfma_f32_16x16x32_bf16 v[58:61], v[154:157], v[192:195], v[58:61]
	v_mfma_f32_16x16x32_bf16 v[54:57], v[162:165], v[192:195], v[54:57]
	v_mfma_f32_16x16x32_bf16 v[54:57], v[166:169], v[196:199], v[54:57]
	v_mfma_f32_16x16x32_bf16 v[38:41], v[166:169], v[204:207], v[38:41]
	v_mfma_f32_16x16x32_bf16 v[38:41], v[162:165], v[200:203], v[38:41]
	v_mfma_f32_16x16x32_bf16 v[22:25], v[162:165], v[208:211], v[22:25]
	v_mfma_f32_16x16x32_bf16 v[22:25], v[166:169], v[212:215], v[22:25]
	v_mfma_f32_16x16x32_bf16 v[6:9], v[166:169], v[220:223], v[6:9]
	v_mfma_f32_16x16x32_bf16 v[6:9], v[162:165], v[216:219], v[6:9]
	v_mfma_f32_16x16x32_bf16 v[2:5], v[184:187], v[216:219], v[2:5]
	v_mfma_f32_16x16x32_bf16 v[2:5], v[188:191], v[220:223], v[2:5]
	v_mfma_f32_16x16x32_bf16 v[18:21], v[188:191], v[212:215], v[18:21]
	v_mfma_f32_16x16x32_bf16 v[18:21], v[184:187], v[208:211], v[18:21]
	s_barrier
	s_setprio 2
	v_mfma_f32_16x16x32_bf16 v[34:37], v[184:187], v[200:203], v[34:37]
	v_mfma_f32_16x16x32_bf16 v[34:37], v[188:191], v[204:207], v[34:37]
	v_mfma_f32_16x16x32_bf16 v[50:53], v[188:191], v[196:199], v[50:53]
	v_mfma_f32_16x16x32_bf16 v[50:53], v[184:187], v[192:195], v[50:53]
	s_setprio 0
	s_add_i32 s80, 0, 0x18000
	v_add_u32_e32 v140, s80, v173
	s_add_i32 s81, 0, 0x1c000
	ds_read_b128 v[130:133], v140
	ds_read_b128 v[134:137], v140 offset:1024
	ds_read_b128 v[154:157], v140 offset:2048
	ds_read_b128 v[158:161], v140 offset:3072
	v_add_u32_e32 v140, s81, v173
	ds_read_b128 v[162:165], v140
	ds_read_b128 v[166:169], v140 offset:1024
	ds_read_b128 v[184:187], v140 offset:2048
	ds_read_b128 v[188:191], v140 offset:3072
	s_mov_b32 m0, s58
	v_lshl_add_u64 v[226:227], v[224:225], 0, s[20:21]
	ds_read_b128 v[192:195], v178 offset:32768
	ds_read_b128 v[196:199], v178 offset:33792
	ds_read_b128 v[200:203], v178 offset:34816
	ds_read_b128 v[204:207], v178 offset:35840
	ds_read_b128 v[208:211], v178 offset:36864
	ds_read_b128 v[212:215], v178 offset:37888
	ds_read_b128 v[216:219], v178 offset:38912
	ds_read_b128 v[220:223], v178 offset:39936
	global_load_lds_dwordx4 v[226:227], off
	v_lshl_add_u64 v[226:227], v[224:225], 0, s[22:23]
	s_mov_b32 m0, s59
	s_nop 0
	global_load_lds_dwordx4 v[226:227], off
	s_waitcnt vmcnt(8)
	s_waitcnt lgkmcnt(0)
	s_barrier
	s_setprio 1
	s_waitcnt lgkmcnt(0)
	v_mfma_f32_16x16x32_bf16 v[126:129], v[130:133], v[192:195], v[126:129]
	v_mfma_f32_16x16x32_bf16 v[126:129], v[134:137], v[196:199], v[126:129]
	v_mfma_f32_16x16x32_bf16 v[110:113], v[134:137], v[204:207], v[110:113]
	v_mfma_f32_16x16x32_bf16 v[110:113], v[130:133], v[200:203], v[110:113]
	v_mfma_f32_16x16x32_bf16 v[94:97], v[130:133], v[208:211], v[94:97]
	v_mfma_f32_16x16x32_bf16 v[94:97], v[134:137], v[212:215], v[94:97]
	v_mfma_f32_16x16x32_bf16 v[78:81], v[134:137], v[220:223], v[78:81]
	v_mfma_f32_16x16x32_bf16 v[78:81], v[130:133], v[216:219], v[78:81]
	v_mfma_f32_16x16x32_bf16 v[74:77], v[154:157], v[216:219], v[74:77]
	v_mfma_f32_16x16x32_bf16 v[74:77], v[158:161], v[220:223], v[74:77]
	v_mfma_f32_16x16x32_bf16 v[90:93], v[158:161], v[212:215], v[90:93]
	v_mfma_f32_16x16x32_bf16 v[90:93], v[154:157], v[208:211], v[90:93]
	v_mfma_f32_16x16x32_bf16 v[106:109], v[154:157], v[200:203], v[106:109]
	v_mfma_f32_16x16x32_bf16 v[106:109], v[158:161], v[204:207], v[106:109]
	v_mfma_f32_16x16x32_bf16 v[122:125], v[158:161], v[196:199], v[122:125]
	v_mfma_f32_16x16x32_bf16 v[122:125], v[154:157], v[192:195], v[122:125]
	v_mfma_f32_16x16x32_bf16 v[118:121], v[162:165], v[192:195], v[118:121]
	v_mfma_f32_16x16x32_bf16 v[118:121], v[166:169], v[196:199], v[118:121]
	v_mfma_f32_16x16x32_bf16 v[102:105], v[166:169], v[204:207], v[102:105]
	v_mfma_f32_16x16x32_bf16 v[102:105], v[162:165], v[200:203], v[102:105]
	v_mfma_f32_16x16x32_bf16 v[86:89], v[162:165], v[208:211], v[86:89]
	v_mfma_f32_16x16x32_bf16 v[86:89], v[166:169], v[212:215], v[86:89]
	v_mfma_f32_16x16x32_bf16 v[70:73], v[166:169], v[220:223], v[70:73]
	v_mfma_f32_16x16x32_bf16 v[70:73], v[162:165], v[216:219], v[70:73]
	v_mfma_f32_16x16x32_bf16 v[66:69], v[184:187], v[216:219], v[66:69]
	v_mfma_f32_16x16x32_bf16 v[66:69], v[188:191], v[220:223], v[66:69]
	v_mfma_f32_16x16x32_bf16 v[82:85], v[188:191], v[212:215], v[82:85]
	v_mfma_f32_16x16x32_bf16 v[82:85], v[184:187], v[208:211], v[82:85]
	s_barrier
; #define PG8_STAGE(bufoff, gbase, voff) do { if constexpr (!pg8_noload<Epi>::value) { _Pragma("unroll") for (int _i = 0; _i < 2; ++_i) \
;         __builtin_amdgcn_global_load_lds((const unsigned*)((const char*)(gbase) + (size_t)_i * pstep + (voff)[0]), (PG8_LAS unsigned*)(lds + (bufoff) + ldsw + _i * 8192), 16, 0, 0); } } while (0)
; #define PG8_LDA(dst, b, h) do { _Pragma("unroll") for (int m = 0; m < 4; ++m) _Pragma("unroll") for (int k = 0; k < 2; ++k) dst[m][k] = *(const PG8_LAS bf16x8*)(lds + PG8_SA(b, h) + aoff + m * 2048 + k * 1024); } while (0)
; #define PG8_MMA(ai, bj, At, Bt) do { __builtin_amdgcn_s_setprio(1); _Pragma("unroll") for (int m = 0; m < 4; ++m) _Pragma("unroll") for (int n = 0; n < 2; ++n) _Pragma("unroll") for (int k = 0; k < 2; ++k) \
;         acc[ai][bj][m][n] = __builtin_amdgcn_mfma_f32_16x16x32_bf16(Bt[n][k], At[m][k], acc[ai][bj][m][n], 0, 0, 0); __builtin_amdgcn_s_setprio(0); } while (0)
; #define PG8_WAIT_V(n) asm volatile("s_waitcnt vmcnt(" #n ")" ::: "memory")
; #define PG8_WAIT_L(n) asm volatile("s_waitcnt lgkmcnt(" #n ")" ::: "memory")
; #define PG8_BAR __builtin_amdgcn_s_barrier()
; #define PG8_SCHED __builtin_amdgcn_sched_barrier(0)
; template <class Epi, class Sched, bool ALIGN_EPI = false, bool SP2 = false, bool ABLK = false>
; __device__ __forceinline__ void gemm_phase(PG8_LAS unsigned char* lds, const Gemm g, const Sched& S, const Epi& E) {
;     ...
;             PG8_WAIT_V(8); PG8_WAIT_L(0); PG8_BAR; PG8_MMA(0, 0, At, B0); PG8_MMA(0, 1, At, B1); PG8_BAR; PG8_SCHED;
;             PG8_LDA(At, 1, 1); PG8_STAGE(PG8_SB(1, 0), b3, voffB); PG8_STAGE(PG8_SB(1, 1), b3 + hstep, voffB); PG8_STAGE(PG8_SA(1, 0), a3, voffA);
;             PG8_WAIT_V(8); PG8_WAIT_L(0); PG8_BAR; PG8_MMA(1, 0, At, B0); PG8_MMA(1, 1, At, B1); PG8_BAR; PG8_SCHED;
	s_setprio 2
	v_mfma_f32_16x16x32_bf16 v[98:101], v[184:187], v[200:203], v[98:101]
	v_mfma_f32_16x16x32_bf16 v[98:101], v[188:191], v[204:207], v[98:101]
	v_mfma_f32_16x16x32_bf16 v[114:117], v[188:191], v[196:199], v[114:117]
	v_mfma_f32_16x16x32_bf16 v[114:117], v[184:187], v[192:195], v[114:117]
	s_setprio 0
	s_add_i32 s80, s80, s55
	v_lshl_add_u64 v[226:227], v[170:171], 0, s[30:31]
	s_mov_b32 m0, s80
	ds_read_b128 v[192:195], v178 offset:49152
	ds_read_b128 v[196:199], v178 offset:50176
	ds_read_b128 v[200:203], v178 offset:51200
	ds_read_b128 v[204:207], v178 offset:52224
	ds_read_b128 v[208:211], v178 offset:53248
	ds_read_b128 v[212:215], v178 offset:54272
	ds_read_b128 v[216:219], v178 offset:55296
	ds_read_b128 v[220:223], v178 offset:56320
	global_load_lds_dwordx4 v[226:227], off
	v_lshl_add_u64 v[226:227], v[170:171], 0, s[34:35]
	s_add_i32 m0, s80, 0x2000
	s_add_i32 s80, s81, s55
	global_load_lds_dwordx4 v[226:227], off
	v_lshl_add_u64 v[226:227], v[170:171], 0, s[36:37]
	s_mov_b32 m0, s80
	v_lshl_add_u64 v[170:171], v[170:171], 0, s[38:39]
	global_load_lds_dwordx4 v[226:227], off
	s_add_i32 m0, s80, 0x2000
	s_nop 0
	global_load_lds_dwordx4 v[170:171], off
	v_lshl_add_u64 v[170:171], v[224:225], 0, s[30:31]
	s_mov_b32 m0, s63
	s_nop 0
	global_load_lds_dwordx4 v[170:171], off
	v_lshl_add_u64 v[170:171], v[224:225], 0, s[34:35]
	s_mov_b32 m0, s73
	s_nop 0
	global_load_lds_dwordx4 v[170:171], off
	s_waitcnt vmcnt(8)
	s_waitcnt lgkmcnt(0)
	s_barrier
	s_setprio 1
	s_waitcnt lgkmcnt(0)
	v_mfma_f32_16x16x32_bf16 v[62:65], v[130:133], v[192:195], v[62:65]
	v_mfma_f32_16x16x32_bf16 v[62:65], v[134:137], v[196:199], v[62:65]
	v_mfma_f32_16x16x32_bf16 v[46:49], v[134:137], v[204:207], v[46:49]
	v_mfma_f32_16x16x32_bf16 v[46:49], v[130:133], v[200:203], v[46:49]
	v_mfma_f32_16x16x32_bf16 v[30:33], v[130:133], v[208:211], v[30:33]
	v_mfma_f32_16x16x32_bf16 v[30:33], v[134:137], v[212:215], v[30:33]
	v_mfma_f32_16x16x32_bf16 v[14:17], v[134:137], v[220:223], v[14:17]
	v_mfma_f32_16x16x32_bf16 v[14:17], v[130:133], v[216:219], v[14:17]
	v_mfma_f32_16x16x32_bf16 v[10:13], v[154:157], v[216:219], v[10:13]
	v_mfma_f32_16x16x32_bf16 v[10:13], v[158:161], v[220:223], v[10:13]
	v_mfma_f32_16x16x32_bf16 v[26:29], v[158:161], v[212:215], v[26:29]
	v_mfma_f32_16x16x32_bf16 v[26:29], v[154:157], v[208:211], v[26:29]
	v_mfma_f32_16x16x32_bf16 v[42:45], v[154:157], v[200:203], v[42:45]
	v_mfma_f32_16x16x32_bf16 v[42:45], v[158:161], v[204:207], v[42:45]
	v_mfma_f32_16x16x32_bf16 v[58:61], v[158:161], v[196:199], v[58:61]
	v_mfma_f32_16x16x32_bf16 v[58:61], v[154:157], v[192:195], v[58:61]
	v_mfma_f32_16x16x32_bf16 v[54:57], v[162:165], v[192:195], v[54:57]
	v_mfma_f32_16x16x32_bf16 v[54:57], v[166:169], v[196:199], v[54:57]
	v_mfma_f32_16x16x32_bf16 v[38:41], v[166:169], v[204:207], v[38:41]
	v_mfma_f32_16x16x32_bf16 v[38:41], v[162:165], v[200:203], v[38:41]
	v_mfma_f32_16x16x32_bf16 v[22:25], v[162:165], v[208:211], v[22:25]
	v_mfma_f32_16x16x32_bf16 v[22:25], v[166:169], v[212:215], v[22:25]
	v_mfma_f32_16x16x32_bf16 v[6:9], v[166:169], v[220:223], v[6:9]
	v_mfma_f32_16x16x32_bf16 v[6:9], v[162:165], v[216:219], v[6:9]
	v_mfma_f32_16x16x32_bf16 v[2:5], v[184:187], v[216:219], v[2:5]
	v_mfma_f32_16x16x32_bf16 v[2:5], v[188:191], v[220:223], v[2:5]
	v_mfma_f32_16x16x32_bf16 v[18:21], v[188:191], v[212:215], v[18:21]
	v_mfma_f32_16x16x32_bf16 v[18:21], v[184:187], v[208:211], v[18:21]
	s_barrier
	s_setprio 2
	v_mfma_f32_16x16x32_bf16 v[34:37], v[184:187], v[200:203], v[34:37]
	v_mfma_f32_16x16x32_bf16 v[34:37], v[188:191], v[204:207], v[34:37]
	v_mfma_f32_16x16x32_bf16 v[50:53], v[188:191], v[196:199], v[50:53]
	v_mfma_f32_16x16x32_bf16 v[50:53], v[184:187], v[192:195], v[50:53]
	s_setprio 0
	s_cmp_gt_u32 s94, 29
	s_mov_b32 s94, s26
	s_cbranch_scc1 .LBB0_1669

; #define PG8_STAGE(bufoff, gbase, voff) do { if constexpr (!pg8_noload<Epi>::value) { _Pragma("unroll") for (int _i = 0; _i < 2; ++_i) \
;         __builtin_amdgcn_global_load_lds((const unsigned*)((const char*)(gbase) + (size_t)_i * pstep + (voff)[0]), (PG8_LAS unsigned*)(lds + (bufoff) + ldsw + _i * 8192), 16, 0, 0); } } while (0)
; #define PG8_LDA(dst, b, h) do { _Pragma("unroll") for (int m = 0; m < 4; ++m) _Pragma("unroll") for (int k = 0; k < 2; ++k) dst[m][k] = *(const PG8_LAS bf16x8*)(lds + PG8_SA(b, h) + aoff + m * 2048 + k * 1024); } while (0)
; #define PG8_LDB(dst, b, h) do { _Pragma("unroll") for (int n = 0; n < 2; ++n) _Pragma("unroll") for (int k = 0; k < 2; ++k) dst[n][k] = *(const PG8_LAS bf16x8*)(lds + PG8_SB(b, h) + boff + n * 2048 + k * 1024); } while (0)
; #define PG8_MMA(ai, bj, At, Bt) do { __builtin_amdgcn_s_setprio(1); _Pragma("unroll") for (int m = 0; m < 4; ++m) _Pragma("unroll") for (int n = 0; n < 2; ++n) _Pragma("unroll") for (int k = 0; k < 2; ++k) \
;         acc[ai][bj][m][n] = __builtin_amdgcn_mfma_f32_16x16x32_bf16(Bt[n][k], At[m][k], acc[ai][bj][m][n], 0, 0, 0); __builtin_amdgcn_s_setprio(0); } while (0)
; #define PG8_WAIT_V(n) asm volatile("s_waitcnt vmcnt(" #n ")" ::: "memory")
; #define PG8_WAIT_L(n) asm volatile("s_waitcnt lgkmcnt(" #n ")" ::: "memory")
; template <class Epi, class Sched, bool ALIGN_EPI = false, bool SP2 = false, bool ABLK = false>
; __device__ __forceinline__ void gemm_phase(PG8_LAS unsigned char* lds, const Gemm g, const Sched& S, const Epi& E) {
;     ...
;         for (int t = 0; t < nt; t += 2) {
;             const bool last = (t == nt - 2);
;             const char* a1 = cA + (size_t)(t + 1) * kstep;
;             const char* a2 = last ? nA : cA + (size_t)(t + 2) * kstep; const char* b2 = last ? nB : cB + (size_t)(t + 2) * kstepB;
;             const char* a3 = a2 + kstep; const char* b3 = b2 + kstepB;
;             if (last && has_next) S.a_ready(nxt);
;             if constexpr (SP2) {
;             PG8_LDB(B0, 0, 0); PG8_LDB(B1, 0, 1); PG8_SCHED; PG8_LDA(At, 0, 0); PG8_STAGE(PG8_SA(1, 1), a1 + hstep, voffA);
;             PG8_WAIT_V(8); PG8_WAIT_L(0); PG8_BAR; PG8_MMA(0, 0, At, B0); PG8_MMA(0, 1, At, B1); PG8_BAR; PG8_SCHED;
;             PG8_LDA(At, 0, 1); PG8_STAGE(PG8_SB(0, 0), b2, voffB); PG8_STAGE(PG8_SB(0, 1), b2 + hstep, voffB); PG8_STAGE(PG8_SA(0, 0), a2, voffA);
.LBB0_1997:
	ds_read_b128 v[130:133], v175
	ds_read_b128 v[134:137], v175 offset:1024
	ds_read_b128 v[138:141], v175 offset:2048
	ds_read_b128 v[142:145], v175 offset:3072
	ds_read_b128 v[146:149], v176
	ds_read_b128 v[150:153], v176 offset:1024
	ds_read_b128 v[154:157], v176 offset:2048
	ds_read_b128 v[158:161], v176 offset:3072
	s_add_i32 s43, s41, 2
	s_add_u32 s62, s52, 0xfff80800
	s_addc_u32 s63, s53, -1
	s_cmp_eq_u32 s3, s41
	s_cselect_b32 s63, s45, s63
	s_cselect_b32 s62, s44, s62
	s_cselect_b32 s77, s47, s39
	s_cselect_b32 s76, s46, s11
	v_lshl_add_u64 v[170:171], s[52:53], 0, v[166:167]
	s_add_i32 m0, s49, 0xc000
	ds_read_b128 v[184:187], v177
	ds_read_b128 v[188:191], v177 offset:1024
	ds_read_b128 v[192:195], v177 offset:2048
	ds_read_b128 v[196:199], v177 offset:3072
	ds_read_b128 v[200:203], v177 offset:4096
	ds_read_b128 v[204:207], v177 offset:5120
	ds_read_b128 v[208:211], v177 offset:6144
	ds_read_b128 v[212:215], v177 offset:7168
	global_load_lds_dwordx4 v[170:171], off
	v_lshl_add_u64 v[170:171], v[170:171], 0, s[12:13]
	s_add_i32 m0, s49, 0xe000
	s_nop 0
	global_load_lds_dwordx4 v[170:171], off
	s_waitcnt vmcnt(8)
	s_waitcnt lgkmcnt(0)
	s_barrier
	s_setprio 1
	s_waitcnt lgkmcnt(0)
	v_mfma_f32_16x16x32_bf16 v[126:129], v[130:133], v[184:187], v[126:129]
	v_mfma_f32_16x16x32_bf16 v[126:129], v[134:137], v[188:191], v[126:129]
	v_mfma_f32_16x16x32_bf16 v[110:113], v[134:137], v[196:199], v[110:113]
	v_mfma_f32_16x16x32_bf16 v[110:113], v[130:133], v[192:195], v[110:113]
	v_mfma_f32_16x16x32_bf16 v[94:97], v[130:133], v[200:203], v[94:97]
	v_mfma_f32_16x16x32_bf16 v[94:97], v[134:137], v[204:207], v[94:97]
	v_mfma_f32_16x16x32_bf16 v[78:81], v[134:137], v[212:215], v[78:81]
	v_mfma_f32_16x16x32_bf16 v[78:81], v[130:133], v[208:211], v[78:81]
	v_mfma_f32_16x16x32_bf16 v[74:77], v[138:141], v[208:211], v[74:77]
	v_mfma_f32_16x16x32_bf16 v[74:77], v[142:145], v[212:215], v[74:77]
	v_mfma_f32_16x16x32_bf16 v[90:93], v[142:145], v[204:207], v[90:93]
	v_mfma_f32_16x16x32_bf16 v[90:93], v[138:141], v[200:203], v[90:93]
	v_mfma_f32_16x16x32_bf16 v[106:109], v[138:141], v[192:195], v[106:109]
	v_mfma_f32_16x16x32_bf16 v[106:109], v[142:145], v[196:199], v[106:109]
	v_mfma_f32_16x16x32_bf16 v[122:125], v[142:145], v[188:191], v[122:125]
	v_mfma_f32_16x16x32_bf16 v[122:125], v[138:141], v[184:187], v[122:125]
	v_mfma_f32_16x16x32_bf16 v[118:121], v[146:149], v[184:187], v[118:121]
	v_mfma_f32_16x16x32_bf16 v[118:121], v[150:153], v[188:191], v[118:121]
	v_mfma_f32_16x16x32_bf16 v[102:105], v[150:153], v[196:199], v[102:105]
	v_mfma_f32_16x16x32_bf16 v[102:105], v[146:149], v[192:195], v[102:105]
	v_mfma_f32_16x16x32_bf16 v[86:89], v[146:149], v[200:203], v[86:89]
	v_mfma_f32_16x16x32_bf16 v[86:89], v[150:153], v[204:207], v[86:89]
	v_mfma_f32_16x16x32_bf16 v[70:73], v[150:153], v[212:215], v[70:73]
	v_mfma_f32_16x16x32_bf16 v[70:73], v[146:149], v[208:211], v[70:73]
	v_mfma_f32_16x16x32_bf16 v[66:69], v[154:157], v[208:211], v[66:69]
	v_mfma_f32_16x16x32_bf16 v[66:69], v[158:161], v[212:215], v[66:69]
	v_mfma_f32_16x16x32_bf16 v[82:85], v[158:161], v[204:207], v[82:85]
	v_mfma_f32_16x16x32_bf16 v[82:85], v[154:157], v[200:203], v[82:85]
	s_barrier
	s_setprio 2
	v_mfma_f32_16x16x32_bf16 v[98:101], v[154:157], v[192:195], v[98:101]
	v_mfma_f32_16x16x32_bf16 v[98:101], v[158:161], v[196:199], v[98:101]
	v_mfma_f32_16x16x32_bf16 v[114:117], v[158:161], v[188:191], v[114:117]
	v_mfma_f32_16x16x32_bf16 v[114:117], v[154:157], v[184:187], v[114:117]
	s_setprio 0
	s_add_i32 s41, s70, s57
	v_lshl_add_u64 v[170:171], s[76:77], 0, v[162:163]
	s_mov_b32 m0, s41
	ds_read_b128 v[184:187], v177 offset:16384
	ds_read_b128 v[188:191], v177 offset:17408
	ds_read_b128 v[192:195], v177 offset:18432
	ds_read_b128 v[196:199], v177 offset:19456
	ds_read_b128 v[200:203], v177 offset:20480
	ds_read_b128 v[204:207], v177 offset:21504
	ds_read_b128 v[208:211], v177 offset:22528
	ds_read_b128 v[212:215], v177 offset:23552
	global_load_lds_dwordx4 v[170:171], off
	v_lshl_add_u64 v[216:217], v[170:171], 0, s[12:13]
	s_add_i32 m0, s41, 0x2000
	s_add_i32 s41, s71, s57
	global_load_lds_dwordx4 v[216:217], off
	v_lshl_add_u64 v[216:217], v[170:171], 0, s[14:15]
	s_mov_b32 m0, s41
	s_nop 0
	global_load_lds_dwordx4 v[216:217], off
	v_lshl_add_u64 v[216:217], v[170:171], 0, s[16:17]
	s_add_i32 m0, s41, 0x2000
	s_nop 0
	global_load_lds_dwordx4 v[216:217], off
	v_lshl_add_u64 v[216:217], s[62:63], 0, v[162:163]
	s_mov_b32 m0, s49
	v_lshl_add_u64 v[218:219], v[216:217], 0, s[12:13]
	global_load_lds_dwordx4 v[216:217], off
	s_mov_b32 m0, s58
	s_nop 0
	global_load_lds_dwordx4 v[218:219], off
	s_waitcnt vmcnt(8)
	s_waitcnt lgkmcnt(0)
	s_barrier
; #define PG8_STAGE(bufoff, gbase, voff) do { if constexpr (!pg8_noload<Epi>::value) { _Pragma("unroll") for (int _i = 0; _i < 2; ++_i) \
;         __builtin_amdgcn_global_load_lds((const unsigned*)((const char*)(gbase) + (size_t)_i * pstep + (voff)[0]), (PG8_LAS unsigned*)(lds + (bufoff) + ldsw + _i * 8192), 16, 0, 0); } } while (0)
; #define PG8_LDA(dst, b, h) do { _Pragma("unroll") for (int m = 0; m < 4; ++m) _Pragma("unroll") for (int k = 0; k < 2; ++k) dst[m][k] = *(const PG8_LAS bf16x8*)(lds + PG8_SA(b, h) + aoff + m * 2048 + k * 1024); } while (0)
; #define PG8_LDB(dst, b, h) do { _Pragma("unroll") for (int n = 0; n < 2; ++n) _Pragma("unroll") for (int k = 0; k < 2; ++k) dst[n][k] = *(const PG8_LAS bf16x8*)(lds + PG8_SB(b, h) + boff + n * 2048 + k * 1024); } while (0)
; #define PG8_MMA(ai, bj, At, Bt) do { __builtin_amdgcn_s_setprio(1); _Pragma("unroll") for (int m = 0; m < 4; ++m) _Pragma("unroll") for (int n = 0; n < 2; ++n) _Pragma("unroll") for (int k = 0; k < 2; ++k) \
;         acc[ai][bj][m][n] = __builtin_amdgcn_mfma_f32_16x16x32_bf16(Bt[n][k], At[m][k], acc[ai][bj][m][n], 0, 0, 0); __builtin_amdgcn_s_setprio(0); } while (0)
; #define PG8_WAIT_V(n) asm volatile("s_waitcnt vmcnt(" #n ")" ::: "memory")
; #define PG8_WAIT_L(n) asm volatile("s_waitcnt lgkmcnt(" #n ")" ::: "memory")
; #define PG8_BAR __builtin_amdgcn_s_barrier()
; #define PG8_SCHED __builtin_amdgcn_sched_barrier(0)
; template <class Epi, class Sched, bool ALIGN_EPI = false, bool SP2 = false, bool ABLK = false>
; __device__ __forceinline__ void gemm_phase(PG8_LAS unsigned char* lds, const Gemm g, const Sched& S, const Epi& E) {
;     ...
;             PG8_WAIT_V(8); PG8_WAIT_L(0); PG8_BAR; PG8_MMA(1, 0, At, B0); PG8_MMA(1, 1, At, B1); PG8_BAR; PG8_SCHED;
;             PG8_LDB(B0, 1, 0); PG8_LDB(B1, 1, 1); PG8_SCHED; PG8_LDA(At, 1, 0); PG8_STAGE(PG8_SA(0, 1), a2 + hstep, voffA);
;             PG8_WAIT_V(8); PG8_WAIT_L(0); PG8_BAR; PG8_MMA(0, 0, At, B0); PG8_MMA(0, 1, At, B1); PG8_BAR; PG8_SCHED;
	s_setprio 1
	s_waitcnt lgkmcnt(0)
	v_mfma_f32_16x16x32_bf16 v[62:65], v[130:133], v[184:187], v[62:65]
	v_mfma_f32_16x16x32_bf16 v[62:65], v[134:137], v[188:191], v[62:65]
	v_mfma_f32_16x16x32_bf16 v[46:49], v[134:137], v[196:199], v[46:49]
	v_mfma_f32_16x16x32_bf16 v[46:49], v[130:133], v[192:195], v[46:49]
	v_mfma_f32_16x16x32_bf16 v[30:33], v[130:133], v[200:203], v[30:33]
	v_mfma_f32_16x16x32_bf16 v[30:33], v[134:137], v[204:207], v[30:33]
	v_mfma_f32_16x16x32_bf16 v[14:17], v[134:137], v[212:215], v[14:17]
	v_mfma_f32_16x16x32_bf16 v[14:17], v[130:133], v[208:211], v[14:17]
	v_mfma_f32_16x16x32_bf16 v[10:13], v[138:141], v[208:211], v[10:13]
	v_mfma_f32_16x16x32_bf16 v[10:13], v[142:145], v[212:215], v[10:13]
	v_mfma_f32_16x16x32_bf16 v[26:29], v[142:145], v[204:207], v[26:29]
	v_mfma_f32_16x16x32_bf16 v[26:29], v[138:141], v[200:203], v[26:29]
	v_mfma_f32_16x16x32_bf16 v[42:45], v[138:141], v[192:195], v[42:45]
	v_mfma_f32_16x16x32_bf16 v[42:45], v[142:145], v[196:199], v[42:45]
	v_mfma_f32_16x16x32_bf16 v[58:61], v[142:145], v[188:191], v[58:61]
	v_mfma_f32_16x16x32_bf16 v[58:61], v[138:141], v[184:187], v[58:61]
	v_mfma_f32_16x16x32_bf16 v[54:57], v[146:149], v[184:187], v[54:57]
	v_mfma_f32_16x16x32_bf16 v[54:57], v[150:153], v[188:191], v[54:57]
	v_mfma_f32_16x16x32_bf16 v[38:41], v[150:153], v[196:199], v[38:41]
	v_mfma_f32_16x16x32_bf16 v[38:41], v[146:149], v[192:195], v[38:41]
	v_mfma_f32_16x16x32_bf16 v[22:25], v[146:149], v[200:203], v[22:25]
	v_mfma_f32_16x16x32_bf16 v[22:25], v[150:153], v[204:207], v[22:25]
	v_mfma_f32_16x16x32_bf16 v[6:9], v[150:153], v[212:215], v[6:9]
	v_mfma_f32_16x16x32_bf16 v[6:9], v[146:149], v[208:211], v[6:9]
	v_mfma_f32_16x16x32_bf16 v[2:5], v[154:157], v[208:211], v[2:5]
	v_mfma_f32_16x16x32_bf16 v[2:5], v[158:161], v[212:215], v[2:5]
	v_mfma_f32_16x16x32_bf16 v[18:21], v[158:161], v[204:207], v[18:21]
	v_mfma_f32_16x16x32_bf16 v[18:21], v[154:157], v[200:203], v[18:21]
	s_barrier
	s_setprio 2
	v_mfma_f32_16x16x32_bf16 v[34:37], v[154:157], v[192:195], v[34:37]
	v_mfma_f32_16x16x32_bf16 v[34:37], v[158:161], v[196:199], v[34:37]
	v_mfma_f32_16x16x32_bf16 v[50:53], v[158:161], v[188:191], v[50:53]
	v_mfma_f32_16x16x32_bf16 v[50:53], v[154:157], v[184:187], v[50:53]
	s_setprio 0
	s_add_i32 s41, 0, 0x18000
	s_add_i32 s62, 0, 0x1c000
	v_add_u32_e32 v142, s41, v1
	v_add_u32_e32 v158, s62, v1
	ds_read_b128 v[130:133], v142
	ds_read_b128 v[134:137], v142 offset:1024
	ds_read_b128 v[138:141], v142 offset:2048
	ds_read_b128 v[142:145], v142 offset:3072
	ds_read_b128 v[146:149], v158
	ds_read_b128 v[150:153], v158 offset:1024
	ds_read_b128 v[154:157], v158 offset:2048
	ds_read_b128 v[158:161], v158 offset:3072
	s_mov_b32 m0, s59
	v_lshl_add_u64 v[218:219], v[216:217], 0, s[14:15]
	ds_read_b128 v[184:187], v177 offset:32768
	ds_read_b128 v[188:191], v177 offset:33792
	ds_read_b128 v[192:195], v177 offset:34816
	ds_read_b128 v[196:199], v177 offset:35840
	ds_read_b128 v[200:203], v177 offset:36864
	ds_read_b128 v[204:207], v177 offset:37888
	ds_read_b128 v[208:211], v177 offset:38912
	ds_read_b128 v[212:215], v177 offset:39936
	global_load_lds_dwordx4 v[218:219], off
	v_lshl_add_u64 v[218:219], v[216:217], 0, s[16:17]
	s_mov_b32 m0, s60
	s_nop 0
	global_load_lds_dwordx4 v[218:219], off
	s_waitcnt vmcnt(8)
	s_waitcnt lgkmcnt(0)
	s_barrier
	s_setprio 1
	s_waitcnt lgkmcnt(0)
	v_mfma_f32_16x16x32_bf16 v[126:129], v[130:133], v[184:187], v[126:129]
	v_mfma_f32_16x16x32_bf16 v[126:129], v[134:137], v[188:191], v[126:129]
	v_mfma_f32_16x16x32_bf16 v[110:113], v[134:137], v[196:199], v[110:113]
	v_mfma_f32_16x16x32_bf16 v[110:113], v[130:133], v[192:195], v[110:113]
	v_mfma_f32_16x16x32_bf16 v[94:97], v[130:133], v[200:203], v[94:97]
	v_mfma_f32_16x16x32_bf16 v[94:97], v[134:137], v[204:207], v[94:97]
	v_mfma_f32_16x16x32_bf16 v[78:81], v[134:137], v[212:215], v[78:81]
	v_mfma_f32_16x16x32_bf16 v[78:81], v[130:133], v[208:211], v[78:81]
	v_mfma_f32_16x16x32_bf16 v[74:77], v[138:141], v[208:211], v[74:77]
	v_mfma_f32_16x16x32_bf16 v[74:77], v[142:145], v[212:215], v[74:77]
	v_mfma_f32_16x16x32_bf16 v[90:93], v[142:145], v[204:207], v[90:93]
	v_mfma_f32_16x16x32_bf16 v[90:93], v[138:141], v[200:203], v[90:93]
	v_mfma_f32_16x16x32_bf16 v[106:109], v[138:141], v[192:195], v[106:109]
	v_mfma_f32_16x16x32_bf16 v[106:109], v[142:145], v[196:199], v[106:109]
	v_mfma_f32_16x16x32_bf16 v[122:125], v[142:145], v[188:191], v[122:125]
	v_mfma_f32_16x16x32_bf16 v[122:125], v[138:141], v[184:187], v[122:125]
	v_mfma_f32_16x16x32_bf16 v[118:121], v[146:149], v[184:187], v[118:121]
	v_mfma_f32_16x16x32_bf16 v[118:121], v[150:153], v[188:191], v[118:121]
	v_mfma_f32_16x16x32_bf16 v[102:105], v[150:153], v[196:199], v[102:105]
	v_mfma_f32_16x16x32_bf16 v[102:105], v[146:149], v[192:195], v[102:105]
	v_mfma_f32_16x16x32_bf16 v[86:89], v[146:149], v[200:203], v[86:89]
	v_mfma_f32_16x16x32_bf16 v[86:89], v[150:153], v[204:207], v[86:89]
	v_mfma_f32_16x16x32_bf16 v[70:73], v[150:153], v[212:215], v[70:73]
	v_mfma_f32_16x16x32_bf16 v[70:73], v[146:149], v[208:211], v[70:73]
	v_mfma_f32_16x16x32_bf16 v[66:69], v[154:157], v[208:211], v[66:69]
	v_mfma_f32_16x16x32_bf16 v[66:69], v[158:161], v[212:215], v[66:69]
	v_mfma_f32_16x16x32_bf16 v[82:85], v[158:161], v[204:207], v[82:85]
	v_mfma_f32_16x16x32_bf16 v[82:85], v[154:157], v[200:203], v[82:85]
	s_barrier
; #define PG8_STAGE(bufoff, gbase, voff) do { if constexpr (!pg8_noload<Epi>::value) { _Pragma("unroll") for (int _i = 0; _i < 2; ++_i) \
;         __builtin_amdgcn_global_load_lds((const unsigned*)((const char*)(gbase) + (size_t)_i * pstep + (voff)[0]), (PG8_LAS unsigned*)(lds + (bufoff) + ldsw + _i * 8192), 16, 0, 0); } } while (0)
; #define PG8_LDA(dst, b, h) do { _Pragma("unroll") for (int m = 0; m < 4; ++m) _Pragma("unroll") for (int k = 0; k < 2; ++k) dst[m][k] = *(const PG8_LAS bf16x8*)(lds + PG8_SA(b, h) + aoff + m * 2048 + k * 1024); } while (0)
; #define PG8_MMA(ai, bj, At, Bt) do { __builtin_amdgcn_s_setprio(1); _Pragma("unroll") for (int m = 0; m < 4; ++m) _Pragma("unroll") for (int n = 0; n < 2; ++n) _Pragma("unroll") for (int k = 0; k < 2; ++k) \
;         acc[ai][bj][m][n] = __builtin_amdgcn_mfma_f32_16x16x32_bf16(Bt[n][k], At[m][k], acc[ai][bj][m][n], 0, 0, 0); __builtin_amdgcn_s_setprio(0); } while (0)
; #define PG8_WAIT_V(n) asm volatile("s_waitcnt vmcnt(" #n ")" ::: "memory")
; #define PG8_WAIT_L(n) asm volatile("s_waitcnt lgkmcnt(" #n ")" ::: "memory")
; #define PG8_BAR __builtin_amdgcn_s_barrier()
; #define PG8_SCHED __builtin_amdgcn_sched_barrier(0)
; template <class Epi, class Sched, bool ALIGN_EPI = false, bool SP2 = false, bool ABLK = false>
; __device__ __forceinline__ void gemm_phase(PG8_LAS unsigned char* lds, const Gemm g, const Sched& S, const Epi& E) {
;     ...
;             PG8_WAIT_V(8); PG8_WAIT_L(0); PG8_BAR; PG8_MMA(0, 0, At, B0); PG8_MMA(0, 1, At, B1); PG8_BAR; PG8_SCHED;
;             PG8_LDA(At, 1, 1); PG8_STAGE(PG8_SB(1, 0), b3, voffB); PG8_STAGE(PG8_SB(1, 1), b3 + hstep, voffB); PG8_STAGE(PG8_SA(1, 0), a3, voffA);
;             PG8_WAIT_V(8); PG8_WAIT_L(0); PG8_BAR; PG8_MMA(1, 0, At, B0); PG8_MMA(1, 1, At, B1); PG8_BAR; PG8_SCHED;
	s_setprio 2
	v_mfma_f32_16x16x32_bf16 v[98:101], v[154:157], v[192:195], v[98:101]
	v_mfma_f32_16x16x32_bf16 v[98:101], v[158:161], v[196:199], v[98:101]
	v_mfma_f32_16x16x32_bf16 v[114:117], v[158:161], v[188:191], v[114:117]
	v_mfma_f32_16x16x32_bf16 v[114:117], v[154:157], v[184:187], v[114:117]
	s_setprio 0
	s_add_i32 s41, s41, s57
	v_lshl_add_u64 v[218:219], v[170:171], 0, s[24:25]
	s_mov_b32 m0, s41
	ds_read_b128 v[184:187], v177 offset:49152
	ds_read_b128 v[188:191], v177 offset:50176
	ds_read_b128 v[192:195], v177 offset:51200
	ds_read_b128 v[196:199], v177 offset:52224
	ds_read_b128 v[200:203], v177 offset:53248
	ds_read_b128 v[204:207], v177 offset:54272
	ds_read_b128 v[208:211], v177 offset:55296
	ds_read_b128 v[212:215], v177 offset:56320
	global_load_lds_dwordx4 v[218:219], off
	v_lshl_add_u64 v[218:219], v[170:171], 0, s[26:27]
	s_add_i32 m0, s41, 0x2000
	s_add_i32 s41, s62, s57
	global_load_lds_dwordx4 v[218:219], off
	v_lshl_add_u64 v[218:219], v[170:171], 0, s[28:29]
	s_mov_b32 m0, s41
	v_lshl_add_u64 v[170:171], v[170:171], 0, s[30:31]
	global_load_lds_dwordx4 v[218:219], off
	s_add_i32 m0, s41, 0x2000
	s_nop 0
	global_load_lds_dwordx4 v[170:171], off
	v_lshl_add_u64 v[170:171], v[216:217], 0, s[24:25]
	s_mov_b32 m0, s65
	s_nop 0
	global_load_lds_dwordx4 v[170:171], off
	v_lshl_add_u64 v[170:171], v[216:217], 0, s[26:27]
	s_mov_b32 m0, s66
	s_nop 0
	global_load_lds_dwordx4 v[170:171], off
	s_waitcnt vmcnt(8)
	s_waitcnt lgkmcnt(0)
	s_barrier
	s_setprio 1
	s_waitcnt lgkmcnt(0)
	v_mfma_f32_16x16x32_bf16 v[62:65], v[130:133], v[184:187], v[62:65]
	v_mfma_f32_16x16x32_bf16 v[62:65], v[134:137], v[188:191], v[62:65]
	v_mfma_f32_16x16x32_bf16 v[46:49], v[134:137], v[196:199], v[46:49]
	v_mfma_f32_16x16x32_bf16 v[46:49], v[130:133], v[192:195], v[46:49]
	v_mfma_f32_16x16x32_bf16 v[30:33], v[130:133], v[200:203], v[30:33]
	v_mfma_f32_16x16x32_bf16 v[30:33], v[134:137], v[204:207], v[30:33]
	v_mfma_f32_16x16x32_bf16 v[14:17], v[134:137], v[212:215], v[14:17]
	v_mfma_f32_16x16x32_bf16 v[14:17], v[130:133], v[208:211], v[14:17]
	v_mfma_f32_16x16x32_bf16 v[10:13], v[138:141], v[208:211], v[10:13]
	v_mfma_f32_16x16x32_bf16 v[10:13], v[142:145], v[212:215], v[10:13]
	v_mfma_f32_16x16x32_bf16 v[26:29], v[142:145], v[204:207], v[26:29]
	v_mfma_f32_16x16x32_bf16 v[26:29], v[138:141], v[200:203], v[26:29]
	v_mfma_f32_16x16x32_bf16 v[42:45], v[138:141], v[192:195], v[42:45]
	v_mfma_f32_16x16x32_bf16 v[42:45], v[142:145], v[196:199], v[42:45]
	v_mfma_f32_16x16x32_bf16 v[58:61], v[142:145], v[188:191], v[58:61]
	v_mfma_f32_16x16x32_bf16 v[58:61], v[138:141], v[184:187], v[58:61]
	v_mfma_f32_16x16x32_bf16 v[54:57], v[146:149], v[184:187], v[54:57]
	v_mfma_f32_16x16x32_bf16 v[54:57], v[150:153], v[188:191], v[54:57]
	v_mfma_f32_16x16x32_bf16 v[38:41], v[150:153], v[196:199], v[38:41]
	v_mfma_f32_16x16x32_bf16 v[38:41], v[146:149], v[192:195], v[38:41]
	v_mfma_f32_16x16x32_bf16 v[22:25], v[146:149], v[200:203], v[22:25]
	v_mfma_f32_16x16x32_bf16 v[22:25], v[150:153], v[204:207], v[22:25]
	v_mfma_f32_16x16x32_bf16 v[6:9], v[150:153], v[212:215], v[6:9]
	v_mfma_f32_16x16x32_bf16 v[6:9], v[146:149], v[208:211], v[6:9]
	v_mfma_f32_16x16x32_bf16 v[2:5], v[154:157], v[208:211], v[2:5]
	v_mfma_f32_16x16x32_bf16 v[2:5], v[158:161], v[212:215], v[2:5]
	v_mfma_f32_16x16x32_bf16 v[18:21], v[158:161], v[204:207], v[18:21]
	v_mfma_f32_16x16x32_bf16 v[18:21], v[154:157], v[200:203], v[18:21]
	s_barrier
	s_setprio 2
	v_mfma_f32_16x16x32_bf16 v[34:37], v[154:157], v[192:195], v[34:37]
	v_mfma_f32_16x16x32_bf16 v[34:37], v[158:161], v[196:199], v[34:37]
	v_mfma_f32_16x16x32_bf16 v[50:53], v[158:161], v[188:191], v[50:53]
	v_mfma_f32_16x16x32_bf16 v[50:53], v[154:157], v[184:187], v[50:53]
	s_setprio 0
	s_add_u32 s52, s52, 0x1000
	s_addc_u32 s53, s53, 0
	s_add_u32 s11, s11, 0x1000
	s_addc_u32 s39, s39, 0
	s_cmp_ge_i32 s43, s75
	s_mov_b32 s41, s43
	s_cbranch_scc0 .LBB0_1997
	s_and_b64 vcc, exec, s[34:35]
	s_cbranch_vccnz .LBB0_2002
	s_lshl_b32 s11, s2, 8
	s_cmp_gt_i32 s2, 63
	s_mov_b64 s[52:53], -1
	s_cbranch_scc1 .LBB0_2003

; #define PG8_STAGE(bufoff, gbase, voff) do { if constexpr (!pg8_noload<Epi>::value) { _Pragma("unroll") for (int _i = 0; _i < 2; ++_i) \
;         __builtin_amdgcn_global_load_lds((const unsigned*)((const char*)(gbase) + (size_t)_i * pstep + (voff)[0]), (PG8_LAS unsigned*)(lds + (bufoff) + ldsw + _i * 8192), 16, 0, 0); } } while (0)
; #define PG8_LDA(dst, b, h) do { _Pragma("unroll") for (int m = 0; m < 4; ++m) _Pragma("unroll") for (int k = 0; k < 2; ++k) dst[m][k] = *(const PG8_LAS bf16x8*)(lds + PG8_SA(b, h) + aoff + m * 2048 + k * 1024); } while (0)
; #define PG8_LDB(dst, b, h) do { _Pragma("unroll") for (int n = 0; n < 2; ++n) _Pragma("unroll") for (int k = 0; k < 2; ++k) dst[n][k] = *(const PG8_LAS bf16x8*)(lds + PG8_SB(b, h) + boff + n * 2048 + k * 1024); } while (0)
; #define PG8_MMA(ai, bj, At, Bt) do { __builtin_amdgcn_s_setprio(1); _Pragma("unroll") for (int m = 0; m < 4; ++m) _Pragma("unroll") for (int n = 0; n < 2; ++n) _Pragma("unroll") for (int k = 0; k < 2; ++k) \
;         acc[ai][bj][m][n] = __builtin_amdgcn_mfma_f32_16x16x32_bf16(Bt[n][k], At[m][k], acc[ai][bj][m][n], 0, 0, 0); __builtin_amdgcn_s_setprio(0); } while (0)
; #define PG8_WAIT_V(n) asm volatile("s_waitcnt vmcnt(" #n ")" ::: "memory")
; #define PG8_WAIT_L(n) asm volatile("s_waitcnt lgkmcnt(" #n ")" ::: "memory")
; template <class Epi, class Sched, bool ALIGN_EPI = false, bool SP2 = false, bool ABLK = false>
; __device__ __forceinline__ void gemm_phase(PG8_LAS unsigned char* lds, const Gemm g, const Sched& S, const Epi& E) {
;     ...
;         for (int t = 0; t < nt; t += 2) {
;             const bool last = (t == nt - 2);
;             const char* a1 = cA + (size_t)(t + 1) * kstep;
;             const char* a2 = last ? nA : cA + (size_t)(t + 2) * kstep; const char* b2 = last ? nB : cB + (size_t)(t + 2) * kstepB;
;             const char* a3 = a2 + kstep; const char* b3 = b2 + kstepB;
;             if (last && has_next) S.a_ready(nxt);
;             if constexpr (SP2) {
;             PG8_LDB(B0, 0, 0); PG8_LDB(B1, 0, 1); PG8_SCHED; PG8_LDA(At, 0, 0); PG8_STAGE(PG8_SA(1, 1), a1 + hstep, voffA);
;             PG8_WAIT_V(8); PG8_WAIT_L(0); PG8_BAR; PG8_MMA(0, 0, At, B0); PG8_MMA(0, 1, At, B1); PG8_BAR; PG8_SCHED;
;             PG8_LDA(At, 0, 1); PG8_STAGE(PG8_SB(0, 0), b2, voffB); PG8_STAGE(PG8_SB(0, 1), b2 + hstep, voffB); PG8_STAGE(PG8_SA(0, 0), a2, voffA);
.LBB0_2119:
	s_or_b32 s30, s59, 1
	s_lshl_b64 s[14:15], s[30:31], 11
	s_add_u32 s14, s82, s14
	v_add_u32_e32 v133, s71, v148
	s_addc_u32 s15, s83, s15
	s_add_i32 s30, s59, 2
	ds_read_b128 v[144:147], v133
	ds_read_b128 v[184:187], v133 offset:1024
	ds_read_b128 v[188:191], v133 offset:2048
	ds_read_b128 v[192:195], v133 offset:3072
	v_add_u32_e32 v133, s73, v148
	s_lshl_b64 s[34:35], s[30:31], 11
	ds_read_b128 v[196:199], v133
	ds_read_b128 v[200:203], v133 offset:1024
	ds_read_b128 v[204:207], v133 offset:2048
	ds_read_b128 v[208:211], v133 offset:3072
	s_add_u32 s96, s82, s34
	s_addc_u32 s97, s83, s35
	s_and_b64 s[94:95], s[92:93], exec
	s_cselect_b32 s95, s97, s77
	s_cselect_b32 s94, s96, s28
	s_add_u32 s96, s88, s34
	s_addc_u32 s97, s89, s35
	s_and_b64 s[34:35], s[92:93], exec
	s_cselect_b32 s35, s97, s29
	s_cselect_b32 s34, s96, s75
	v_lshl_add_u64 v[180:181], s[14:15], 0, v[130:131]
	v_lshl_add_u64 v[244:245], v[180:181], 0, s[24:25]
	s_add_i32 m0, s17, 0xc000
	ds_read_b128 v[212:215], v168
	ds_read_b128 v[216:219], v168 offset:1024
	ds_read_b128 v[220:223], v168 offset:2048
	ds_read_b128 v[224:227], v168 offset:3072
	ds_read_b128 v[228:231], v168 offset:4096
	ds_read_b128 v[232:235], v168 offset:5120
	ds_read_b128 v[236:239], v168 offset:6144
	ds_read_b128 v[240:243], v168 offset:7168
	global_load_lds_dwordx4 v[244:245], off
	v_lshl_add_u64 v[180:181], v[180:181], 0, s[26:27]
	s_add_i32 m0, s17, 0xe000
	s_nop 0
	global_load_lds_dwordx4 v[180:181], off
	s_waitcnt vmcnt(8)
	s_waitcnt lgkmcnt(0)
	s_barrier
	s_setprio 1
	s_waitcnt lgkmcnt(0)
	v_mfma_f32_16x16x32_bf16 v[126:129], v[144:147], v[212:215], v[126:129]
	v_mfma_f32_16x16x32_bf16 v[126:129], v[184:187], v[216:219], v[126:129]
	v_mfma_f32_16x16x32_bf16 v[110:113], v[184:187], v[224:227], v[110:113]
	v_mfma_f32_16x16x32_bf16 v[110:113], v[144:147], v[220:223], v[110:113]
	v_mfma_f32_16x16x32_bf16 v[94:97], v[144:147], v[228:231], v[94:97]
	v_mfma_f32_16x16x32_bf16 v[94:97], v[184:187], v[232:235], v[94:97]
	v_mfma_f32_16x16x32_bf16 v[78:81], v[184:187], v[240:243], v[78:81]
	v_mfma_f32_16x16x32_bf16 v[78:81], v[144:147], v[236:239], v[78:81]
	v_mfma_f32_16x16x32_bf16 v[74:77], v[188:191], v[236:239], v[74:77]
	v_mfma_f32_16x16x32_bf16 v[74:77], v[192:195], v[240:243], v[74:77]
	v_mfma_f32_16x16x32_bf16 v[90:93], v[192:195], v[232:235], v[90:93]
	v_mfma_f32_16x16x32_bf16 v[90:93], v[188:191], v[228:231], v[90:93]
	v_mfma_f32_16x16x32_bf16 v[106:109], v[188:191], v[220:223], v[106:109]
	v_mfma_f32_16x16x32_bf16 v[106:109], v[192:195], v[224:227], v[106:109]
	v_mfma_f32_16x16x32_bf16 v[122:125], v[192:195], v[216:219], v[122:125]
	v_mfma_f32_16x16x32_bf16 v[122:125], v[188:191], v[212:215], v[122:125]
	v_mfma_f32_16x16x32_bf16 v[118:121], v[196:199], v[212:215], v[118:121]
	v_mfma_f32_16x16x32_bf16 v[118:121], v[200:203], v[216:219], v[118:121]
	v_mfma_f32_16x16x32_bf16 v[102:105], v[200:203], v[224:227], v[102:105]
	v_mfma_f32_16x16x32_bf16 v[102:105], v[196:199], v[220:223], v[102:105]
	v_mfma_f32_16x16x32_bf16 v[86:89], v[196:199], v[228:231], v[86:89]
	v_mfma_f32_16x16x32_bf16 v[86:89], v[200:203], v[232:235], v[86:89]
	v_mfma_f32_16x16x32_bf16 v[70:73], v[200:203], v[240:243], v[70:73]
	v_mfma_f32_16x16x32_bf16 v[70:73], v[196:199], v[236:239], v[70:73]
	v_mfma_f32_16x16x32_bf16 v[66:69], v[204:207], v[236:239], v[66:69]
	v_mfma_f32_16x16x32_bf16 v[66:69], v[208:211], v[240:243], v[66:69]
	v_mfma_f32_16x16x32_bf16 v[82:85], v[208:211], v[232:235], v[82:85]
	v_mfma_f32_16x16x32_bf16 v[82:85], v[204:207], v[228:231], v[82:85]
	s_barrier
	s_setprio 2
	v_mfma_f32_16x16x32_bf16 v[98:101], v[204:207], v[220:223], v[98:101]
	v_mfma_f32_16x16x32_bf16 v[98:101], v[208:211], v[224:227], v[98:101]
	v_mfma_f32_16x16x32_bf16 v[114:117], v[208:211], v[216:219], v[114:117]
	v_mfma_f32_16x16x32_bf16 v[114:117], v[204:207], v[212:215], v[114:117]
	s_setprio 0
	s_add_i32 s14, s71, s3
	v_lshl_add_u64 v[180:181], s[34:35], 0, v[130:131]
	s_mov_b32 m0, s14
	ds_read_b128 v[212:215], v168 offset:16384
	ds_read_b128 v[216:219], v168 offset:17408
	ds_read_b128 v[220:223], v168 offset:18432
	ds_read_b128 v[224:227], v168 offset:19456
	ds_read_b128 v[228:231], v168 offset:20480
	ds_read_b128 v[232:235], v168 offset:21504
	ds_read_b128 v[236:239], v168 offset:22528
	ds_read_b128 v[240:243], v168 offset:23552
	global_load_lds_dwordx4 v[180:181], off
	v_lshl_add_u64 v[244:245], v[180:181], 0, s[22:23]
	s_add_i32 m0, s14, 0x2000
	s_add_i32 s14, s73, s3
	global_load_lds_dwordx4 v[244:245], off
	v_lshl_add_u64 v[244:245], v[180:181], 0, s[24:25]
	s_mov_b32 m0, s14
	s_nop 0
	global_load_lds_dwordx4 v[244:245], off
	v_lshl_add_u64 v[244:245], v[180:181], 0, s[26:27]
	s_add_i32 m0, s14, 0x2000
	s_nop 0
	global_load_lds_dwordx4 v[244:245], off
	v_lshl_add_u64 v[244:245], s[94:95], 0, v[130:131]
	s_mov_b32 m0, s17
	v_lshl_add_u64 v[246:247], v[244:245], 0, s[22:23]
	global_load_lds_dwordx4 v[244:245], off
	s_mov_b32 m0, s56
	s_nop 0
	global_load_lds_dwordx4 v[246:247], off
	s_waitcnt vmcnt(8)
	s_waitcnt lgkmcnt(0)
	s_barrier
; #define PG8_STAGE(bufoff, gbase, voff) do { if constexpr (!pg8_noload<Epi>::value) { _Pragma("unroll") for (int _i = 0; _i < 2; ++_i) \
;         __builtin_amdgcn_global_load_lds((const unsigned*)((const char*)(gbase) + (size_t)_i * pstep + (voff)[0]), (PG8_LAS unsigned*)(lds + (bufoff) + ldsw + _i * 8192), 16, 0, 0); } } while (0)
; #define PG8_LDA(dst, b, h) do { _Pragma("unroll") for (int m = 0; m < 4; ++m) _Pragma("unroll") for (int k = 0; k < 2; ++k) dst[m][k] = *(const PG8_LAS bf16x8*)(lds + PG8_SA(b, h) + aoff + m * 2048 + k * 1024); } while (0)
; #define PG8_LDB(dst, b, h) do { _Pragma("unroll") for (int n = 0; n < 2; ++n) _Pragma("unroll") for (int k = 0; k < 2; ++k) dst[n][k] = *(const PG8_LAS bf16x8*)(lds + PG8_SB(b, h) + boff + n * 2048 + k * 1024); } while (0)
; #define PG8_MMA(ai, bj, At, Bt) do { __builtin_amdgcn_s_setprio(1); _Pragma("unroll") for (int m = 0; m < 4; ++m) _Pragma("unroll") for (int n = 0; n < 2; ++n) _Pragma("unroll") for (int k = 0; k < 2; ++k) \
;         acc[ai][bj][m][n] = __builtin_amdgcn_mfma_f32_16x16x32_bf16(Bt[n][k], At[m][k], acc[ai][bj][m][n], 0, 0, 0); __builtin_amdgcn_s_setprio(0); } while (0)
; #define PG8_WAIT_V(n) asm volatile("s_waitcnt vmcnt(" #n ")" ::: "memory")
; #define PG8_WAIT_L(n) asm volatile("s_waitcnt lgkmcnt(" #n ")" ::: "memory")
; #define PG8_BAR __builtin_amdgcn_s_barrier()
; #define PG8_SCHED __builtin_amdgcn_sched_barrier(0)
; template <class Epi, class Sched, bool ALIGN_EPI = false, bool SP2 = false, bool ABLK = false>
; __device__ __forceinline__ void gemm_phase(PG8_LAS unsigned char* lds, const Gemm g, const Sched& S, const Epi& E) {
;     ...
;             PG8_WAIT_V(8); PG8_WAIT_L(0); PG8_BAR; PG8_MMA(1, 0, At, B0); PG8_MMA(1, 1, At, B1); PG8_BAR; PG8_SCHED;
;             PG8_LDB(B0, 1, 0); PG8_LDB(B1, 1, 1); PG8_SCHED; PG8_LDA(At, 1, 0); PG8_STAGE(PG8_SA(0, 1), a2 + hstep, voffA);
;             PG8_WAIT_V(8); PG8_WAIT_L(0); PG8_BAR; PG8_MMA(0, 0, At, B0); PG8_MMA(0, 1, At, B1); PG8_BAR; PG8_SCHED;
	s_setprio 1
	s_waitcnt lgkmcnt(0)
	v_mfma_f32_16x16x32_bf16 v[62:65], v[144:147], v[212:215], v[62:65]
	v_mfma_f32_16x16x32_bf16 v[62:65], v[184:187], v[216:219], v[62:65]
	v_mfma_f32_16x16x32_bf16 v[46:49], v[184:187], v[224:227], v[46:49]
	v_mfma_f32_16x16x32_bf16 v[46:49], v[144:147], v[220:223], v[46:49]
	v_mfma_f32_16x16x32_bf16 v[30:33], v[144:147], v[228:231], v[30:33]
	v_mfma_f32_16x16x32_bf16 v[30:33], v[184:187], v[232:235], v[30:33]
	v_mfma_f32_16x16x32_bf16 v[14:17], v[184:187], v[240:243], v[14:17]
	v_mfma_f32_16x16x32_bf16 v[14:17], v[144:147], v[236:239], v[14:17]
	v_mfma_f32_16x16x32_bf16 v[10:13], v[188:191], v[236:239], v[10:13]
	v_mfma_f32_16x16x32_bf16 v[10:13], v[192:195], v[240:243], v[10:13]
	v_mfma_f32_16x16x32_bf16 v[26:29], v[192:195], v[232:235], v[26:29]
	v_mfma_f32_16x16x32_bf16 v[26:29], v[188:191], v[228:231], v[26:29]
	v_mfma_f32_16x16x32_bf16 v[42:45], v[188:191], v[220:223], v[42:45]
	v_mfma_f32_16x16x32_bf16 v[42:45], v[192:195], v[224:227], v[42:45]
	v_mfma_f32_16x16x32_bf16 v[58:61], v[192:195], v[216:219], v[58:61]
	v_mfma_f32_16x16x32_bf16 v[58:61], v[188:191], v[212:215], v[58:61]
	v_mfma_f32_16x16x32_bf16 v[54:57], v[196:199], v[212:215], v[54:57]
	v_mfma_f32_16x16x32_bf16 v[54:57], v[200:203], v[216:219], v[54:57]
	v_mfma_f32_16x16x32_bf16 v[38:41], v[200:203], v[224:227], v[38:41]
	v_mfma_f32_16x16x32_bf16 v[38:41], v[196:199], v[220:223], v[38:41]
	v_mfma_f32_16x16x32_bf16 v[22:25], v[196:199], v[228:231], v[22:25]
	v_mfma_f32_16x16x32_bf16 v[22:25], v[200:203], v[232:235], v[22:25]
	v_mfma_f32_16x16x32_bf16 v[6:9], v[200:203], v[240:243], v[6:9]
	v_mfma_f32_16x16x32_bf16 v[6:9], v[196:199], v[236:239], v[6:9]
	v_mfma_f32_16x16x32_bf16 v[2:5], v[204:207], v[236:239], v[2:5]
	v_mfma_f32_16x16x32_bf16 v[2:5], v[208:211], v[240:243], v[2:5]
	v_mfma_f32_16x16x32_bf16 v[18:21], v[208:211], v[232:235], v[18:21]
	v_mfma_f32_16x16x32_bf16 v[18:21], v[204:207], v[228:231], v[18:21]
	s_barrier
	s_setprio 2
	v_mfma_f32_16x16x32_bf16 v[34:37], v[204:207], v[220:223], v[34:37]
	v_mfma_f32_16x16x32_bf16 v[34:37], v[208:211], v[224:227], v[34:37]
	v_mfma_f32_16x16x32_bf16 v[50:53], v[208:211], v[216:219], v[50:53]
	v_mfma_f32_16x16x32_bf16 v[50:53], v[204:207], v[212:215], v[50:53]
	s_setprio 0
	s_add_i32 s14, 0, 0x18000
	v_add_u32_e32 v133, s14, v148
	s_add_i32 s15, 0, 0x1c000
	ds_read_b128 v[144:147], v133
	ds_read_b128 v[184:187], v133 offset:1024
	ds_read_b128 v[188:191], v133 offset:2048
	ds_read_b128 v[192:195], v133 offset:3072
	v_add_u32_e32 v133, s15, v148
	ds_read_b128 v[196:199], v133
	ds_read_b128 v[200:203], v133 offset:1024
	ds_read_b128 v[204:207], v133 offset:2048
	ds_read_b128 v[208:211], v133 offset:3072
	s_mov_b32 m0, s57
	v_lshl_add_u64 v[246:247], v[244:245], 0, s[24:25]
	ds_read_b128 v[212:215], v168 offset:32768
	ds_read_b128 v[216:219], v168 offset:33792
	ds_read_b128 v[220:223], v168 offset:34816
	ds_read_b128 v[224:227], v168 offset:35840
	ds_read_b128 v[228:231], v168 offset:36864
	ds_read_b128 v[232:235], v168 offset:37888
	ds_read_b128 v[236:239], v168 offset:38912
	ds_read_b128 v[240:243], v168 offset:39936
	global_load_lds_dwordx4 v[246:247], off
	v_lshl_add_u64 v[246:247], v[244:245], 0, s[26:27]
	s_mov_b32 m0, s58
	s_nop 0
	global_load_lds_dwordx4 v[246:247], off
	s_waitcnt vmcnt(8)
	s_waitcnt lgkmcnt(0)
	s_barrier
	s_setprio 1
	s_waitcnt lgkmcnt(0)
	v_mfma_f32_16x16x32_bf16 v[126:129], v[144:147], v[212:215], v[126:129]
	v_mfma_f32_16x16x32_bf16 v[126:129], v[184:187], v[216:219], v[126:129]
	v_mfma_f32_16x16x32_bf16 v[110:113], v[184:187], v[224:227], v[110:113]
	v_mfma_f32_16x16x32_bf16 v[110:113], v[144:147], v[220:223], v[110:113]
	v_mfma_f32_16x16x32_bf16 v[94:97], v[144:147], v[228:231], v[94:97]
	v_mfma_f32_16x16x32_bf16 v[94:97], v[184:187], v[232:235], v[94:97]
	v_mfma_f32_16x16x32_bf16 v[78:81], v[184:187], v[240:243], v[78:81]
	v_mfma_f32_16x16x32_bf16 v[78:81], v[144:147], v[236:239], v[78:81]
	v_mfma_f32_16x16x32_bf16 v[74:77], v[188:191], v[236:239], v[74:77]
	v_mfma_f32_16x16x32_bf16 v[74:77], v[192:195], v[240:243], v[74:77]
	v_mfma_f32_16x16x32_bf16 v[90:93], v[192:195], v[232:235], v[90:93]
	v_mfma_f32_16x16x32_bf16 v[90:93], v[188:191], v[228:231], v[90:93]
	v_mfma_f32_16x16x32_bf16 v[106:109], v[188:191], v[220:223], v[106:109]
	v_mfma_f32_16x16x32_bf16 v[106:109], v[192:195], v[224:227], v[106:109]
	v_mfma_f32_16x16x32_bf16 v[122:125], v[192:195], v[216:219], v[122:125]
	v_mfma_f32_16x16x32_bf16 v[122:125], v[188:191], v[212:215], v[122:125]
	v_mfma_f32_16x16x32_bf16 v[118:121], v[196:199], v[212:215], v[118:121]
	v_mfma_f32_16x16x32_bf16 v[118:121], v[200:203], v[216:219], v[118:121]
	v_mfma_f32_16x16x32_bf16 v[102:105], v[200:203], v[224:227], v[102:105]
	v_mfma_f32_16x16x32_bf16 v[102:105], v[196:199], v[220:223], v[102:105]
	v_mfma_f32_16x16x32_bf16 v[86:89], v[196:199], v[228:231], v[86:89]
	v_mfma_f32_16x16x32_bf16 v[86:89], v[200:203], v[232:235], v[86:89]
	v_mfma_f32_16x16x32_bf16 v[70:73], v[200:203], v[240:243], v[70:73]
	v_mfma_f32_16x16x32_bf16 v[70:73], v[196:199], v[236:239], v[70:73]
	v_mfma_f32_16x16x32_bf16 v[66:69], v[204:207], v[236:239], v[66:69]
	v_mfma_f32_16x16x32_bf16 v[66:69], v[208:211], v[240:243], v[66:69]
	v_mfma_f32_16x16x32_bf16 v[82:85], v[208:211], v[232:235], v[82:85]
	v_mfma_f32_16x16x32_bf16 v[82:85], v[204:207], v[228:231], v[82:85]
	s_barrier
; #define PG8_STAGE(bufoff, gbase, voff) do { if constexpr (!pg8_noload<Epi>::value) { _Pragma("unroll") for (int _i = 0; _i < 2; ++_i) \
;         __builtin_amdgcn_global_load_lds((const unsigned*)((const char*)(gbase) + (size_t)_i * pstep + (voff)[0]), (PG8_LAS unsigned*)(lds + (bufoff) + ldsw + _i * 8192), 16, 0, 0); } } while (0)
; #define PG8_LDA(dst, b, h) do { _Pragma("unroll") for (int m = 0; m < 4; ++m) _Pragma("unroll") for (int k = 0; k < 2; ++k) dst[m][k] = *(const PG8_LAS bf16x8*)(lds + PG8_SA(b, h) + aoff + m * 2048 + k * 1024); } while (0)
; #define PG8_MMA(ai, bj, At, Bt) do { __builtin_amdgcn_s_setprio(1); _Pragma("unroll") for (int m = 0; m < 4; ++m) _Pragma("unroll") for (int n = 0; n < 2; ++n) _Pragma("unroll") for (int k = 0; k < 2; ++k) \
;         acc[ai][bj][m][n] = __builtin_amdgcn_mfma_f32_16x16x32_bf16(Bt[n][k], At[m][k], acc[ai][bj][m][n], 0, 0, 0); __builtin_amdgcn_s_setprio(0); } while (0)
; #define PG8_WAIT_V(n) asm volatile("s_waitcnt vmcnt(" #n ")" ::: "memory")
; #define PG8_WAIT_L(n) asm volatile("s_waitcnt lgkmcnt(" #n ")" ::: "memory")
; #define PG8_BAR __builtin_amdgcn_s_barrier()
; #define PG8_SCHED __builtin_amdgcn_sched_barrier(0)
; template <class Epi, class Sched, bool ALIGN_EPI = false, bool SP2 = false, bool ABLK = false>
; __device__ __forceinline__ void gemm_phase(PG8_LAS unsigned char* lds, const Gemm g, const Sched& S, const Epi& E) {
;     ...
;             PG8_WAIT_V(8); PG8_WAIT_L(0); PG8_BAR; PG8_MMA(0, 0, At, B0); PG8_MMA(0, 1, At, B1); PG8_BAR; PG8_SCHED;
;             PG8_LDA(At, 1, 1); PG8_STAGE(PG8_SB(1, 0), b3, voffB); PG8_STAGE(PG8_SB(1, 1), b3 + hstep, voffB); PG8_STAGE(PG8_SA(1, 0), a3, voffA);
;             PG8_WAIT_V(8); PG8_WAIT_L(0); PG8_BAR; PG8_MMA(1, 0, At, B0); PG8_MMA(1, 1, At, B1); PG8_BAR; PG8_SCHED;
	s_setprio 2
	v_mfma_f32_16x16x32_bf16 v[98:101], v[204:207], v[220:223], v[98:101]
	v_mfma_f32_16x16x32_bf16 v[98:101], v[208:211], v[224:227], v[98:101]
	v_mfma_f32_16x16x32_bf16 v[114:117], v[208:211], v[216:219], v[114:117]
	v_mfma_f32_16x16x32_bf16 v[114:117], v[204:207], v[212:215], v[114:117]
	s_setprio 0
	s_add_i32 s14, s14, s3
	v_lshl_add_u64 v[246:247], v[180:181], 0, s[38:39]
	s_mov_b32 m0, s14
	ds_read_b128 v[212:215], v168 offset:49152
	ds_read_b128 v[216:219], v168 offset:50176
	ds_read_b128 v[220:223], v168 offset:51200
	ds_read_b128 v[224:227], v168 offset:52224
	ds_read_b128 v[228:231], v168 offset:53248
	ds_read_b128 v[232:235], v168 offset:54272
	ds_read_b128 v[236:239], v168 offset:55296
	ds_read_b128 v[240:243], v168 offset:56320
	global_load_lds_dwordx4 v[246:247], off
	v_lshl_add_u64 v[246:247], v[180:181], 0, s[40:41]
	s_add_i32 m0, s14, 0x2000
	s_add_i32 s14, s15, s3
	global_load_lds_dwordx4 v[246:247], off
	v_lshl_add_u64 v[246:247], v[180:181], 0, s[42:43]
	s_mov_b32 m0, s14
	v_lshl_add_u64 v[180:181], v[180:181], 0, s[44:45]
	global_load_lds_dwordx4 v[246:247], off
	s_add_i32 m0, s14, 0x2000
	s_nop 0
	global_load_lds_dwordx4 v[180:181], off
	v_lshl_add_u64 v[180:181], v[244:245], 0, s[38:39]
	s_mov_b32 m0, s61
	s_nop 0
	global_load_lds_dwordx4 v[180:181], off
	v_lshl_add_u64 v[180:181], v[244:245], 0, s[40:41]
	s_mov_b32 m0, s63
	s_nop 0
	global_load_lds_dwordx4 v[180:181], off
	s_waitcnt vmcnt(8)
	s_waitcnt lgkmcnt(0)
	s_barrier
	s_setprio 1
	s_waitcnt lgkmcnt(0)
	v_mfma_f32_16x16x32_bf16 v[62:65], v[144:147], v[212:215], v[62:65]
	v_mfma_f32_16x16x32_bf16 v[62:65], v[184:187], v[216:219], v[62:65]
	v_mfma_f32_16x16x32_bf16 v[46:49], v[184:187], v[224:227], v[46:49]
	v_mfma_f32_16x16x32_bf16 v[46:49], v[144:147], v[220:223], v[46:49]
	v_mfma_f32_16x16x32_bf16 v[30:33], v[144:147], v[228:231], v[30:33]
	v_mfma_f32_16x16x32_bf16 v[30:33], v[184:187], v[232:235], v[30:33]
	v_mfma_f32_16x16x32_bf16 v[14:17], v[184:187], v[240:243], v[14:17]
	v_mfma_f32_16x16x32_bf16 v[14:17], v[144:147], v[236:239], v[14:17]
	v_mfma_f32_16x16x32_bf16 v[10:13], v[188:191], v[236:239], v[10:13]
	v_mfma_f32_16x16x32_bf16 v[10:13], v[192:195], v[240:243], v[10:13]
	v_mfma_f32_16x16x32_bf16 v[26:29], v[192:195], v[232:235], v[26:29]
	v_mfma_f32_16x16x32_bf16 v[26:29], v[188:191], v[228:231], v[26:29]
	v_mfma_f32_16x16x32_bf16 v[42:45], v[188:191], v[220:223], v[42:45]
	v_mfma_f32_16x16x32_bf16 v[42:45], v[192:195], v[224:227], v[42:45]
	v_mfma_f32_16x16x32_bf16 v[58:61], v[192:195], v[216:219], v[58:61]
	v_mfma_f32_16x16x32_bf16 v[58:61], v[188:191], v[212:215], v[58:61]
	v_mfma_f32_16x16x32_bf16 v[54:57], v[196:199], v[212:215], v[54:57]
	v_mfma_f32_16x16x32_bf16 v[54:57], v[200:203], v[216:219], v[54:57]
	v_mfma_f32_16x16x32_bf16 v[38:41], v[200:203], v[224:227], v[38:41]
	v_mfma_f32_16x16x32_bf16 v[38:41], v[196:199], v[220:223], v[38:41]
	v_mfma_f32_16x16x32_bf16 v[22:25], v[196:199], v[228:231], v[22:25]
	v_mfma_f32_16x16x32_bf16 v[22:25], v[200:203], v[232:235], v[22:25]
	v_mfma_f32_16x16x32_bf16 v[6:9], v[200:203], v[240:243], v[6:9]
	v_mfma_f32_16x16x32_bf16 v[6:9], v[196:199], v[236:239], v[6:9]
	v_mfma_f32_16x16x32_bf16 v[2:5], v[204:207], v[236:239], v[2:5]
	v_mfma_f32_16x16x32_bf16 v[2:5], v[208:211], v[240:243], v[2:5]
	v_mfma_f32_16x16x32_bf16 v[18:21], v[208:211], v[232:235], v[18:21]
	v_mfma_f32_16x16x32_bf16 v[18:21], v[204:207], v[228:231], v[18:21]
	s_barrier
	s_setprio 2
	v_mfma_f32_16x16x32_bf16 v[34:37], v[204:207], v[220:223], v[34:37]
	v_mfma_f32_16x16x32_bf16 v[34:37], v[208:211], v[224:227], v[34:37]
	v_mfma_f32_16x16x32_bf16 v[50:53], v[208:211], v[216:219], v[50:53]
	v_mfma_f32_16x16x32_bf16 v[50:53], v[204:207], v[212:215], v[50:53]
	s_setprio 0
	s_cmp_gt_u32 s59, 29
	s_mov_b32 s59, s30
	s_cbranch_scc1 .LBB0_2131

; #define PG8_STAGE(bufoff, gbase, voff) do { if constexpr (!pg8_noload<Epi>::value) { _Pragma("unroll") for (int _i = 0; _i < 2; ++_i) \
;         __builtin_amdgcn_global_load_lds((const unsigned*)((const char*)(gbase) + (size_t)_i * pstep + (voff)[0]), (PG8_LAS unsigned*)(lds + (bufoff) + ldsw + _i * 8192), 16, 0, 0); } } while (0)
; #define PG8_LDA(dst, b, h) do { _Pragma("unroll") for (int m = 0; m < 4; ++m) _Pragma("unroll") for (int k = 0; k < 2; ++k) dst[m][k] = *(const PG8_LAS bf16x8*)(lds + PG8_SA(b, h) + aoff + m * 2048 + k * 1024); } while (0)
; #define PG8_LDB(dst, b, h) do { _Pragma("unroll") for (int n = 0; n < 2; ++n) _Pragma("unroll") for (int k = 0; k < 2; ++k) dst[n][k] = *(const PG8_LAS bf16x8*)(lds + PG8_SB(b, h) + boff + n * 2048 + k * 1024); } while (0)
; #define PG8_MMA(ai, bj, At, Bt) do { __builtin_amdgcn_s_setprio(1); _Pragma("unroll") for (int m = 0; m < 4; ++m) _Pragma("unroll") for (int n = 0; n < 2; ++n) _Pragma("unroll") for (int k = 0; k < 2; ++k) \
;         acc[ai][bj][m][n] = __builtin_amdgcn_mfma_f32_16x16x32_bf16(Bt[n][k], At[m][k], acc[ai][bj][m][n], 0, 0, 0); __builtin_amdgcn_s_setprio(0); } while (0)
; #define PG8_WAIT_V(n) asm volatile("s_waitcnt vmcnt(" #n ")" ::: "memory")
; #define PG8_WAIT_L(n) asm volatile("s_waitcnt lgkmcnt(" #n ")" ::: "memory")
; template <class Epi, class Sched, bool ALIGN_EPI = false, bool SP2 = false, bool ABLK = false>
; __device__ __forceinline__ void gemm_phase(PG8_LAS unsigned char* lds, const Gemm g, const Sched& S, const Epi& E) {
;     ...
;         for (int t = 0; t < nt; t += 2) {
;             const bool last = (t == nt - 2);
;             const char* a1 = cA + (size_t)(t + 1) * kstep;
;             const char* a2 = last ? nA : cA + (size_t)(t + 2) * kstep; const char* b2 = last ? nB : cB + (size_t)(t + 2) * kstepB;
;             const char* a3 = a2 + kstep; const char* b3 = b2 + kstepB;
;             if (last && has_next) S.a_ready(nxt);
;             if constexpr (SP2) {
;             PG8_LDB(B0, 0, 0); PG8_LDB(B1, 0, 1); PG8_SCHED; PG8_LDA(At, 0, 0); PG8_STAGE(PG8_SA(1, 1), a1 + hstep, voffA);
;             PG8_WAIT_V(8); PG8_WAIT_L(0); PG8_BAR; PG8_MMA(0, 0, At, B0); PG8_MMA(0, 1, At, B1); PG8_BAR; PG8_SCHED;
;             PG8_LDA(At, 0, 1); PG8_STAGE(PG8_SB(0, 0), b2, voffB); PG8_STAGE(PG8_SB(0, 1), b2 + hstep, voffB); PG8_STAGE(PG8_SA(0, 0), a2, voffA);
.LBB0_2399:
	ds_read_b128 v[130:133], v175
	ds_read_b128 v[134:137], v175 offset:1024
	ds_read_b128 v[138:141], v175 offset:2048
	ds_read_b128 v[142:145], v175 offset:3072
	ds_read_b128 v[146:149], v176
	ds_read_b128 v[150:153], v176 offset:1024
	ds_read_b128 v[154:157], v176 offset:2048
	ds_read_b128 v[158:161], v176 offset:3072
	s_add_i32 s55, s53, 2
	s_add_u32 s64, s62, 0xfff00800
	s_addc_u32 s65, s63, -1
	s_cmp_eq_u32 s3, s53
	s_cselect_b32 s65, s57, s65
	s_cselect_b32 s64, s56, s64
	s_cselect_b32 s91, s59, s49
	s_cselect_b32 s90, s58, s11
	v_lshl_add_u64 v[170:171], s[62:63], 0, v[166:167]
	s_add_i32 m0, s61, 0xc000
	ds_read_b128 v[184:187], v177
	ds_read_b128 v[188:191], v177 offset:1024
	ds_read_b128 v[192:195], v177 offset:2048
	ds_read_b128 v[196:199], v177 offset:3072
	ds_read_b128 v[200:203], v177 offset:4096
	ds_read_b128 v[204:207], v177 offset:5120
	ds_read_b128 v[208:211], v177 offset:6144
	ds_read_b128 v[212:215], v177 offset:7168
	global_load_lds_dwordx4 v[170:171], off
	v_lshl_add_u64 v[170:171], v[170:171], 0, s[12:13]
	s_add_i32 m0, s61, 0xe000
	s_nop 0
	global_load_lds_dwordx4 v[170:171], off
	s_waitcnt vmcnt(8)
	s_waitcnt lgkmcnt(0)
	s_barrier
	s_setprio 1
	s_waitcnt lgkmcnt(0)
	v_mfma_f32_16x16x32_bf16 v[126:129], v[130:133], v[184:187], v[126:129]
	v_mfma_f32_16x16x32_bf16 v[126:129], v[134:137], v[188:191], v[126:129]
	v_mfma_f32_16x16x32_bf16 v[110:113], v[134:137], v[196:199], v[110:113]
	v_mfma_f32_16x16x32_bf16 v[110:113], v[130:133], v[192:195], v[110:113]
	v_mfma_f32_16x16x32_bf16 v[94:97], v[130:133], v[200:203], v[94:97]
	v_mfma_f32_16x16x32_bf16 v[94:97], v[134:137], v[204:207], v[94:97]
	v_mfma_f32_16x16x32_bf16 v[78:81], v[134:137], v[212:215], v[78:81]
	v_mfma_f32_16x16x32_bf16 v[78:81], v[130:133], v[208:211], v[78:81]
	v_mfma_f32_16x16x32_bf16 v[74:77], v[138:141], v[208:211], v[74:77]
	v_mfma_f32_16x16x32_bf16 v[74:77], v[142:145], v[212:215], v[74:77]
	v_mfma_f32_16x16x32_bf16 v[90:93], v[142:145], v[204:207], v[90:93]
	v_mfma_f32_16x16x32_bf16 v[90:93], v[138:141], v[200:203], v[90:93]
	v_mfma_f32_16x16x32_bf16 v[106:109], v[138:141], v[192:195], v[106:109]
	v_mfma_f32_16x16x32_bf16 v[106:109], v[142:145], v[196:199], v[106:109]
	v_mfma_f32_16x16x32_bf16 v[122:125], v[142:145], v[188:191], v[122:125]
	v_mfma_f32_16x16x32_bf16 v[122:125], v[138:141], v[184:187], v[122:125]
	v_mfma_f32_16x16x32_bf16 v[118:121], v[146:149], v[184:187], v[118:121]
	v_mfma_f32_16x16x32_bf16 v[118:121], v[150:153], v[188:191], v[118:121]
	v_mfma_f32_16x16x32_bf16 v[102:105], v[150:153], v[196:199], v[102:105]
	v_mfma_f32_16x16x32_bf16 v[102:105], v[146:149], v[192:195], v[102:105]
	v_mfma_f32_16x16x32_bf16 v[86:89], v[146:149], v[200:203], v[86:89]
	v_mfma_f32_16x16x32_bf16 v[86:89], v[150:153], v[204:207], v[86:89]
	v_mfma_f32_16x16x32_bf16 v[70:73], v[150:153], v[212:215], v[70:73]
	v_mfma_f32_16x16x32_bf16 v[70:73], v[146:149], v[208:211], v[70:73]
	v_mfma_f32_16x16x32_bf16 v[66:69], v[154:157], v[208:211], v[66:69]
	v_mfma_f32_16x16x32_bf16 v[66:69], v[158:161], v[212:215], v[66:69]
	v_mfma_f32_16x16x32_bf16 v[82:85], v[158:161], v[204:207], v[82:85]
	v_mfma_f32_16x16x32_bf16 v[82:85], v[154:157], v[200:203], v[82:85]
	s_barrier
	s_setprio 2
	v_mfma_f32_16x16x32_bf16 v[98:101], v[154:157], v[192:195], v[98:101]
	v_mfma_f32_16x16x32_bf16 v[98:101], v[158:161], v[196:199], v[98:101]
	v_mfma_f32_16x16x32_bf16 v[114:117], v[158:161], v[188:191], v[114:117]
	v_mfma_f32_16x16x32_bf16 v[114:117], v[154:157], v[184:187], v[114:117]
	s_setprio 0
	s_add_i32 s53, s80, s69
	v_lshl_add_u64 v[170:171], s[90:91], 0, v[162:163]
	s_mov_b32 m0, s53
	ds_read_b128 v[184:187], v177 offset:16384
	ds_read_b128 v[188:191], v177 offset:17408
	ds_read_b128 v[192:195], v177 offset:18432
	ds_read_b128 v[196:199], v177 offset:19456
	ds_read_b128 v[200:203], v177 offset:20480
	ds_read_b128 v[204:207], v177 offset:21504
	ds_read_b128 v[208:211], v177 offset:22528
	ds_read_b128 v[212:215], v177 offset:23552
	global_load_lds_dwordx4 v[170:171], off
	v_lshl_add_u64 v[216:217], v[170:171], 0, s[12:13]
	s_add_i32 m0, s53, 0x2000
	s_add_i32 s53, s81, s69
	global_load_lds_dwordx4 v[216:217], off
	v_lshl_add_u64 v[216:217], v[170:171], 0, s[14:15]
	s_mov_b32 m0, s53
	s_nop 0
	global_load_lds_dwordx4 v[216:217], off
	v_lshl_add_u64 v[216:217], v[170:171], 0, s[16:17]
	s_add_i32 m0, s53, 0x2000
	s_nop 0
	global_load_lds_dwordx4 v[216:217], off
	v_lshl_add_u64 v[216:217], s[64:65], 0, v[162:163]
	s_mov_b32 m0, s61
	v_lshl_add_u64 v[218:219], v[216:217], 0, s[12:13]
	global_load_lds_dwordx4 v[216:217], off
	s_mov_b32 m0, s70
	s_nop 0
	global_load_lds_dwordx4 v[218:219], off
	s_waitcnt vmcnt(8)
	s_waitcnt lgkmcnt(0)
	s_barrier
; #define PG8_STAGE(bufoff, gbase, voff) do { if constexpr (!pg8_noload<Epi>::value) { _Pragma("unroll") for (int _i = 0; _i < 2; ++_i) \
;         __builtin_amdgcn_global_load_lds((const unsigned*)((const char*)(gbase) + (size_t)_i * pstep + (voff)[0]), (PG8_LAS unsigned*)(lds + (bufoff) + ldsw + _i * 8192), 16, 0, 0); } } while (0)
; #define PG8_LDA(dst, b, h) do { _Pragma("unroll") for (int m = 0; m < 4; ++m) _Pragma("unroll") for (int k = 0; k < 2; ++k) dst[m][k] = *(const PG8_LAS bf16x8*)(lds + PG8_SA(b, h) + aoff + m * 2048 + k * 1024); } while (0)
; #define PG8_LDB(dst, b, h) do { _Pragma("unroll") for (int n = 0; n < 2; ++n) _Pragma("unroll") for (int k = 0; k < 2; ++k) dst[n][k] = *(const PG8_LAS bf16x8*)(lds + PG8_SB(b, h) + boff + n * 2048 + k * 1024); } while (0)
; #define PG8_MMA(ai, bj, At, Bt) do { __builtin_amdgcn_s_setprio(1); _Pragma("unroll") for (int m = 0; m < 4; ++m) _Pragma("unroll") for (int n = 0; n < 2; ++n) _Pragma("unroll") for (int k = 0; k < 2; ++k) \
;         acc[ai][bj][m][n] = __builtin_amdgcn_mfma_f32_16x16x32_bf16(Bt[n][k], At[m][k], acc[ai][bj][m][n], 0, 0, 0); __builtin_amdgcn_s_setprio(0); } while (0)
; #define PG8_WAIT_V(n) asm volatile("s_waitcnt vmcnt(" #n ")" ::: "memory")
; #define PG8_WAIT_L(n) asm volatile("s_waitcnt lgkmcnt(" #n ")" ::: "memory")
; #define PG8_BAR __builtin_amdgcn_s_barrier()
; #define PG8_SCHED __builtin_amdgcn_sched_barrier(0)
; template <class Epi, class Sched, bool ALIGN_EPI = false, bool SP2 = false, bool ABLK = false>
; __device__ __forceinline__ void gemm_phase(PG8_LAS unsigned char* lds, const Gemm g, const Sched& S, const Epi& E) {
;     ...
;             PG8_WAIT_V(8); PG8_WAIT_L(0); PG8_BAR; PG8_MMA(1, 0, At, B0); PG8_MMA(1, 1, At, B1); PG8_BAR; PG8_SCHED;
;             PG8_LDB(B0, 1, 0); PG8_LDB(B1, 1, 1); PG8_SCHED; PG8_LDA(At, 1, 0); PG8_STAGE(PG8_SA(0, 1), a2 + hstep, voffA);
;             PG8_WAIT_V(8); PG8_WAIT_L(0); PG8_BAR; PG8_MMA(0, 0, At, B0); PG8_MMA(0, 1, At, B1); PG8_BAR; PG8_SCHED;
	s_setprio 1
	s_waitcnt lgkmcnt(0)
	v_mfma_f32_16x16x32_bf16 v[62:65], v[130:133], v[184:187], v[62:65]
	v_mfma_f32_16x16x32_bf16 v[62:65], v[134:137], v[188:191], v[62:65]
	v_mfma_f32_16x16x32_bf16 v[46:49], v[134:137], v[196:199], v[46:49]
	v_mfma_f32_16x16x32_bf16 v[46:49], v[130:133], v[192:195], v[46:49]
	v_mfma_f32_16x16x32_bf16 v[30:33], v[130:133], v[200:203], v[30:33]
	v_mfma_f32_16x16x32_bf16 v[30:33], v[134:137], v[204:207], v[30:33]
	v_mfma_f32_16x16x32_bf16 v[14:17], v[134:137], v[212:215], v[14:17]
	v_mfma_f32_16x16x32_bf16 v[14:17], v[130:133], v[208:211], v[14:17]
	v_mfma_f32_16x16x32_bf16 v[10:13], v[138:141], v[208:211], v[10:13]
	v_mfma_f32_16x16x32_bf16 v[10:13], v[142:145], v[212:215], v[10:13]
	v_mfma_f32_16x16x32_bf16 v[26:29], v[142:145], v[204:207], v[26:29]
	v_mfma_f32_16x16x32_bf16 v[26:29], v[138:141], v[200:203], v[26:29]
	v_mfma_f32_16x16x32_bf16 v[42:45], v[138:141], v[192:195], v[42:45]
	v_mfma_f32_16x16x32_bf16 v[42:45], v[142:145], v[196:199], v[42:45]
	v_mfma_f32_16x16x32_bf16 v[58:61], v[142:145], v[188:191], v[58:61]
	v_mfma_f32_16x16x32_bf16 v[58:61], v[138:141], v[184:187], v[58:61]
	v_mfma_f32_16x16x32_bf16 v[54:57], v[146:149], v[184:187], v[54:57]
	v_mfma_f32_16x16x32_bf16 v[54:57], v[150:153], v[188:191], v[54:57]
	v_mfma_f32_16x16x32_bf16 v[38:41], v[150:153], v[196:199], v[38:41]
	v_mfma_f32_16x16x32_bf16 v[38:41], v[146:149], v[192:195], v[38:41]
	v_mfma_f32_16x16x32_bf16 v[22:25], v[146:149], v[200:203], v[22:25]
	v_mfma_f32_16x16x32_bf16 v[22:25], v[150:153], v[204:207], v[22:25]
	v_mfma_f32_16x16x32_bf16 v[6:9], v[150:153], v[212:215], v[6:9]
	v_mfma_f32_16x16x32_bf16 v[6:9], v[146:149], v[208:211], v[6:9]
	v_mfma_f32_16x16x32_bf16 v[2:5], v[154:157], v[208:211], v[2:5]
	v_mfma_f32_16x16x32_bf16 v[2:5], v[158:161], v[212:215], v[2:5]
	v_mfma_f32_16x16x32_bf16 v[18:21], v[158:161], v[204:207], v[18:21]
	v_mfma_f32_16x16x32_bf16 v[18:21], v[154:157], v[200:203], v[18:21]
	s_barrier
	s_setprio 2
	v_mfma_f32_16x16x32_bf16 v[34:37], v[154:157], v[192:195], v[34:37]
	v_mfma_f32_16x16x32_bf16 v[34:37], v[158:161], v[196:199], v[34:37]
	v_mfma_f32_16x16x32_bf16 v[50:53], v[158:161], v[188:191], v[50:53]
	v_mfma_f32_16x16x32_bf16 v[50:53], v[154:157], v[184:187], v[50:53]
	s_setprio 0
	s_add_i32 s53, 0, 0x18000
	s_add_i32 s64, 0, 0x1c000
	v_add_u32_e32 v142, s53, v1
	v_add_u32_e32 v158, s64, v1
	ds_read_b128 v[130:133], v142
	ds_read_b128 v[134:137], v142 offset:1024
	ds_read_b128 v[138:141], v142 offset:2048
	ds_read_b128 v[142:145], v142 offset:3072
	ds_read_b128 v[146:149], v158
	ds_read_b128 v[150:153], v158 offset:1024
	ds_read_b128 v[154:157], v158 offset:2048
	ds_read_b128 v[158:161], v158 offset:3072
	s_mov_b32 m0, s71
	v_lshl_add_u64 v[218:219], v[216:217], 0, s[14:15]
	ds_read_b128 v[184:187], v177 offset:32768
	ds_read_b128 v[188:191], v177 offset:33792
	ds_read_b128 v[192:195], v177 offset:34816
	ds_read_b128 v[196:199], v177 offset:35840
	ds_read_b128 v[200:203], v177 offset:36864
	ds_read_b128 v[204:207], v177 offset:37888
	ds_read_b128 v[208:211], v177 offset:38912
	ds_read_b128 v[212:215], v177 offset:39936
	global_load_lds_dwordx4 v[218:219], off
	v_lshl_add_u64 v[218:219], v[216:217], 0, s[16:17]
	s_mov_b32 m0, s72
	s_nop 0
	global_load_lds_dwordx4 v[218:219], off
	s_waitcnt vmcnt(8)
	s_waitcnt lgkmcnt(0)
	s_barrier
	s_setprio 1
	s_waitcnt lgkmcnt(0)
	v_mfma_f32_16x16x32_bf16 v[126:129], v[130:133], v[184:187], v[126:129]
	v_mfma_f32_16x16x32_bf16 v[126:129], v[134:137], v[188:191], v[126:129]
	v_mfma_f32_16x16x32_bf16 v[110:113], v[134:137], v[196:199], v[110:113]
	v_mfma_f32_16x16x32_bf16 v[110:113], v[130:133], v[192:195], v[110:113]
	v_mfma_f32_16x16x32_bf16 v[94:97], v[130:133], v[200:203], v[94:97]
	v_mfma_f32_16x16x32_bf16 v[94:97], v[134:137], v[204:207], v[94:97]
	v_mfma_f32_16x16x32_bf16 v[78:81], v[134:137], v[212:215], v[78:81]
	v_mfma_f32_16x16x32_bf16 v[78:81], v[130:133], v[208:211], v[78:81]
	v_mfma_f32_16x16x32_bf16 v[74:77], v[138:141], v[208:211], v[74:77]
	v_mfma_f32_16x16x32_bf16 v[74:77], v[142:145], v[212:215], v[74:77]
	v_mfma_f32_16x16x32_bf16 v[90:93], v[142:145], v[204:207], v[90:93]
	v_mfma_f32_16x16x32_bf16 v[90:93], v[138:141], v[200:203], v[90:93]
	v_mfma_f32_16x16x32_bf16 v[106:109], v[138:141], v[192:195], v[106:109]
	v_mfma_f32_16x16x32_bf16 v[106:109], v[142:145], v[196:199], v[106:109]
	v_mfma_f32_16x16x32_bf16 v[122:125], v[142:145], v[188:191], v[122:125]
	v_mfma_f32_16x16x32_bf16 v[122:125], v[138:141], v[184:187], v[122:125]
	v_mfma_f32_16x16x32_bf16 v[118:121], v[146:149], v[184:187], v[118:121]
	v_mfma_f32_16x16x32_bf16 v[118:121], v[150:153], v[188:191], v[118:121]
	v_mfma_f32_16x16x32_bf16 v[102:105], v[150:153], v[196:199], v[102:105]
	v_mfma_f32_16x16x32_bf16 v[102:105], v[146:149], v[192:195], v[102:105]
	v_mfma_f32_16x16x32_bf16 v[86:89], v[146:149], v[200:203], v[86:89]
	v_mfma_f32_16x16x32_bf16 v[86:89], v[150:153], v[204:207], v[86:89]
	v_mfma_f32_16x16x32_bf16 v[70:73], v[150:153], v[212:215], v[70:73]
	v_mfma_f32_16x16x32_bf16 v[70:73], v[146:149], v[208:211], v[70:73]
	v_mfma_f32_16x16x32_bf16 v[66:69], v[154:157], v[208:211], v[66:69]
	v_mfma_f32_16x16x32_bf16 v[66:69], v[158:161], v[212:215], v[66:69]
	v_mfma_f32_16x16x32_bf16 v[82:85], v[158:161], v[204:207], v[82:85]
	v_mfma_f32_16x16x32_bf16 v[82:85], v[154:157], v[200:203], v[82:85]
	s_barrier
; #define PG8_STAGE(bufoff, gbase, voff) do { if constexpr (!pg8_noload<Epi>::value) { _Pragma("unroll") for (int _i = 0; _i < 2; ++_i) \
;         __builtin_amdgcn_global_load_lds((const unsigned*)((const char*)(gbase) + (size_t)_i * pstep + (voff)[0]), (PG8_LAS unsigned*)(lds + (bufoff) + ldsw + _i * 8192), 16, 0, 0); } } while (0)
; #define PG8_LDA(dst, b, h) do { _Pragma("unroll") for (int m = 0; m < 4; ++m) _Pragma("unroll") for (int k = 0; k < 2; ++k) dst[m][k] = *(const PG8_LAS bf16x8*)(lds + PG8_SA(b, h) + aoff + m * 2048 + k * 1024); } while (0)
; #define PG8_MMA(ai, bj, At, Bt) do { __builtin_amdgcn_s_setprio(1); _Pragma("unroll") for (int m = 0; m < 4; ++m) _Pragma("unroll") for (int n = 0; n < 2; ++n) _Pragma("unroll") for (int k = 0; k < 2; ++k) \
;         acc[ai][bj][m][n] = __builtin_amdgcn_mfma_f32_16x16x32_bf16(Bt[n][k], At[m][k], acc[ai][bj][m][n], 0, 0, 0); __builtin_amdgcn_s_setprio(0); } while (0)
; #define PG8_WAIT_V(n) asm volatile("s_waitcnt vmcnt(" #n ")" ::: "memory")
; #define PG8_WAIT_L(n) asm volatile("s_waitcnt lgkmcnt(" #n ")" ::: "memory")
; #define PG8_BAR __builtin_amdgcn_s_barrier()
; #define PG8_SCHED __builtin_amdgcn_sched_barrier(0)
; template <class Epi, class Sched, bool ALIGN_EPI = false, bool SP2 = false, bool ABLK = false>
; __device__ __forceinline__ void gemm_phase(PG8_LAS unsigned char* lds, const Gemm g, const Sched& S, const Epi& E) {
;     ...
;             PG8_WAIT_V(8); PG8_WAIT_L(0); PG8_BAR; PG8_MMA(0, 0, At, B0); PG8_MMA(0, 1, At, B1); PG8_BAR; PG8_SCHED;
;             PG8_LDA(At, 1, 1); PG8_STAGE(PG8_SB(1, 0), b3, voffB); PG8_STAGE(PG8_SB(1, 1), b3 + hstep, voffB); PG8_STAGE(PG8_SA(1, 0), a3, voffA);
;             PG8_WAIT_V(8); PG8_WAIT_L(0); PG8_BAR; PG8_MMA(1, 0, At, B0); PG8_MMA(1, 1, At, B1); PG8_BAR; PG8_SCHED;
	s_setprio 2
	v_mfma_f32_16x16x32_bf16 v[98:101], v[154:157], v[192:195], v[98:101]
	v_mfma_f32_16x16x32_bf16 v[98:101], v[158:161], v[196:199], v[98:101]
	v_mfma_f32_16x16x32_bf16 v[114:117], v[158:161], v[188:191], v[114:117]
	v_mfma_f32_16x16x32_bf16 v[114:117], v[154:157], v[184:187], v[114:117]
	s_setprio 0
	s_add_i32 s53, s53, s69
	v_lshl_add_u64 v[218:219], v[170:171], 0, s[24:25]
	s_mov_b32 m0, s53
	ds_read_b128 v[184:187], v177 offset:49152
	ds_read_b128 v[188:191], v177 offset:50176
	ds_read_b128 v[192:195], v177 offset:51200
	ds_read_b128 v[196:199], v177 offset:52224
	ds_read_b128 v[200:203], v177 offset:53248
	ds_read_b128 v[204:207], v177 offset:54272
	ds_read_b128 v[208:211], v177 offset:55296
	ds_read_b128 v[212:215], v177 offset:56320
	global_load_lds_dwordx4 v[218:219], off
	v_lshl_add_u64 v[218:219], v[170:171], 0, s[26:27]
	s_add_i32 m0, s53, 0x2000
	s_add_i32 s53, s64, s69
	global_load_lds_dwordx4 v[218:219], off
	v_lshl_add_u64 v[218:219], v[170:171], 0, s[28:29]
	s_mov_b32 m0, s53
	v_lshl_add_u64 v[170:171], v[170:171], 0, s[30:31]
	global_load_lds_dwordx4 v[218:219], off
	s_add_i32 m0, s53, 0x2000
	s_nop 0
	global_load_lds_dwordx4 v[170:171], off
	v_lshl_add_u64 v[170:171], v[216:217], 0, s[24:25]
	s_mov_b32 m0, s75
	s_nop 0
	global_load_lds_dwordx4 v[170:171], off
	v_lshl_add_u64 v[170:171], v[216:217], 0, s[26:27]
	s_mov_b32 m0, s76
	s_nop 0
	global_load_lds_dwordx4 v[170:171], off
	s_waitcnt vmcnt(8)
	s_waitcnt lgkmcnt(0)
	s_barrier
	s_setprio 1
	s_waitcnt lgkmcnt(0)
	v_mfma_f32_16x16x32_bf16 v[62:65], v[130:133], v[184:187], v[62:65]
	v_mfma_f32_16x16x32_bf16 v[62:65], v[134:137], v[188:191], v[62:65]
	v_mfma_f32_16x16x32_bf16 v[46:49], v[134:137], v[196:199], v[46:49]
	v_mfma_f32_16x16x32_bf16 v[46:49], v[130:133], v[192:195], v[46:49]
	v_mfma_f32_16x16x32_bf16 v[30:33], v[130:133], v[200:203], v[30:33]
	v_mfma_f32_16x16x32_bf16 v[30:33], v[134:137], v[204:207], v[30:33]
	v_mfma_f32_16x16x32_bf16 v[14:17], v[134:137], v[212:215], v[14:17]
	v_mfma_f32_16x16x32_bf16 v[14:17], v[130:133], v[208:211], v[14:17]
	v_mfma_f32_16x16x32_bf16 v[10:13], v[138:141], v[208:211], v[10:13]
	v_mfma_f32_16x16x32_bf16 v[10:13], v[142:145], v[212:215], v[10:13]
	v_mfma_f32_16x16x32_bf16 v[26:29], v[142:145], v[204:207], v[26:29]
	v_mfma_f32_16x16x32_bf16 v[26:29], v[138:141], v[200:203], v[26:29]
	v_mfma_f32_16x16x32_bf16 v[42:45], v[138:141], v[192:195], v[42:45]
	v_mfma_f32_16x16x32_bf16 v[42:45], v[142:145], v[196:199], v[42:45]
	v_mfma_f32_16x16x32_bf16 v[58:61], v[142:145], v[188:191], v[58:61]
	v_mfma_f32_16x16x32_bf16 v[58:61], v[138:141], v[184:187], v[58:61]
	v_mfma_f32_16x16x32_bf16 v[54:57], v[146:149], v[184:187], v[54:57]
	v_mfma_f32_16x16x32_bf16 v[54:57], v[150:153], v[188:191], v[54:57]
	v_mfma_f32_16x16x32_bf16 v[38:41], v[150:153], v[196:199], v[38:41]
	v_mfma_f32_16x16x32_bf16 v[38:41], v[146:149], v[192:195], v[38:41]
	v_mfma_f32_16x16x32_bf16 v[22:25], v[146:149], v[200:203], v[22:25]
	v_mfma_f32_16x16x32_bf16 v[22:25], v[150:153], v[204:207], v[22:25]
	v_mfma_f32_16x16x32_bf16 v[6:9], v[150:153], v[212:215], v[6:9]
	v_mfma_f32_16x16x32_bf16 v[6:9], v[146:149], v[208:211], v[6:9]
	v_mfma_f32_16x16x32_bf16 v[2:5], v[154:157], v[208:211], v[2:5]
	v_mfma_f32_16x16x32_bf16 v[2:5], v[158:161], v[212:215], v[2:5]
	v_mfma_f32_16x16x32_bf16 v[18:21], v[158:161], v[204:207], v[18:21]
	v_mfma_f32_16x16x32_bf16 v[18:21], v[154:157], v[200:203], v[18:21]
	s_barrier
	s_setprio 2
	v_mfma_f32_16x16x32_bf16 v[34:37], v[154:157], v[192:195], v[34:37]
	v_mfma_f32_16x16x32_bf16 v[34:37], v[158:161], v[196:199], v[34:37]
	v_mfma_f32_16x16x32_bf16 v[50:53], v[158:161], v[188:191], v[50:53]
	v_mfma_f32_16x16x32_bf16 v[50:53], v[154:157], v[184:187], v[50:53]
	s_setprio 0
	s_add_u32 s62, s62, 0x1000
	s_addc_u32 s63, s63, 0
	s_add_u32 s11, s11, 0x1000
	s_addc_u32 s49, s49, 0
	s_cmp_ge_i32 s55, s89
	s_mov_b32 s53, s55
	s_cbranch_scc0 .LBB0_2399
	s_and_b64 vcc, exec, s[34:35]
	s_cbranch_vccnz .LBB0_2404
	s_lshl_b32 s11, s2, 8
	s_cmp_gt_i32 s2, 63
	s_mov_b64 s[62:63], -1
	s_cbranch_scc1 .LBB0_2405
